# low-rank K-slice + all 16-byte global stores write-through (sc1) so the grid barrier release fence finds a clean L2
# speedup vs baseline: 1.0015x; 1.0015x over previous
.LBB0_106:
	s_add_i32 s0, s6, 0xfffffa80
	s_ashr_i32 s1, s0, 31
	v_add_u32_e32 v4, 0x400, v10
	s_lshr_b32 s1, s1, 28
	s_waitcnt vmcnt(6)
	ds_write2_b32 v10, v12, v13 offset1:65
	s_waitcnt vmcnt(4)
	ds_write2_b32 v10, v14, v15 offset0:130 offset1:195
	s_waitcnt vmcnt(2)
	ds_write2_b32 v4, v16, v17 offset0:4 offset1:69
	s_waitcnt vmcnt(0)
	ds_write2_b32 v4, v18, v19 offset0:134 offset1:199
	s_waitcnt lgkmcnt(0)
	s_barrier
	ds_read2_b32 v[6:7], v11 offset1:65
	ds_read2_b32 v[14:15], v11 offset0:130 offset1:195
	s_add_i32 s1, s0, s1
	s_and_b32 s6, s1, 0x3fffff0
	v_add_u32_e32 v4, 0x400, v11
	s_sub_i32 s6, s0, s6
	s_lshl_b32 s0, s1, 2
	ds_read2_b32 v[16:17], v4 offset0:4 offset1:69
	ds_read2_b32 v[18:19], v4 offset0:134 offset1:199
	s_andn2_b32 s0, s0, 63
	s_waitcnt lgkmcnt(3)
	v_cvt_pk_bf16_f32 v12, v6, v7
	v_lshl_add_u32 v4, s6, 6, v9
	v_mov_b64_e32 v[6:7], s[2:3]
	v_mad_i64_i32 v[6:7], s[10:11], v4, s9, v[6:7]
	s_ashr_i32 s1, s0, 31
	v_lshl_add_u64 v[6:7], s[0:1], 1, v[6:7]
	v_lshl_add_u64 v[6:7], v[6:7], 0, v[2:3]
	s_andn2_b64 vcc, exec, s[4:5]
	s_waitcnt lgkmcnt(2)
	v_cvt_pk_bf16_f32 v13, v14, v15
	s_waitcnt lgkmcnt(1)
	v_cvt_pk_bf16_f32 v14, v16, v17
	s_waitcnt lgkmcnt(0)
	v_cvt_pk_bf16_f32 v15, v18, v19
	global_store_dwordx4 v[6:7], v[12:15], off sc1
	s_barrier
	s_cbranch_vccz .LBB0_150
	s_mov_b32 s6, s8
	v_mov_b32_e32 v12, v5
	v_mov_b32_e32 v13, v21
	v_mov_b32_e32 v14, v23
	v_mov_b32_e32 v15, v22
	v_mov_b32_e32 v16, v25
	v_mov_b32_e32 v17, v24
	v_mov_b32_e32 v18, v27
	v_mov_b32_e32 v19, v26
	s_branch .LBB0_88

.LBB0_147:
	s_waitcnt vmcnt(0)
	ds_write2_b32 v27, v2, v3 offset1:65
	ds_write2_b32 v27, v4, v5 offset0:130 offset1:195
	v_add_u32_e32 v2, 0x400, v27
	s_mul_hi_i32 s0, s12, 0x2e8ba2e9
	ds_write2_b32 v2, v6, v7 offset0:4 offset1:69
	ds_write2_b32 v2, v8, v9 offset0:134 offset1:199
	s_waitcnt lgkmcnt(0)
	s_barrier
	ds_read2_b32 v[2:3], v29 offset1:65
	ds_read2_b32 v[4:5], v29 offset0:130 offset1:195
	v_add_u32_e32 v8, 0x400, v29
	s_lshr_b32 s1, s0, 31
	s_ashr_i32 s0, s0, 4
	ds_read2_b32 v[6:7], v8 offset0:4 offset1:69
	ds_read2_b32 v[8:9], v8 offset0:134 offset1:199
	s_add_i32 s1, s0, s1
	s_lshl_b32 s0, s1, 6
	s_mulk_i32 s1, 0xea00
	s_add_i32 s1, s1, s10
	s_waitcnt lgkmcnt(3)
	v_cvt_pk_bf16_f32 v2, v2, v3
	s_waitcnt lgkmcnt(2)
	v_cvt_pk_bf16_f32 v3, v4, v5
	s_waitcnt lgkmcnt(1)
	v_cvt_pk_bf16_f32 v4, v6, v7
	v_add_u32_e32 v6, s1, v26
	v_ashrrev_i32_e32 v7, 31, v6
	v_readlane_b32 s12, v251, 53
	v_lshlrev_b64 v[6:7], 11, v[6:7]
	v_readlane_b32 s13, v251, 54
	s_ashr_i32 s1, s0, 31
	v_mov_b32_e32 v23, v10
	v_lshl_add_u64 v[6:7], s[12:13], 0, v[6:7]
	v_lshl_add_u64 v[6:7], s[0:1], 1, v[6:7]
	v_lshl_add_u64 v[6:7], v[6:7], 0, v[22:23]
	s_andn2_b64 vcc, exec, s[2:3]
	s_add_i32 s5, s5, s7
	s_waitcnt lgkmcnt(0)
	v_cvt_pk_bf16_f32 v5, v8, v9
	global_store_dwordx4 v[6:7], v[2:5], off sc1
	s_barrier
	s_cbranch_vccz .LBB0_86
	v_mov_b64_e32 v[2:3], v[12:13]
	s_mov_b32 s10, s11
	s_mov_b32 s12, s6
	v_mov_b64_e32 v[4:5], v[14:15]
	v_mov_b64_e32 v[6:7], v[16:17]
	v_mov_b64_e32 v[8:9], v[18:19]
	s_branch .LBB0_127

.LBB0_180:
	s_add_i32 s0, s9, 0xfffff240
	s_ashr_i32 s1, s0, 31
	v_add_u32_e32 v4, 0x400, v10
	s_lshr_b32 s1, s1, 28
	s_waitcnt vmcnt(6)
	ds_write2_b32 v10, v12, v13 offset1:65
	s_waitcnt vmcnt(4)
	ds_write2_b32 v10, v14, v15 offset0:130 offset1:195
	s_waitcnt vmcnt(2)
	ds_write2_b32 v4, v16, v17 offset0:4 offset1:69
	s_waitcnt vmcnt(0)
	ds_write2_b32 v4, v18, v19 offset0:134 offset1:199
	s_waitcnt lgkmcnt(0)
	s_barrier
	ds_read2_b32 v[4:5], v11 offset1:65
	ds_read2_b32 v[14:15], v11 offset0:130 offset1:195
	s_add_i32 s1, s0, s1
	s_and_b32 s9, s1, 0x3fffff0
	v_add_u32_e32 v6, 0x400, v11
	s_sub_i32 s9, s0, s9
	s_lshl_b32 s0, s1, 2
	ds_read2_b32 v[16:17], v6 offset0:4 offset1:69
	ds_read2_b32 v[18:19], v6 offset0:134 offset1:199
	s_andn2_b32 s0, s0, 63
	s_waitcnt lgkmcnt(3)
	v_cvt_pk_bf16_f32 v12, v4, v5
	v_lshl_add_u32 v6, s9, 6, v9
	v_mov_b64_e32 v[4:5], s[4:5]
	v_mad_i64_i32 v[4:5], s[12:13], v6, s11, v[4:5]
	s_ashr_i32 s1, s0, 31
	v_lshl_add_u64 v[4:5], s[0:1], 1, v[4:5]
	v_lshl_add_u64 v[4:5], v[4:5], 0, v[2:3]
	s_andn2_b64 vcc, exec, s[6:7]
	s_waitcnt lgkmcnt(2)
	v_cvt_pk_bf16_f32 v13, v14, v15
	s_waitcnt lgkmcnt(1)
	v_cvt_pk_bf16_f32 v14, v16, v17
	s_waitcnt lgkmcnt(0)
	v_cvt_pk_bf16_f32 v15, v18, v19
	global_store_dwordx4 v[4:5], v[12:15], off sc1
	s_barrier
	s_cbranch_vccz .LBB0_212
	s_mov_b32 s9, s8
	v_mov_b32_e32 v12, v7
	v_mov_b32_e32 v13, v21
	v_mov_b32_e32 v14, v23
	v_mov_b32_e32 v15, v22
	v_mov_b32_e32 v16, v25
	v_mov_b32_e32 v17, v24
	v_mov_b32_e32 v18, v27
	v_mov_b32_e32 v19, v26
	s_branch .LBB0_162

.LBB0_209:
	s_add_i32 s0, s8, 0xfffff7c0
	s_waitcnt vmcnt(0)
	ds_write2_b32 v27, v2, v3 offset1:65
	ds_write2_b32 v27, v4, v5 offset0:130 offset1:195
	v_add_u32_e32 v2, 0x400, v27
	s_mul_hi_i32 s1, s0, 0x2e8ba2e9
	ds_write2_b32 v2, v6, v7 offset0:4 offset1:69
	ds_write2_b32 v2, v8, v9 offset0:134 offset1:199
	s_waitcnt lgkmcnt(0)
	s_barrier
	ds_read2_b32 v[2:3], v29 offset1:65
	ds_read2_b32 v[4:5], v29 offset0:130 offset1:195
	v_add_u32_e32 v8, 0x400, v29
	s_lshr_b32 s8, s1, 31
	s_ashr_i32 s1, s1, 4
	ds_read2_b32 v[6:7], v8 offset0:4 offset1:69
	ds_read2_b32 v[8:9], v8 offset0:134 offset1:199
	s_add_i32 s1, s1, s8
	s_mul_i32 s8, s1, 0x58
	s_sub_i32 s8, s0, s8
	s_waitcnt lgkmcnt(3)
	v_cvt_pk_bf16_f32 v2, v2, v3
	s_waitcnt lgkmcnt(2)
	v_cvt_pk_bf16_f32 v3, v4, v5
	s_waitcnt lgkmcnt(1)
	v_cvt_pk_bf16_f32 v4, v6, v7
	v_lshl_add_u32 v6, s8, 6, v26
	v_ashrrev_i32_e32 v7, 31, v6
	s_lshl_b32 s0, s1, 6
	v_lshlrev_b64 v[6:7], 11, v[6:7]
	v_lshl_add_u64 v[6:7], s[4:5], 0, v[6:7]
	s_ashr_i32 s1, s0, 31
	v_lshl_add_u64 v[6:7], s[0:1], 1, v[6:7]
	v_mov_b32_e32 v23, v10
	v_lshl_add_u64 v[6:7], v[6:7], 0, v[22:23]
	s_andn2_b64 vcc, exec, s[6:7]
	s_waitcnt lgkmcnt(0)
	v_cvt_pk_bf16_f32 v5, v8, v9
	global_store_dwordx4 v[6:7], v[2:5], off sc1
	s_barrier
	s_cbranch_vccz .LBB0_160
	v_mov_b64_e32 v[2:3], v[12:13]
	s_mov_b32 s8, s9
	v_mov_b64_e32 v[4:5], v[14:15]
	v_mov_b64_e32 v[6:7], v[16:17]
	v_mov_b64_e32 v[8:9], v[18:19]
	s_branch .LBB0_191

.LBB0_225:
	s_add_i32 s0, s6, 0xffffec00
	s_ashr_i32 s1, s0, 31
	v_add_u32_e32 v4, 0x400, v10
	s_lshr_b32 s1, s1, 28
	s_waitcnt vmcnt(6)
	ds_write2_b32 v10, v12, v13 offset1:65
	s_waitcnt vmcnt(4)
	ds_write2_b32 v10, v14, v15 offset0:130 offset1:195
	s_waitcnt vmcnt(2)
	ds_write2_b32 v4, v16, v17 offset0:4 offset1:69
	s_waitcnt vmcnt(0)
	ds_write2_b32 v4, v18, v19 offset0:134 offset1:199
	s_waitcnt lgkmcnt(0)
	s_barrier
	ds_read2_b32 v[6:7], v11 offset1:65
	ds_read2_b32 v[14:15], v11 offset0:130 offset1:195
	s_add_i32 s1, s0, s1
	s_and_b32 s6, s1, 0x3fffff0
	s_sub_i32 s6, s0, s6
	v_add_u32_e32 v4, 0x400, v11
	ds_read2_b32 v[16:17], v4 offset0:4 offset1:69
	ds_read2_b32 v[18:19], v4 offset0:134 offset1:199
	s_waitcnt lgkmcnt(3)
	v_cvt_pk_bf16_f32 v12, v6, v7
	v_lshl_add_u32 v6, s6, 6, v9
	s_lshl_b32 s0, s1, 2
	v_ashrrev_i32_e32 v7, 31, v6
	s_andn2_b32 s0, s0, 63
	v_lshlrev_b64 v[6:7], 11, v[6:7]
	v_lshl_add_u64 v[6:7], s[2:3], 0, v[6:7]
	s_ashr_i32 s1, s0, 31
	v_lshl_add_u64 v[6:7], s[0:1], 1, v[6:7]
	s_waitcnt lgkmcnt(2)
	v_cvt_pk_bf16_f32 v13, v14, v15
	s_waitcnt lgkmcnt(1)
	v_cvt_pk_bf16_f32 v14, v16, v17
	s_waitcnt lgkmcnt(0)
	v_cvt_pk_bf16_f32 v15, v18, v19
	v_lshl_add_u64 v[6:7], v[6:7], 0, v[2:3]
	global_store_dwordx4 v[6:7], v[12:15], off sc1
	s_andn2_b64 vcc, exec, s[4:5]
	s_mov_b32 s6, s8
	v_mov_b32_e32 v12, v5
	v_mov_b32_e32 v13, v21
	v_mov_b32_e32 v14, v23
	v_mov_b32_e32 v15, v22
	v_mov_b32_e32 v16, v25
	v_mov_b32_e32 v17, v24
	v_mov_b32_e32 v18, v27
	v_mov_b32_e32 v19, v26
	s_barrier
	s_cbranch_vccz .LBB0_243

.LBB0_311:
	s_add_i32 s0, s8, 0xffffef80
	s_mul_hi_i32 s1, s0, 0x92492493
	s_waitcnt vmcnt(0)
	ds_write2_b32 v27, v2, v3 offset1:65
	ds_write2_b32 v27, v4, v5 offset0:130 offset1:195
	v_add_u32_e32 v2, 0x400, v27
	s_add_i32 s1, s1, s0
	ds_write2_b32 v2, v6, v7 offset0:4 offset1:69
	ds_write2_b32 v2, v8, v9 offset0:134 offset1:199
	s_waitcnt lgkmcnt(0)
	s_barrier
	ds_read2_b32 v[2:3], v29 offset1:65
	ds_read2_b32 v[4:5], v29 offset0:130 offset1:195
	v_add_u32_e32 v8, 0x400, v29
	s_lshr_b32 s8, s1, 31
	s_ashr_i32 s1, s1, 5
	ds_read2_b32 v[6:7], v8 offset0:4 offset1:69
	ds_read2_b32 v[8:9], v8 offset0:134 offset1:199
	s_add_i32 s1, s1, s8
	s_mul_i32 s8, s1, 56
	s_sub_i32 s8, s0, s8
	s_waitcnt lgkmcnt(3)
	v_cvt_pk_bf16_f32 v2, v2, v3
	s_waitcnt lgkmcnt(2)
	v_cvt_pk_bf16_f32 v3, v4, v5
	s_waitcnt lgkmcnt(1)
	v_cvt_pk_bf16_f32 v4, v6, v7
	v_lshl_add_u32 v6, s8, 6, v26
	v_ashrrev_i32_e32 v7, 31, v6
	s_lshl_b32 s0, s1, 6
	v_lshlrev_b64 v[6:7], 11, v[6:7]
	v_lshl_add_u64 v[6:7], s[2:3], 0, v[6:7]
	s_ashr_i32 s1, s0, 31
	v_lshl_add_u64 v[6:7], s[0:1], 1, v[6:7]
	v_mov_b32_e32 v23, v10
	v_lshl_add_u64 v[6:7], v[6:7], 0, v[22:23]
	s_andn2_b64 vcc, exec, s[4:5]
	s_waitcnt lgkmcnt(0)
	v_cvt_pk_bf16_f32 v5, v8, v9
	global_store_dwordx4 v[6:7], v[2:5], off sc1
	s_barrier
	s_cbranch_vccz .LBB0_222
	v_mov_b64_e32 v[2:3], v[12:13]
	s_mov_b32 s8, s6
	v_mov_b64_e32 v[4:5], v[14:15]
	v_mov_b64_e32 v[6:7], v[16:17]
	v_mov_b64_e32 v[8:9], v[18:19]
	s_branch .LBB0_293

.LBB0_458:
	v_add_u32_e32 v124, s22, v147
	v_ashrrev_i32_e32 v125, 31, v124
	v_lshl_add_u64 v[128:129], v[124:125], 1, s[48:49]
	v_mad_i64_i32 v[124:125], s[22:23], s46, v146, 0
	v_lshl_add_u64 v[124:125], v[124:125], 1, v[128:129]
	global_store_dwordx4 v[124:125], v[132:135], off sc1
	v_cndmask_b32_e64 v124, 0, 1, s[26:27]
	v_cmp_ne_u32_e64 s[40:41], 1, v124
	s_andn2_b64 vcc, exec, s[26:27]
	s_mov_b64 s[26:27], -1
	s_cbranch_vccnz .LBB0_460
	v_cvt_f16_f32_e32 v124, v120
	v_cvt_f16_f32_sdwa v125, v121 dst_sel:WORD_1 dst_unused:UNUSED_PAD src0_sel:DWORD
	v_cvt_f16_f32_sdwa v126, v123 dst_sel:WORD_1 dst_unused:UNUSED_PAD src0_sel:DWORD
	v_cvt_f16_f32_sdwa v127, v117 dst_sel:WORD_1 dst_unused:UNUSED_PAD src0_sel:DWORD
	v_cvt_f16_f32_sdwa v130, v119 dst_sel:WORD_1 dst_unused:UNUSED_PAD src0_sel:DWORD
	v_or_b32_e32 v124, v125, v124
	v_cvt_f16_f32_e32 v125, v122
	s_mov_b64 s[26:27], 0
	v_or_b32_e32 v125, v126, v125
	v_cvt_f16_f32_e32 v126, v116
	v_or_b32_e32 v126, v127, v126
	v_cvt_f16_f32_e32 v127, v118
	v_or_b32_e32 v127, v130, v127

.LBB0_462:
	v_or_b32_e32 v116, 16, v146
	v_mad_i64_i32 v[116:117], s[22:23], s46, v116, 0
	v_lshl_add_u64 v[116:117], v[116:117], 1, v[128:129]
	s_and_b64 vcc, exec, s[40:41]
	s_mov_b64 s[26:27], -1
	global_store_dwordx4 v[116:117], v[124:127], off sc1
	s_cbranch_vccnz .LBB0_464
	v_cvt_f16_f32_e32 v116, v112
	v_cvt_f16_f32_sdwa v117, v113 dst_sel:WORD_1 dst_unused:UNUSED_PAD src0_sel:DWORD
	v_cvt_f16_f32_sdwa v118, v115 dst_sel:WORD_1 dst_unused:UNUSED_PAD src0_sel:DWORD
	v_cvt_f16_f32_sdwa v119, v109 dst_sel:WORD_1 dst_unused:UNUSED_PAD src0_sel:DWORD
	v_cvt_f16_f32_sdwa v120, v111 dst_sel:WORD_1 dst_unused:UNUSED_PAD src0_sel:DWORD
	v_or_b32_e32 v116, v117, v116
	v_cvt_f16_f32_e32 v117, v114
	s_mov_b64 s[26:27], 0
	v_or_b32_e32 v117, v118, v117
	v_cvt_f16_f32_e32 v118, v108
	v_or_b32_e32 v118, v119, v118
	v_cvt_f16_f32_e32 v119, v110
	v_or_b32_e32 v119, v120, v119

.LBB0_466:
	v_or_b32_e32 v108, 32, v146
	v_mad_i64_i32 v[108:109], s[22:23], s46, v108, 0
	v_lshl_add_u64 v[108:109], v[108:109], 1, v[128:129]
	s_and_b64 vcc, exec, s[40:41]
	s_mov_b64 s[26:27], -1
	global_store_dwordx4 v[108:109], v[116:119], off sc1
	s_cbranch_vccnz .LBB0_468
	v_cvt_f16_f32_e32 v108, v104
	v_cvt_f16_f32_sdwa v109, v105 dst_sel:WORD_1 dst_unused:UNUSED_PAD src0_sel:DWORD
	v_cvt_f16_f32_sdwa v110, v107 dst_sel:WORD_1 dst_unused:UNUSED_PAD src0_sel:DWORD
	v_cvt_f16_f32_sdwa v111, v101 dst_sel:WORD_1 dst_unused:UNUSED_PAD src0_sel:DWORD
	v_cvt_f16_f32_sdwa v112, v103 dst_sel:WORD_1 dst_unused:UNUSED_PAD src0_sel:DWORD
	v_or_b32_e32 v108, v109, v108
	v_cvt_f16_f32_e32 v109, v106
	s_mov_b64 s[26:27], 0
	v_or_b32_e32 v109, v110, v109
	v_cvt_f16_f32_e32 v110, v100
	v_or_b32_e32 v110, v111, v110
	v_cvt_f16_f32_e32 v111, v102
	v_or_b32_e32 v111, v112, v111

.LBB0_470:
	v_or_b32_e32 v100, 48, v146
	v_mad_i64_i32 v[100:101], s[22:23], s46, v100, 0
	v_lshl_add_u64 v[100:101], v[100:101], 1, v[128:129]
	s_and_b64 vcc, exec, s[40:41]
	s_mov_b64 s[26:27], -1
	global_store_dwordx4 v[100:101], v[108:111], off sc1
	s_cbranch_vccnz .LBB0_472
	v_cvt_f16_f32_e32 v100, v96
	v_cvt_f16_f32_sdwa v101, v97 dst_sel:WORD_1 dst_unused:UNUSED_PAD src0_sel:DWORD
	v_cvt_f16_f32_sdwa v102, v99 dst_sel:WORD_1 dst_unused:UNUSED_PAD src0_sel:DWORD
	v_cvt_f16_f32_sdwa v103, v93 dst_sel:WORD_1 dst_unused:UNUSED_PAD src0_sel:DWORD
	v_cvt_f16_f32_sdwa v104, v95 dst_sel:WORD_1 dst_unused:UNUSED_PAD src0_sel:DWORD
	v_or_b32_e32 v100, v101, v100
	v_cvt_f16_f32_e32 v101, v98
	s_mov_b64 s[26:27], 0
	v_or_b32_e32 v101, v102, v101
	v_cvt_f16_f32_e32 v102, v92
	v_or_b32_e32 v102, v103, v102
	v_cvt_f16_f32_e32 v103, v94
	v_or_b32_e32 v103, v104, v103

.LBB0_474:
	v_add_u32_e32 v92, 0x80, v146
	v_mad_i64_i32 v[92:93], s[22:23], s46, v92, 0
	v_lshl_add_u64 v[92:93], v[92:93], 1, v[128:129]
	s_and_b64 vcc, exec, s[40:41]
	s_mov_b64 s[26:27], -1
	global_store_dwordx4 v[92:93], v[100:103], off sc1
	s_cbranch_vccnz .LBB0_476
	v_cvt_f16_f32_e32 v92, v88
	v_cvt_f16_f32_sdwa v93, v89 dst_sel:WORD_1 dst_unused:UNUSED_PAD src0_sel:DWORD
	v_cvt_f16_f32_sdwa v94, v91 dst_sel:WORD_1 dst_unused:UNUSED_PAD src0_sel:DWORD
	v_cvt_f16_f32_sdwa v95, v85 dst_sel:WORD_1 dst_unused:UNUSED_PAD src0_sel:DWORD
	v_cvt_f16_f32_sdwa v96, v87 dst_sel:WORD_1 dst_unused:UNUSED_PAD src0_sel:DWORD
	v_or_b32_e32 v92, v93, v92
	v_cvt_f16_f32_e32 v93, v90
	s_mov_b64 s[26:27], 0
	v_or_b32_e32 v93, v94, v93
	v_cvt_f16_f32_e32 v94, v84
	v_or_b32_e32 v94, v95, v94
	v_cvt_f16_f32_e32 v95, v86
	v_or_b32_e32 v95, v96, v95

.LBB0_478:
	v_add_u32_e32 v84, 0x90, v146
	v_mad_i64_i32 v[84:85], s[22:23], s46, v84, 0
	v_lshl_add_u64 v[84:85], v[84:85], 1, v[128:129]
	s_and_b64 vcc, exec, s[40:41]
	s_mov_b64 s[26:27], -1
	global_store_dwordx4 v[84:85], v[92:95], off sc1
	s_cbranch_vccnz .LBB0_480
	v_cvt_f16_f32_e32 v84, v80
	v_cvt_f16_f32_sdwa v85, v81 dst_sel:WORD_1 dst_unused:UNUSED_PAD src0_sel:DWORD
	v_cvt_f16_f32_sdwa v86, v83 dst_sel:WORD_1 dst_unused:UNUSED_PAD src0_sel:DWORD
	v_cvt_f16_f32_sdwa v87, v77 dst_sel:WORD_1 dst_unused:UNUSED_PAD src0_sel:DWORD
	v_cvt_f16_f32_sdwa v88, v79 dst_sel:WORD_1 dst_unused:UNUSED_PAD src0_sel:DWORD
	v_or_b32_e32 v84, v85, v84
	v_cvt_f16_f32_e32 v85, v82
	s_mov_b64 s[26:27], 0
	v_or_b32_e32 v85, v86, v85
	v_cvt_f16_f32_e32 v86, v76
	v_or_b32_e32 v86, v87, v86
	v_cvt_f16_f32_e32 v87, v78
	v_or_b32_e32 v87, v88, v87

.LBB0_482:
	v_add_u32_e32 v76, 0xa0, v146
	v_mad_i64_i32 v[76:77], s[22:23], s46, v76, 0
	v_lshl_add_u64 v[76:77], v[76:77], 1, v[128:129]
	s_and_b64 vcc, exec, s[40:41]
	s_mov_b64 s[26:27], -1
	global_store_dwordx4 v[76:77], v[84:87], off sc1
	s_cbranch_vccnz .LBB0_484
	v_cvt_f16_f32_e32 v76, v72
	v_cvt_f16_f32_sdwa v77, v73 dst_sel:WORD_1 dst_unused:UNUSED_PAD src0_sel:DWORD
	v_cvt_f16_f32_sdwa v78, v75 dst_sel:WORD_1 dst_unused:UNUSED_PAD src0_sel:DWORD
	v_cvt_f16_f32_sdwa v79, v69 dst_sel:WORD_1 dst_unused:UNUSED_PAD src0_sel:DWORD
	v_cvt_f16_f32_sdwa v80, v71 dst_sel:WORD_1 dst_unused:UNUSED_PAD src0_sel:DWORD
	v_or_b32_e32 v76, v77, v76
	v_cvt_f16_f32_e32 v77, v74
	s_mov_b64 s[26:27], 0
	v_or_b32_e32 v77, v78, v77
	v_cvt_f16_f32_e32 v78, v68
	v_or_b32_e32 v78, v79, v78
	v_cvt_f16_f32_e32 v79, v70
	v_or_b32_e32 v79, v80, v79

.LBB0_486:
	v_add_u32_e32 v68, 0xb0, v146
	v_mad_i64_i32 v[68:69], s[22:23], s46, v68, 0
	v_lshl_add_u64 v[68:69], v[68:69], 1, v[128:129]
	global_store_dwordx4 v[68:69], v[76:79], off sc1

.LBB0_504:
	v_add_u32_e32 v60, s22, v147
	v_ashrrev_i32_e32 v61, 31, v60
	v_lshl_add_u64 v[64:65], v[60:61], 1, s[26:27]
	v_mad_i64_i32 v[60:61], s[22:23], s46, v146, 0
	v_lshl_add_u64 v[60:61], v[60:61], 1, v[64:65]
	s_and_b64 vcc, exec, s[40:41]
	s_mov_b64 s[26:27], -1
	global_store_dwordx4 v[60:61], v[68:71], off sc1
	s_cbranch_vccnz .LBB0_506
	v_cvt_f16_f32_e32 v60, v56
	v_cvt_f16_f32_sdwa v61, v57 dst_sel:WORD_1 dst_unused:UNUSED_PAD src0_sel:DWORD
	v_cvt_f16_f32_sdwa v62, v59 dst_sel:WORD_1 dst_unused:UNUSED_PAD src0_sel:DWORD
	v_cvt_f16_f32_sdwa v63, v53 dst_sel:WORD_1 dst_unused:UNUSED_PAD src0_sel:DWORD
	v_cvt_f16_f32_sdwa v66, v55 dst_sel:WORD_1 dst_unused:UNUSED_PAD src0_sel:DWORD
	v_or_b32_e32 v60, v61, v60
	v_cvt_f16_f32_e32 v61, v58
	s_mov_b64 s[26:27], 0
	v_or_b32_e32 v61, v62, v61
	v_cvt_f16_f32_e32 v62, v52
	v_or_b32_e32 v62, v63, v62
	v_cvt_f16_f32_e32 v63, v54
	v_or_b32_e32 v63, v66, v63

.LBB0_508:
	v_or_b32_e32 v52, 16, v146
	v_mad_i64_i32 v[52:53], s[22:23], s46, v52, 0
	v_lshl_add_u64 v[52:53], v[52:53], 1, v[64:65]
	s_and_b64 vcc, exec, s[40:41]
	s_mov_b64 s[26:27], -1
	global_store_dwordx4 v[52:53], v[60:63], off sc1
	s_cbranch_vccnz .LBB0_510
	v_cvt_f16_f32_e32 v52, v44
	v_cvt_f16_f32_sdwa v53, v45 dst_sel:WORD_1 dst_unused:UNUSED_PAD src0_sel:DWORD
	v_cvt_f16_f32_sdwa v54, v47 dst_sel:WORD_1 dst_unused:UNUSED_PAD src0_sel:DWORD
	v_cvt_f16_f32_sdwa v55, v41 dst_sel:WORD_1 dst_unused:UNUSED_PAD src0_sel:DWORD
	v_cvt_f16_f32_sdwa v56, v43 dst_sel:WORD_1 dst_unused:UNUSED_PAD src0_sel:DWORD
	v_or_b32_e32 v52, v53, v52
	v_cvt_f16_f32_e32 v53, v46
	s_mov_b64 s[26:27], 0
	v_or_b32_e32 v53, v54, v53
	v_cvt_f16_f32_e32 v54, v40
	v_or_b32_e32 v54, v55, v54
	v_cvt_f16_f32_e32 v55, v42
	v_or_b32_e32 v55, v56, v55

.LBB0_512:
	v_or_b32_e32 v40, 32, v146
	v_mad_i64_i32 v[40:41], s[22:23], s46, v40, 0
	v_lshl_add_u64 v[40:41], v[40:41], 1, v[64:65]
	s_and_b64 vcc, exec, s[40:41]
	s_mov_b64 s[26:27], -1
	global_store_dwordx4 v[40:41], v[52:55], off sc1
	s_cbranch_vccnz .LBB0_514
	v_cvt_f16_f32_e32 v40, v36
	v_cvt_f16_f32_sdwa v41, v37 dst_sel:WORD_1 dst_unused:UNUSED_PAD src0_sel:DWORD
	v_cvt_f16_f32_sdwa v42, v39 dst_sel:WORD_1 dst_unused:UNUSED_PAD src0_sel:DWORD
	v_cvt_f16_f32_sdwa v43, v33 dst_sel:WORD_1 dst_unused:UNUSED_PAD src0_sel:DWORD
	v_cvt_f16_f32_sdwa v44, v35 dst_sel:WORD_1 dst_unused:UNUSED_PAD src0_sel:DWORD
	v_or_b32_e32 v40, v41, v40
	v_cvt_f16_f32_e32 v41, v38
	s_mov_b64 s[26:27], 0
	v_or_b32_e32 v41, v42, v41
	v_cvt_f16_f32_e32 v42, v32
	v_or_b32_e32 v42, v43, v42
	v_cvt_f16_f32_e32 v43, v34
	v_or_b32_e32 v43, v44, v43

.LBB0_516:
	v_or_b32_e32 v32, 48, v146
	v_mad_i64_i32 v[32:33], s[22:23], s46, v32, 0
	v_lshl_add_u64 v[32:33], v[32:33], 1, v[64:65]
	s_and_b64 vcc, exec, s[40:41]
	s_mov_b64 s[26:27], -1
	global_store_dwordx4 v[32:33], v[40:43], off sc1
	s_cbranch_vccnz .LBB0_518
	v_cvt_f16_f32_e32 v32, v28
	v_cvt_f16_f32_sdwa v33, v29 dst_sel:WORD_1 dst_unused:UNUSED_PAD src0_sel:DWORD
	v_cvt_f16_f32_sdwa v34, v31 dst_sel:WORD_1 dst_unused:UNUSED_PAD src0_sel:DWORD
	v_cvt_f16_f32_sdwa v35, v25 dst_sel:WORD_1 dst_unused:UNUSED_PAD src0_sel:DWORD
	v_cvt_f16_f32_sdwa v36, v27 dst_sel:WORD_1 dst_unused:UNUSED_PAD src0_sel:DWORD
	v_or_b32_e32 v32, v33, v32
	v_cvt_f16_f32_e32 v33, v30
	s_mov_b64 s[26:27], 0
	v_or_b32_e32 v33, v34, v33
	v_cvt_f16_f32_e32 v34, v24
	v_or_b32_e32 v34, v35, v34
	v_cvt_f16_f32_e32 v35, v26
	v_or_b32_e32 v35, v36, v35

.LBB0_520:
	v_add_u32_e32 v24, 0x80, v146
	v_mad_i64_i32 v[24:25], s[22:23], s46, v24, 0
	v_lshl_add_u64 v[24:25], v[24:25], 1, v[64:65]
	s_and_b64 vcc, exec, s[40:41]
	s_mov_b64 s[26:27], -1
	global_store_dwordx4 v[24:25], v[32:35], off sc1
	s_cbranch_vccnz .LBB0_522
	v_cvt_f16_f32_e32 v24, v20
	v_cvt_f16_f32_sdwa v25, v21 dst_sel:WORD_1 dst_unused:UNUSED_PAD src0_sel:DWORD
	v_cvt_f16_f32_sdwa v26, v23 dst_sel:WORD_1 dst_unused:UNUSED_PAD src0_sel:DWORD
	v_cvt_f16_f32_sdwa v27, v17 dst_sel:WORD_1 dst_unused:UNUSED_PAD src0_sel:DWORD
	v_cvt_f16_f32_sdwa v28, v19 dst_sel:WORD_1 dst_unused:UNUSED_PAD src0_sel:DWORD
	v_or_b32_e32 v24, v25, v24
	v_cvt_f16_f32_e32 v25, v22
	s_mov_b64 s[26:27], 0
	v_or_b32_e32 v25, v26, v25
	v_cvt_f16_f32_e32 v26, v16
	v_or_b32_e32 v26, v27, v26
	v_cvt_f16_f32_e32 v27, v18
	v_or_b32_e32 v27, v28, v27

.LBB0_524:
	v_add_u32_e32 v16, 0x90, v146
	v_mad_i64_i32 v[16:17], s[22:23], s46, v16, 0
	v_lshl_add_u64 v[16:17], v[16:17], 1, v[64:65]
	s_and_b64 vcc, exec, s[40:41]
	s_mov_b64 s[26:27], -1
	global_store_dwordx4 v[16:17], v[24:27], off sc1
	s_cbranch_vccnz .LBB0_526
	v_cvt_f16_f32_e32 v16, v12
	v_cvt_f16_f32_sdwa v17, v13 dst_sel:WORD_1 dst_unused:UNUSED_PAD src0_sel:DWORD
	v_cvt_f16_f32_sdwa v18, v15 dst_sel:WORD_1 dst_unused:UNUSED_PAD src0_sel:DWORD
	v_cvt_f16_f32_sdwa v19, v9 dst_sel:WORD_1 dst_unused:UNUSED_PAD src0_sel:DWORD
	v_cvt_f16_f32_sdwa v20, v11 dst_sel:WORD_1 dst_unused:UNUSED_PAD src0_sel:DWORD
	v_or_b32_e32 v16, v17, v16
	v_cvt_f16_f32_e32 v17, v14
	s_mov_b64 s[26:27], 0
	v_or_b32_e32 v17, v18, v17
	v_cvt_f16_f32_e32 v18, v8
	v_or_b32_e32 v18, v19, v18
	v_cvt_f16_f32_e32 v19, v10
	v_or_b32_e32 v19, v20, v19

.LBB0_528:
	v_add_u32_e32 v8, 0xa0, v146
	v_mad_i64_i32 v[8:9], s[22:23], s46, v8, 0
	v_lshl_add_u64 v[8:9], v[8:9], 1, v[64:65]
	s_and_b64 vcc, exec, s[40:41]
	s_mov_b64 s[26:27], -1
	global_store_dwordx4 v[8:9], v[16:19], off sc1
	s_cbranch_vccnz .LBB0_530
	v_cvt_f16_f32_e32 v8, v4
	v_cvt_f16_f32_sdwa v9, v5 dst_sel:WORD_1 dst_unused:UNUSED_PAD src0_sel:DWORD
	v_cvt_f16_f32_sdwa v10, v7 dst_sel:WORD_1 dst_unused:UNUSED_PAD src0_sel:DWORD
	v_cvt_f16_f32_sdwa v11, v1 dst_sel:WORD_1 dst_unused:UNUSED_PAD src0_sel:DWORD
	v_cvt_f16_f32_sdwa v12, v3 dst_sel:WORD_1 dst_unused:UNUSED_PAD src0_sel:DWORD
	v_or_b32_e32 v8, v9, v8
	v_cvt_f16_f32_e32 v9, v6
	s_mov_b64 s[26:27], 0
	v_or_b32_e32 v9, v10, v9
	v_cvt_f16_f32_e32 v10, v0
	v_or_b32_e32 v10, v11, v10
	v_cvt_f16_f32_e32 v11, v2
	v_or_b32_e32 v11, v12, v11

.LBB0_532:
	v_add_u32_e32 v0, 0xb0, v146
	v_mad_i64_i32 v[0:1], s[22:23], s46, v0, 0
	v_lshl_add_u64 v[0:1], v[0:1], 1, v[64:65]
	global_store_dwordx4 v[0:1], v[8:11], off sc1

.LBB0_643:
	s_or_b64 exec, exec, s[12:13]
	s_waitcnt vmcnt(0)
	v_cvt_f32_f16_e32 v49, v24
	v_cvt_f32_f16_sdwa v53, v24 dst_sel:DWORD dst_unused:UNUSED_PAD src0_sel:WORD_1
	v_cvt_f32_f16_e32 v55, v25
	v_cvt_f32_f16_sdwa v56, v25 dst_sel:DWORD dst_unused:UNUSED_PAD src0_sel:WORD_1
	v_cvt_f32_f16_e32 v62, v26
	v_cvt_f32_f16_sdwa v63, v26 dst_sel:DWORD dst_unused:UNUSED_PAD src0_sel:WORD_1
	v_cvt_f32_f16_e32 v64, v27
	v_cvt_f32_f16_sdwa v65, v27 dst_sel:DWORD dst_unused:UNUSED_PAD src0_sel:WORD_1
	v_cvt_f32_f16_e32 v24, v20
	v_cvt_f32_f16_sdwa v25, v20 dst_sel:DWORD dst_unused:UNUSED_PAD src0_sel:WORD_1
	v_cvt_f32_f16_e32 v26, v21
	v_cvt_f32_f16_sdwa v21, v21 dst_sel:DWORD dst_unused:UNUSED_PAD src0_sel:WORD_1
	v_cvt_f32_f16_e32 v27, v22
	v_cvt_f32_f16_sdwa v22, v22 dst_sel:DWORD dst_unused:UNUSED_PAD src0_sel:WORD_1
	v_cvt_f32_f16_e32 v31, v23
	v_cvt_f32_f16_sdwa v23, v23 dst_sel:DWORD dst_unused:UNUSED_PAD src0_sel:WORD_1
	v_cvt_f32_f16_e32 v20, v12
	v_cvt_f32_f16_sdwa v12, v12 dst_sel:DWORD dst_unused:UNUSED_PAD src0_sel:WORD_1
	v_cvt_f32_f16_e32 v30, v13
	v_cvt_f32_f16_sdwa v13, v13 dst_sel:DWORD dst_unused:UNUSED_PAD src0_sel:WORD_1
	v_cvt_f32_f16_e32 v32, v14
	v_cvt_f32_f16_sdwa v14, v14 dst_sel:DWORD dst_unused:UNUSED_PAD src0_sel:WORD_1
	v_cvt_f32_f16_e32 v33, v15
	v_cvt_f32_f16_sdwa v15, v15 dst_sel:DWORD dst_unused:UNUSED_PAD src0_sel:WORD_1
	v_mul_f32_e32 v20, v24, v20
	v_mul_f32_e32 v38, v25, v12
	v_mul_f32_e32 v36, v26, v30
	v_mul_f32_e32 v34, v21, v13
	v_mul_f32_e32 v30, v22, v14
	v_mul_f32_e32 v24, v23, v15
	v_cvt_f32_f16_e32 v54, v8
	v_cvt_f32_f16_sdwa v52, v8 dst_sel:DWORD dst_unused:UNUSED_PAD src0_sel:WORD_1
	v_cvt_f32_f16_e32 v48, v9
	v_cvt_f32_f16_sdwa v47, v9 dst_sel:DWORD dst_unused:UNUSED_PAD src0_sel:WORD_1
	v_cvt_f32_f16_e32 v46, v10
	v_cvt_f32_f16_sdwa v45, v10 dst_sel:DWORD dst_unused:UNUSED_PAD src0_sel:WORD_1
	v_cvt_f32_f16_e32 v44, v11
	v_cvt_f32_f16_sdwa v43, v11 dst_sel:DWORD dst_unused:UNUSED_PAD src0_sel:WORD_1
	v_cvt_f32_f16_e32 v8, v4
	v_cvt_f32_f16_sdwa v4, v4 dst_sel:DWORD dst_unused:UNUSED_PAD src0_sel:WORD_1
	v_cvt_f32_f16_e32 v9, v5
	v_cvt_f32_f16_sdwa v5, v5 dst_sel:DWORD dst_unused:UNUSED_PAD src0_sel:WORD_1
	v_cvt_f32_f16_e32 v10, v6
	v_cvt_f32_f16_sdwa v6, v6 dst_sel:DWORD dst_unused:UNUSED_PAD src0_sel:WORD_1
	v_cvt_f32_f16_e32 v11, v7
	v_cvt_f32_f16_sdwa v7, v7 dst_sel:DWORD dst_unused:UNUSED_PAD src0_sel:WORD_1
	v_cvt_f32_f16_e32 v12, v0
	v_cvt_f32_f16_sdwa v0, v0 dst_sel:DWORD dst_unused:UNUSED_PAD src0_sel:WORD_1
	v_cvt_f32_f16_e32 v13, v1
	v_cvt_f32_f16_sdwa v1, v1 dst_sel:DWORD dst_unused:UNUSED_PAD src0_sel:WORD_1
	v_cvt_f32_f16_e32 v14, v2
	v_cvt_f32_f16_sdwa v2, v2 dst_sel:DWORD dst_unused:UNUSED_PAD src0_sel:WORD_1
	v_cvt_f32_f16_e32 v15, v3
	v_cvt_f32_f16_sdwa v3, v3 dst_sel:DWORD dst_unused:UNUSED_PAD src0_sel:WORD_1
	v_mul_f32_e32 v26, v31, v33
	v_mul_f32_e32 v39, v4, v0
	v_mul_f32_e32 v35, v5, v1
	v_mul_f32_e32 v31, v6, v2
	v_mul_f32_e32 v25, v7, v3
	v_cvt_f32_f16_e32 v0, v16
	v_cvt_f32_f16_sdwa v1, v16 dst_sel:DWORD dst_unused:UNUSED_PAD src0_sel:WORD_1
	v_cvt_f32_f16_e32 v2, v17
	v_cvt_f32_f16_sdwa v3, v17 dst_sel:DWORD dst_unused:UNUSED_PAD src0_sel:WORD_1
	v_cvt_f32_f16_e32 v4, v18
	v_cvt_f32_f16_sdwa v5, v18 dst_sel:DWORD dst_unused:UNUSED_PAD src0_sel:WORD_1
	v_cvt_f32_f16_e32 v6, v19
	v_cvt_f32_f16_sdwa v7, v19 dst_sel:DWORD dst_unused:UNUSED_PAD src0_sel:WORD_1
	v_readlane_b32 s0, v254, 48
	v_lshlrev_b32_e32 v22, 2, v61
	v_readlane_b32 s1, v254, 49
	v_mul_f32_e32 v32, v27, v32
	v_mul_f32_e32 v21, v8, v12
	v_mul_f32_e32 v37, v9, v13
	v_mul_f32_e32 v33, v10, v14
	v_mul_f32_e32 v27, v11, v15
	v_mul_f32_e32 v60, v49, v0
	v_mul_f32_e32 v59, v53, v1
	v_mul_f32_e32 v58, v55, v2
	v_mul_f32_e32 v57, v56, v3
	v_mul_f32_e32 v56, v62, v4
	v_mul_f32_e32 v55, v63, v5
	v_mul_f32_e32 v53, v64, v6
	v_mul_f32_e32 v49, v65, v7
	global_load_dwordx4 v[0:3], v22, s[0:1] offset:16
	global_load_dwordx4 v[12:15], v22, s[0:1]
	global_load_dwordx4 v[4:7], v22, s[0:1] offset:1040
	global_load_dwordx4 v[16:19], v22, s[0:1] offset:1024
	v_ashrrev_i32_e32 v29, 31, v28
	v_add_u32_e32 v42, s87, v42
	s_waitcnt vmcnt(2)
	v_mov_b32_e32 v8, v12
	s_waitcnt vmcnt(0)
	v_mov_b32_e32 v9, v16
	v_pk_mul_f32 v[8:9], v[20:21], v[8:9]
	v_mov_b32_e32 v16, v13
	v_add_f32_e32 v12, v8, v9
	global_load_dwordx4 v[8:11], v22, s[0:1] offset:2064
	s_nop 0
	global_load_dwordx4 v[20:23], v22, s[0:1] offset:2048
	v_readlane_b32 s0, v254, 5
	s_waitcnt vmcnt(0)
	v_fmac_f32_e32 v12, v20, v60
	v_mul_f32_e32 v20, v12, v54
	v_pk_mul_f32 v[12:13], v[38:39], v[16:17]
	v_add_u32_e32 v41, s0, v41
	v_add_f32_e32 v12, v12, v13
	v_fmac_f32_e32 v12, v59, v21
	v_mul_f32_e32 v16, v12, v52
	v_mov_b32_e32 v12, v14
	v_mov_b32_e32 v13, v18
	v_pk_mul_f32 v[12:13], v[36:37], v[12:13]
	v_mov_b32_e32 v18, v15
	v_add_f32_e32 v12, v12, v13
	v_fmac_f32_e32 v12, v58, v22
	v_mul_f32_e32 v14, v12, v48
	v_pk_mul_f32 v[12:13], v[34:35], v[18:19]
	s_mov_b32 s0, 0xfffff
	v_add_f32_e32 v12, v12, v13
	v_fmac_f32_e32 v12, v57, v23
	v_mul_f32_e32 v15, v12, v47
	v_mov_b32_e32 v12, v0
	v_mov_b32_e32 v13, v4
	v_pk_mul_f32 v[12:13], v[32:33], v[12:13]
	v_mov_b32_e32 v4, v1
	v_add_f32_e32 v0, v12, v13
	v_fmac_f32_e32 v0, v56, v8
	v_mul_f32_e32 v8, v0, v46
	v_pk_mul_f32 v[0:1], v[30:31], v[4:5]
	s_nop 0
	v_add_f32_e32 v0, v0, v1
	v_fmac_f32_e32 v0, v55, v9
	v_mul_f32_e32 v4, v0, v45
	v_mov_b32_e32 v0, v2
	v_mov_b32_e32 v1, v6
	v_pk_mul_f32 v[0:1], v[26:27], v[0:1]
	v_mov_b32_e32 v6, v3
	v_add_f32_e32 v0, v0, v1
	v_fmac_f32_e32 v0, v53, v10
	v_mul_f32_e32 v5, v0, v44
	v_pk_mul_f32 v[0:1], v[24:25], v[6:7]
	s_nop 0
	v_add_f32_e32 v0, v0, v1
	v_fmac_f32_e32 v0, v49, v11
	v_mul_f32_e32 v3, v0, v43
	v_cvt_pk_bf16_f32 v0, v20, v16
	v_cvt_pk_bf16_f32 v1, v14, v15
	v_cvt_pk_bf16_f32 v2, v8, v4
	v_cvt_pk_bf16_f32 v3, v5, v3
	v_lshlrev_b64 v[4:5], 11, v[28:29]
	v_lshl_add_u64 v[4:5], s[92:93], 0, v[4:5]
	v_lshl_add_u64 v[4:5], v[4:5], 0, v[50:51]
	v_add_co_u32_e32 v4, vcc, 0x2c00000, v4
	s_nop 1
	v_addc_co_u32_e32 v5, vcc, 0, v5, vcc
	v_cmp_lt_i32_e32 vcc, s0, v42
	s_or_b64 s[6:7], vcc, s[6:7]
	global_store_dwordx4 v[4:5], v[0:3], off offset:768 sc1
	s_andn2_b64 exec, exec, s[6:7]
	s_cbranch_execz .LBB0_652

.LBB0_654:
	s_or_b64 exec, exec, s[12:13]
	v_readlane_b32 s8, v253, 13
	v_readlane_b32 s9, v253, 14
	v_add_u32_e32 v14, s87, v14
	s_mov_b32 s1, 0x17ffff
	v_cvt_pk_bf16_f32 v0, v13, v0
	v_cvt_pk_bf16_f32 v1, v4, v1
	v_cvt_pk_bf16_f32 v2, v5, v2
	v_lshl_add_u64 v[4:5], v[18:19], 1, s[8:9]
	v_cmp_lt_i32_e32 vcc, s1, v14
	v_lshl_add_u64 v[4:5], v[16:17], 1, v[4:5]
	s_or_b64 s[6:7], vcc, s[6:7]
	v_add_u32_e32 v12, s0, v12
	v_cvt_pk_bf16_f32 v3, v6, v3
	global_store_dwordx4 v[4:5], v[0:3], off sc1
	s_andn2_b64 exec, exec, s[6:7]
	s_cbranch_execz .LBB0_691

.LBB0_843:
	v_mul_hi_i32 v144, v141, s85
	v_lshrrev_b32_e32 v145, 31, v144
	v_ashrrev_i32_e32 v144, 6, v144
	v_add_u32_e32 v146, v144, v145
	v_mul_i32_i24_e32 v144, 0x180, v146
	v_sub_u32_e32 v144, v141, v144
	v_ashrrev_i32_e32 v147, 31, v146
	v_lshlrev_b64 v[146:147], 15, v[146:147]
	v_ashrrev_i32_e32 v145, 31, v144
	s_waitcnt vmcnt(0)
	v_add_f32_e32 v162, v128, v151
	v_add_f32_e32 v161, v129, v152
	v_add_f32_e32 v160, v130, v153
	v_add_f32_e32 v159, v131, v154
	v_add_f32_e32 v131, v124, v155
	v_add_f32_e32 v130, v125, v156
	v_add_f32_e32 v129, v126, v157
	v_add_f32_e32 v128, v127, v158
	s_cmp_lt_i32 s1, 1
	s_mov_b64 s[2:3], -1
	s_cbranch_scc1 .LBB0_849
	s_cmp_lg_u32 s1, 1
	s_cbranch_scc0 .LBB0_846
	v_ashrrev_i32_e32 v141, 31, v140
	v_lshlrev_b64 v[164:165], 11, v[140:141]
	v_lshl_add_u64 v[164:165], s[24:25], 0, v[164:165]
	v_lshl_add_u64 v[164:165], v[142:143], 1, v[164:165]
	v_cvt_pk_bf16_f32 v124, v162, v161
	v_cvt_pk_bf16_f32 v125, v160, v159
	v_cvt_pk_bf16_f32 v126, v131, v130
	v_cvt_pk_bf16_f32 v127, v129, v128
	global_store_dwordx4 v[164:165], v[124:127], off offset:-1792 sc1
	s_mov_b64 s[2:3], 0
.LBB0_846:
	s_andn2_b64 vcc, exec, s[2:3]
	s_cbranch_vccnz .LBB0_848
	v_mul_f32_e32 v124, 0xbfb8aa3b, v162
	v_mul_f32_e32 v125, 0xbfb8aa3b, v161
	v_mul_f32_e32 v126, 0xbfb8aa3b, v160
	v_mul_f32_e32 v127, 0xbfb8aa3b, v159
	v_mul_f32_e32 v141, 0xbfb8aa3b, v131
	v_mul_f32_e32 v163, 0xbfb8aa3b, v130
	v_exp_f32_e32 v124, v124
	v_exp_f32_e32 v125, v125
	v_exp_f32_e32 v126, v126
	v_exp_f32_e32 v127, v127
	v_exp_f32_e32 v141, v141
	v_exp_f32_e32 v163, v163
	v_mul_f32_e32 v164, 0xbfb8aa3b, v129
	v_mul_f32_e32 v165, 0xbfb8aa3b, v128
	v_exp_f32_e32 v164, v164
	v_exp_f32_e32 v165, v165
	v_add_f32_e32 v124, 1.0, v124
	v_add_f32_e32 v125, 1.0, v125
	v_add_f32_e32 v126, 1.0, v126
	v_add_f32_e32 v127, 1.0, v127
	v_add_f32_e32 v141, 1.0, v141
	v_add_f32_e32 v163, 1.0, v163
	v_rcp_f32_e32 v124, v124
	v_rcp_f32_e32 v125, v125
	v_rcp_f32_e32 v126, v126
	v_rcp_f32_e32 v127, v127
	v_rcp_f32_e32 v141, v141
	v_rcp_f32_e32 v163, v163
	v_add_f32_e32 v164, 1.0, v164
	v_add_f32_e32 v165, 1.0, v165
	v_rcp_f32_e32 v164, v164
	v_rcp_f32_e32 v165, v165
	v_cvt_f16_f32_e32 v124, v124
	v_cvt_f16_f32_sdwa v125, v125 dst_sel:WORD_1 dst_unused:UNUSED_PAD src0_sel:DWORD
	v_cvt_f16_f32_e32 v126, v126
	v_cvt_f16_f32_sdwa v127, v127 dst_sel:WORD_1 dst_unused:UNUSED_PAD src0_sel:DWORD
	v_cvt_f16_f32_e32 v141, v141
	v_cvt_f16_f32_sdwa v163, v163 dst_sel:WORD_1 dst_unused:UNUSED_PAD src0_sel:DWORD
	v_cvt_f16_f32_e32 v164, v164
	v_cvt_f16_f32_sdwa v165, v165 dst_sel:WORD_1 dst_unused:UNUSED_PAD src0_sel:DWORD
	v_readlane_b32 s2, v253, 19
	v_or_b32_e32 v124, v125, v124
	v_or_b32_e32 v125, v127, v126
	v_or_b32_e32 v126, v163, v141
	v_ashrrev_i32_e32 v141, 31, v140
	v_readlane_b32 s3, v253, 20
	v_or_b32_e32 v127, v165, v164
	v_lshl_add_u64 v[164:165], v[146:147], 0, v[140:141]
	v_mov_b64_e32 v[166:167], s[2:3]
	v_mad_u64_u32 v[166:167], s[2:3], v164, s77, v[166:167]
	v_mad_i32_i24 v167, v165, s77, v167
	v_lshl_add_u64 v[164:165], v[144:145], 1, v[166:167]
	global_store_dwordx4 v[164:165], v[124:127], off sc1

.LBB0_849:
	s_nop 0
	v_mul_hi_i32 v124, v142, s85
	v_lshrrev_b32_e32 v125, 31, v124
	v_ashrrev_i32_e32 v124, 6, v124
	v_add_u32_e32 v126, v124, v125
	v_mul_i32_i24_e32 v124, 0x180, v126
	v_sub_u32_e32 v124, v142, v124
	v_ashrrev_i32_e32 v127, 31, v126
	v_lshlrev_b64 v[126:127], 15, v[126:127]
	s_andn2_b64 vcc, exec, s[2:3]
	v_ashrrev_i32_e32 v125, 31, v124
	s_cbranch_vccnz .LBB0_851
	v_mul_f32_e32 v141, 0xbfb8aa3b, v162
	v_exp_f32_e32 v141, v141
	v_mul_f32_e32 v159, 0xbfb8aa3b, v159
	v_exp_f32_e32 v159, v159
	v_mul_f32_e32 v161, 0xbfb8aa3b, v161
	v_add_f32_e32 v141, 1.0, v141
	v_rcp_f32_e32 v162, v141
	v_mul_f32_e32 v141, 0xbfb8aa3b, v160
	v_exp_f32_e32 v141, v141
	v_exp_f32_e32 v161, v161
	v_mul_f32_e32 v131, 0xbfb8aa3b, v131
	v_mul_f32_e32 v130, 0xbfb8aa3b, v130
	v_add_f32_e32 v141, 1.0, v141
	v_mul_f32_e32 v129, 0xbfb8aa3b, v129
	v_mul_f32_e32 v128, 0xbfb8aa3b, v128
	v_rcp_f32_e32 v163, v141
	v_add_f32_e32 v141, 1.0, v159
	v_exp_f32_e32 v131, v131
	v_exp_f32_e32 v159, v130
	v_exp_f32_e32 v129, v129
	v_exp_f32_e32 v128, v128
	v_add_f32_e32 v161, 1.0, v161
	v_rcp_f32_e32 v160, v161
	v_rcp_f32_e32 v161, v141
	v_add_f32_e32 v130, 1.0, v131
	v_add_f32_e32 v131, 1.0, v159
	v_add_f32_e32 v129, 1.0, v129
	v_add_f32_e32 v128, 1.0, v128
	v_rcp_f32_e32 v130, v130
	v_rcp_f32_e32 v164, v131
	v_rcp_f32_e32 v131, v129
	v_rcp_f32_e32 v165, v128
	s_mov_b32 s2, 0xbf1b4598
	v_pk_mul_f32 v[128:129], v[162:163], s[2:3] op_sel_hi:[1,0]
	v_pk_mul_f32 v[160:161], v[160:161], s[2:3] op_sel_hi:[1,0]
	v_cvt_pk_f16_f32 v128, v128, v129
	v_cvt_pk_f16_f32 v129, v160, v161
	v_pk_mul_f32 v[130:131], v[130:131], s[2:3] op_sel_hi:[1,0]
	v_pk_mul_f32 v[160:161], v[164:165], s[2:3] op_sel_hi:[1,0]
	v_and_b32_e32 v141, 0xffff0000, v129
	v_cvt_pk_f16_f32 v130, v130, v131
	v_cvt_pk_f16_f32 v131, v160, v161
	v_lshlrev_b32_e32 v159, 16, v129
	v_or_b32_sdwa v129, v141, v128 dst_sel:DWORD dst_unused:UNUSED_PAD src0_sel:DWORD src1_sel:WORD_1
	v_and_b32_e32 v141, 0xffff0000, v131
	v_or_b32_sdwa v128, v159, v128 dst_sel:DWORD dst_unused:UNUSED_PAD src0_sel:DWORD src1_sel:WORD_0
	v_lshlrev_b32_e32 v159, 16, v131
	v_or_b32_sdwa v131, v141, v130 dst_sel:DWORD dst_unused:UNUSED_PAD src0_sel:DWORD src1_sel:WORD_1
	v_ashrrev_i32_e32 v141, 31, v140
	v_lshl_add_u64 v[160:161], v[126:127], 0, v[140:141]
	v_mov_b64_e32 v[162:163], s[4:5]
	v_mad_u64_u32 v[162:163], s[2:3], v160, s77, v[162:163]
	v_mad_i32_i24 v163, v161, s77, v163
	v_or_b32_sdwa v130, v159, v130 dst_sel:DWORD dst_unused:UNUSED_PAD src0_sel:DWORD src1_sel:WORD_0
	v_lshl_add_u64 v[160:161], v[124:125], 1, v[162:163]
	global_store_dwordx4 v[160:161], v[128:131], off sc1
.LBB0_851:
	s_nop 1
	v_add_f32_e32 v130, v120, v151
	v_add_f32_e32 v129, v121, v152
	v_add_f32_e32 v128, v122, v153
	v_add_f32_e32 v123, v123, v154
	v_add_f32_e32 v122, v116, v155
	v_add_f32_e32 v121, v117, v156
	v_add_f32_e32 v120, v118, v157
	v_add_f32_e32 v118, v119, v158
	v_or_b32_e32 v116, 16, v140
	s_cmp_lt_i32 s1, 1
	s_mov_b64 s[2:3], -1
	s_cbranch_scc1 .LBB0_857
	s_cmp_lg_u32 s1, 1
	s_cbranch_scc0 .LBB0_854
	v_ashrrev_i32_e32 v117, 31, v116
	v_lshlrev_b64 v[164:165], 11, v[116:117]
	v_lshl_add_u64 v[164:165], s[24:25], 0, v[164:165]
	v_lshl_add_u64 v[164:165], v[142:143], 1, v[164:165]
	v_cvt_pk_bf16_f32 v160, v130, v129
	v_cvt_pk_bf16_f32 v161, v128, v123
	v_cvt_pk_bf16_f32 v162, v122, v121
	v_cvt_pk_bf16_f32 v163, v120, v118
	global_store_dwordx4 v[164:165], v[160:163], off offset:-1792 sc1
	s_mov_b64 s[2:3], 0
.LBB0_854:
	s_andn2_b64 vcc, exec, s[2:3]
	s_cbranch_vccnz .LBB0_856
	v_mul_f32_e32 v117, 0xbfb8aa3b, v130
	v_mul_f32_e32 v119, 0xbfb8aa3b, v129
	v_exp_f32_e32 v117, v117
	v_exp_f32_e32 v119, v119
	v_mul_f32_e32 v159, 0xbfb8aa3b, v122
	v_mul_f32_e32 v160, 0xbfb8aa3b, v121
	v_mul_f32_e32 v161, 0xbfb8aa3b, v120
	v_mul_f32_e32 v162, 0xbfb8aa3b, v118
	v_exp_f32_e32 v159, v159
	v_exp_f32_e32 v160, v160
	v_exp_f32_e32 v161, v161
	v_exp_f32_e32 v162, v162
	v_mul_f32_e32 v131, 0xbfb8aa3b, v128
	v_mul_f32_e32 v141, 0xbfb8aa3b, v123
	v_add_f32_e32 v117, 1.0, v117
	v_add_f32_e32 v119, 1.0, v119
	v_exp_f32_e32 v131, v131
	v_exp_f32_e32 v141, v141
	v_rcp_f32_e32 v117, v117
	v_rcp_f32_e32 v119, v119
	v_add_f32_e32 v159, 1.0, v159
	v_add_f32_e32 v160, 1.0, v160
	v_add_f32_e32 v161, 1.0, v161
	v_add_f32_e32 v162, 1.0, v162
	v_rcp_f32_e32 v159, v159
	v_rcp_f32_e32 v160, v160
	v_rcp_f32_e32 v161, v161
	v_rcp_f32_e32 v162, v162
	v_add_f32_e32 v131, 1.0, v131
	v_add_f32_e32 v141, 1.0, v141
	v_rcp_f32_e32 v131, v131
	v_rcp_f32_e32 v141, v141
	v_cvt_f16_f32_e32 v117, v117
	v_cvt_f16_f32_sdwa v119, v119 dst_sel:WORD_1 dst_unused:UNUSED_PAD src0_sel:DWORD
	v_cvt_f16_f32_e32 v159, v159
	v_cvt_f16_f32_sdwa v163, v160 dst_sel:WORD_1 dst_unused:UNUSED_PAD src0_sel:DWORD
	v_cvt_f16_f32_e32 v164, v161
	v_cvt_f16_f32_sdwa v165, v162 dst_sel:WORD_1 dst_unused:UNUSED_PAD src0_sel:DWORD
	v_readlane_b32 s2, v253, 19
	v_cvt_f16_f32_e32 v131, v131
	v_cvt_f16_f32_sdwa v141, v141 dst_sel:WORD_1 dst_unused:UNUSED_PAD src0_sel:DWORD
	v_or_b32_e32 v160, v119, v117
	v_ashrrev_i32_e32 v117, 31, v116
	v_readlane_b32 s3, v253, 20
	v_or_b32_e32 v162, v163, v159
	v_or_b32_e32 v163, v165, v164
	v_lshl_add_u64 v[164:165], v[146:147], 0, v[116:117]
	v_mov_b64_e32 v[166:167], s[2:3]
	v_mad_u64_u32 v[166:167], s[2:3], v164, s77, v[166:167]
	v_mad_i32_i24 v167, v165, s77, v167
	v_or_b32_e32 v161, v141, v131
	v_lshl_add_u64 v[164:165], v[144:145], 1, v[166:167]
	global_store_dwordx4 v[164:165], v[160:163], off sc1

.LBB0_857:
	s_andn2_b64 vcc, exec, s[2:3]
	s_cbranch_vccnz .LBB0_859
	v_mul_f32_e32 v117, 0xbfb8aa3b, v130
	v_exp_f32_e32 v117, v117
	v_mul_f32_e32 v119, 0xbfb8aa3b, v129
	v_exp_f32_e32 v119, v119
	v_mul_f32_e32 v123, 0xbfb8aa3b, v123
	v_add_f32_e32 v117, 1.0, v117
	v_rcp_f32_e32 v130, v117
	v_mul_f32_e32 v117, 0xbfb8aa3b, v128
	v_add_f32_e32 v119, 1.0, v119
	v_exp_f32_e32 v117, v117
	v_exp_f32_e32 v123, v123
	v_rcp_f32_e32 v128, v119
	v_mul_f32_e32 v119, 0xbfb8aa3b, v122
	v_exp_f32_e32 v119, v119
	v_add_f32_e32 v117, 1.0, v117
	v_rcp_f32_e32 v131, v117
	v_add_f32_e32 v117, 1.0, v123
	v_mul_f32_e32 v121, 0xbfb8aa3b, v121
	v_exp_f32_e32 v121, v121
	v_rcp_f32_e32 v129, v117
	v_add_f32_e32 v117, 1.0, v119
	v_mul_f32_e32 v119, 0xbfb8aa3b, v120
	v_exp_f32_e32 v119, v119
	v_mul_f32_e32 v118, 0xbfb8aa3b, v118
	v_exp_f32_e32 v118, v118
	v_rcp_f32_e32 v122, v117
	v_add_f32_e32 v117, 1.0, v121
	v_rcp_f32_e32 v120, v117
	v_add_f32_e32 v117, 1.0, v119
	v_rcp_f32_e32 v123, v117
	v_add_f32_e32 v117, 1.0, v118
	v_rcp_f32_e32 v121, v117
	s_mov_b32 s2, 0xbf1b4598
	v_pk_mul_f32 v[118:119], v[130:131], s[2:3] op_sel_hi:[1,0]
	v_pk_mul_f32 v[128:129], v[128:129], s[2:3] op_sel_hi:[1,0]
	v_cvt_pk_f16_f32 v117, v118, v119
	v_cvt_pk_f16_f32 v118, v128, v129
	v_pk_mul_f32 v[120:121], v[120:121], s[2:3] op_sel_hi:[1,0]
	v_and_b32_e32 v119, 0xffff0000, v118
	v_lshlrev_b32_e32 v118, 16, v118
	v_pk_mul_f32 v[122:123], v[122:123], s[2:3] op_sel_hi:[1,0]
	v_cvt_pk_f16_f32 v120, v120, v121
	v_or_b32_sdwa v119, v119, v117 dst_sel:DWORD dst_unused:UNUSED_PAD src0_sel:DWORD src1_sel:WORD_1
	v_or_b32_sdwa v118, v118, v117 dst_sel:DWORD dst_unused:UNUSED_PAD src0_sel:DWORD src1_sel:WORD_0
	v_cvt_pk_f16_f32 v117, v122, v123
	v_and_b32_e32 v121, 0xffff0000, v120
	v_lshlrev_b32_e32 v120, 16, v120
	v_or_b32_sdwa v121, v121, v117 dst_sel:DWORD dst_unused:UNUSED_PAD src0_sel:DWORD src1_sel:WORD_1
	v_or_b32_sdwa v120, v120, v117 dst_sel:DWORD dst_unused:UNUSED_PAD src0_sel:DWORD src1_sel:WORD_0
	v_ashrrev_i32_e32 v117, 31, v116
	v_lshl_add_u64 v[116:117], v[126:127], 0, v[116:117]
	v_mov_b64_e32 v[122:123], s[4:5]
	v_mad_u64_u32 v[122:123], s[2:3], v116, s77, v[122:123]
	v_mad_i32_i24 v123, v117, s77, v123
	v_lshl_add_u64 v[116:117], v[124:125], 1, v[122:123]
	global_store_dwordx4 v[116:117], v[118:121], off sc1
.LBB0_859:
	s_nop 1
	v_add_f32_e32 v118, v112, v151
	v_add_f32_e32 v117, v113, v152
	v_add_f32_e32 v116, v114, v153
	v_add_f32_e32 v115, v115, v154
	v_add_f32_e32 v114, v108, v155
	v_add_f32_e32 v113, v109, v156
	v_add_f32_e32 v112, v110, v157
	v_add_f32_e32 v110, v111, v158
	v_or_b32_e32 v108, 32, v140
	s_cmp_lt_i32 s1, 1
	s_mov_b64 s[2:3], -1
	s_cbranch_scc1 .LBB0_865
	s_cmp_lg_u32 s1, 1
	s_cbranch_scc0 .LBB0_862
	v_ashrrev_i32_e32 v109, 31, v108
	v_lshlrev_b64 v[128:129], 11, v[108:109]
	v_lshl_add_u64 v[128:129], s[24:25], 0, v[128:129]
	v_lshl_add_u64 v[128:129], v[142:143], 1, v[128:129]
	v_cvt_pk_bf16_f32 v120, v118, v117
	v_cvt_pk_bf16_f32 v121, v116, v115
	v_cvt_pk_bf16_f32 v122, v114, v113
	v_cvt_pk_bf16_f32 v123, v112, v110
	global_store_dwordx4 v[128:129], v[120:123], off offset:-1792 sc1
	s_mov_b64 s[2:3], 0
.LBB0_862:
	s_andn2_b64 vcc, exec, s[2:3]
	s_cbranch_vccnz .LBB0_864
	v_mul_f32_e32 v109, 0xbfb8aa3b, v118
	v_mul_f32_e32 v111, 0xbfb8aa3b, v117
	v_exp_f32_e32 v109, v109
	v_exp_f32_e32 v111, v111
	v_mul_f32_e32 v119, 0xbfb8aa3b, v116
	v_mul_f32_e32 v120, 0xbfb8aa3b, v115
	v_mul_f32_e32 v121, 0xbfb8aa3b, v114
	v_mul_f32_e32 v122, 0xbfb8aa3b, v113
	v_mul_f32_e32 v123, 0xbfb8aa3b, v112
	v_mul_f32_e32 v128, 0xbfb8aa3b, v110
	v_exp_f32_e32 v119, v119
	v_exp_f32_e32 v120, v120
	v_exp_f32_e32 v121, v121
	v_exp_f32_e32 v122, v122
	v_exp_f32_e32 v123, v123
	v_exp_f32_e32 v128, v128
	v_add_f32_e32 v109, 1.0, v109
	v_add_f32_e32 v111, 1.0, v111
	v_rcp_f32_e32 v109, v109
	v_rcp_f32_e32 v111, v111
	v_add_f32_e32 v119, 1.0, v119
	v_add_f32_e32 v120, 1.0, v120
	v_add_f32_e32 v121, 1.0, v121
	v_add_f32_e32 v122, 1.0, v122
	v_add_f32_e32 v123, 1.0, v123
	v_add_f32_e32 v128, 1.0, v128
	v_rcp_f32_e32 v119, v119
	v_rcp_f32_e32 v120, v120
	v_rcp_f32_e32 v121, v121
	v_rcp_f32_e32 v122, v122
	v_rcp_f32_e32 v123, v123
	v_rcp_f32_e32 v128, v128
	v_cvt_f16_f32_e32 v109, v109
	v_cvt_f16_f32_sdwa v111, v111 dst_sel:WORD_1 dst_unused:UNUSED_PAD src0_sel:DWORD
	v_cvt_f16_f32_e32 v119, v119
	v_cvt_f16_f32_sdwa v129, v120 dst_sel:WORD_1 dst_unused:UNUSED_PAD src0_sel:DWORD
	v_cvt_f16_f32_e32 v130, v121
	v_cvt_f16_f32_sdwa v122, v122 dst_sel:WORD_1 dst_unused:UNUSED_PAD src0_sel:DWORD
	v_cvt_f16_f32_e32 v123, v123
	v_cvt_f16_f32_sdwa v128, v128 dst_sel:WORD_1 dst_unused:UNUSED_PAD src0_sel:DWORD
	v_readlane_b32 s2, v253, 19
	v_or_b32_e32 v120, v111, v109
	v_ashrrev_i32_e32 v109, 31, v108
	v_readlane_b32 s3, v253, 20
	v_or_b32_e32 v121, v129, v119
	v_or_b32_e32 v122, v122, v130
	v_or_b32_e32 v123, v128, v123
	v_lshl_add_u64 v[128:129], v[146:147], 0, v[108:109]
	v_mov_b64_e32 v[130:131], s[2:3]
	v_mad_u64_u32 v[130:131], s[2:3], v128, s77, v[130:131]
	v_mad_i32_i24 v131, v129, s77, v131
	v_lshl_add_u64 v[128:129], v[144:145], 1, v[130:131]
	global_store_dwordx4 v[128:129], v[120:123], off sc1

.LBB0_865:
	s_andn2_b64 vcc, exec, s[2:3]
	s_cbranch_vccnz .LBB0_867
	v_mul_f32_e32 v109, 0xbfb8aa3b, v118
	v_exp_f32_e32 v109, v109
	v_mul_f32_e32 v111, 0xbfb8aa3b, v117
	v_exp_f32_e32 v111, v111
	v_mul_f32_e32 v115, 0xbfb8aa3b, v115
	v_add_f32_e32 v109, 1.0, v109
	v_rcp_f32_e32 v118, v109
	v_mul_f32_e32 v109, 0xbfb8aa3b, v116
	v_add_f32_e32 v111, 1.0, v111
	v_exp_f32_e32 v109, v109
	v_exp_f32_e32 v115, v115
	v_rcp_f32_e32 v116, v111
	v_mul_f32_e32 v111, 0xbfb8aa3b, v114
	v_exp_f32_e32 v111, v111
	v_add_f32_e32 v109, 1.0, v109
	v_rcp_f32_e32 v119, v109
	v_add_f32_e32 v109, 1.0, v115
	v_mul_f32_e32 v113, 0xbfb8aa3b, v113
	v_exp_f32_e32 v113, v113
	v_rcp_f32_e32 v117, v109
	v_add_f32_e32 v109, 1.0, v111
	v_mul_f32_e32 v111, 0xbfb8aa3b, v112
	v_exp_f32_e32 v111, v111
	v_mul_f32_e32 v110, 0xbfb8aa3b, v110
	v_exp_f32_e32 v110, v110
	v_rcp_f32_e32 v114, v109
	v_add_f32_e32 v109, 1.0, v113
	v_rcp_f32_e32 v112, v109
	v_add_f32_e32 v109, 1.0, v111
	v_rcp_f32_e32 v115, v109
	v_add_f32_e32 v109, 1.0, v110
	v_rcp_f32_e32 v113, v109
	s_mov_b32 s2, 0xbf1b4598
	v_pk_mul_f32 v[110:111], v[118:119], s[2:3] op_sel_hi:[1,0]
	v_pk_mul_f32 v[116:117], v[116:117], s[2:3] op_sel_hi:[1,0]
	v_cvt_pk_f16_f32 v109, v110, v111
	v_cvt_pk_f16_f32 v110, v116, v117
	v_pk_mul_f32 v[112:113], v[112:113], s[2:3] op_sel_hi:[1,0]
	v_and_b32_e32 v111, 0xffff0000, v110
	v_lshlrev_b32_e32 v110, 16, v110
	v_pk_mul_f32 v[114:115], v[114:115], s[2:3] op_sel_hi:[1,0]
	v_cvt_pk_f16_f32 v112, v112, v113
	v_or_b32_sdwa v111, v111, v109 dst_sel:DWORD dst_unused:UNUSED_PAD src0_sel:DWORD src1_sel:WORD_1
	v_or_b32_sdwa v110, v110, v109 dst_sel:DWORD dst_unused:UNUSED_PAD src0_sel:DWORD src1_sel:WORD_0
	v_cvt_pk_f16_f32 v109, v114, v115
	v_and_b32_e32 v113, 0xffff0000, v112
	v_lshlrev_b32_e32 v112, 16, v112
	v_or_b32_sdwa v113, v113, v109 dst_sel:DWORD dst_unused:UNUSED_PAD src0_sel:DWORD src1_sel:WORD_1
	v_or_b32_sdwa v112, v112, v109 dst_sel:DWORD dst_unused:UNUSED_PAD src0_sel:DWORD src1_sel:WORD_0
	v_ashrrev_i32_e32 v109, 31, v108
	v_lshl_add_u64 v[108:109], v[126:127], 0, v[108:109]
	v_mov_b64_e32 v[114:115], s[4:5]
	v_mad_u64_u32 v[114:115], s[2:3], v108, s77, v[114:115]
	v_mad_i32_i24 v115, v109, s77, v115
	v_lshl_add_u64 v[108:109], v[124:125], 1, v[114:115]
	global_store_dwordx4 v[108:109], v[110:113], off sc1
.LBB0_867:
	s_nop 1
	v_add_f32_e32 v110, v104, v151
	v_add_f32_e32 v109, v105, v152
	v_add_f32_e32 v108, v106, v153
	v_add_f32_e32 v107, v107, v154
	v_add_f32_e32 v106, v100, v155
	v_add_f32_e32 v105, v101, v156
	v_add_f32_e32 v104, v102, v157
	v_add_f32_e32 v102, v103, v158
	v_or_b32_e32 v100, 48, v140
	s_cmp_lt_i32 s1, 1
	s_mov_b64 s[2:3], -1
	s_cbranch_scc1 .LBB0_873
	s_cmp_lg_u32 s1, 1
	s_cbranch_scc0 .LBB0_870
	v_ashrrev_i32_e32 v101, 31, v100
	v_lshlrev_b64 v[116:117], 11, v[100:101]
	v_lshl_add_u64 v[116:117], s[24:25], 0, v[116:117]
	v_lshl_add_u64 v[116:117], v[142:143], 1, v[116:117]
	v_cvt_pk_bf16_f32 v112, v110, v109
	v_cvt_pk_bf16_f32 v113, v108, v107
	v_cvt_pk_bf16_f32 v114, v106, v105
	v_cvt_pk_bf16_f32 v115, v104, v102
	global_store_dwordx4 v[116:117], v[112:115], off offset:-1792 sc1
	s_mov_b64 s[2:3], 0
.LBB0_870:
	s_andn2_b64 vcc, exec, s[2:3]
	s_cbranch_vccnz .LBB0_872
	v_mul_f32_e32 v101, 0xbfb8aa3b, v110
	v_mul_f32_e32 v103, 0xbfb8aa3b, v109
	v_exp_f32_e32 v101, v101
	v_exp_f32_e32 v103, v103
	v_mul_f32_e32 v111, 0xbfb8aa3b, v108
	v_mul_f32_e32 v112, 0xbfb8aa3b, v107
	v_mul_f32_e32 v113, 0xbfb8aa3b, v106
	v_mul_f32_e32 v114, 0xbfb8aa3b, v105
	v_mul_f32_e32 v115, 0xbfb8aa3b, v104
	v_mul_f32_e32 v116, 0xbfb8aa3b, v102
	v_exp_f32_e32 v111, v111
	v_exp_f32_e32 v112, v112
	v_exp_f32_e32 v113, v113
	v_exp_f32_e32 v114, v114
	v_exp_f32_e32 v115, v115
	v_exp_f32_e32 v116, v116
	v_add_f32_e32 v101, 1.0, v101
	v_add_f32_e32 v103, 1.0, v103
	v_rcp_f32_e32 v101, v101
	v_rcp_f32_e32 v103, v103
	v_add_f32_e32 v111, 1.0, v111
	v_add_f32_e32 v112, 1.0, v112
	v_add_f32_e32 v113, 1.0, v113
	v_add_f32_e32 v114, 1.0, v114
	v_add_f32_e32 v115, 1.0, v115
	v_add_f32_e32 v116, 1.0, v116
	v_rcp_f32_e32 v111, v111
	v_rcp_f32_e32 v112, v112
	v_rcp_f32_e32 v113, v113
	v_rcp_f32_e32 v114, v114
	v_rcp_f32_e32 v115, v115
	v_rcp_f32_e32 v116, v116
	v_cvt_f16_f32_e32 v101, v101
	v_cvt_f16_f32_sdwa v103, v103 dst_sel:WORD_1 dst_unused:UNUSED_PAD src0_sel:DWORD
	v_cvt_f16_f32_e32 v111, v111
	v_cvt_f16_f32_sdwa v117, v112 dst_sel:WORD_1 dst_unused:UNUSED_PAD src0_sel:DWORD
	v_cvt_f16_f32_e32 v118, v113
	v_cvt_f16_f32_sdwa v114, v114 dst_sel:WORD_1 dst_unused:UNUSED_PAD src0_sel:DWORD
	v_cvt_f16_f32_e32 v115, v115
	v_cvt_f16_f32_sdwa v116, v116 dst_sel:WORD_1 dst_unused:UNUSED_PAD src0_sel:DWORD
	v_readlane_b32 s2, v253, 19
	v_or_b32_e32 v112, v103, v101
	v_ashrrev_i32_e32 v101, 31, v100
	v_readlane_b32 s3, v253, 20
	v_or_b32_e32 v113, v117, v111
	v_or_b32_e32 v114, v114, v118
	v_or_b32_e32 v115, v116, v115
	v_lshl_add_u64 v[116:117], v[146:147], 0, v[100:101]
	v_mov_b64_e32 v[118:119], s[2:3]
	v_mad_u64_u32 v[118:119], s[2:3], v116, s77, v[118:119]
	v_mad_i32_i24 v119, v117, s77, v119
	v_lshl_add_u64 v[116:117], v[144:145], 1, v[118:119]
	global_store_dwordx4 v[116:117], v[112:115], off sc1

.LBB0_873:
	s_andn2_b64 vcc, exec, s[2:3]
	s_cbranch_vccnz .LBB0_875
	v_mul_f32_e32 v101, 0xbfb8aa3b, v110
	v_exp_f32_e32 v101, v101
	v_mul_f32_e32 v103, 0xbfb8aa3b, v109
	v_exp_f32_e32 v103, v103
	v_mul_f32_e32 v107, 0xbfb8aa3b, v107
	v_add_f32_e32 v101, 1.0, v101
	v_rcp_f32_e32 v110, v101
	v_mul_f32_e32 v101, 0xbfb8aa3b, v108
	v_add_f32_e32 v103, 1.0, v103
	v_exp_f32_e32 v101, v101
	v_exp_f32_e32 v107, v107
	v_rcp_f32_e32 v108, v103
	v_mul_f32_e32 v103, 0xbfb8aa3b, v106
	v_exp_f32_e32 v103, v103
	v_add_f32_e32 v101, 1.0, v101
	v_rcp_f32_e32 v111, v101
	v_add_f32_e32 v101, 1.0, v107
	v_mul_f32_e32 v105, 0xbfb8aa3b, v105
	v_exp_f32_e32 v105, v105
	v_rcp_f32_e32 v109, v101
	v_add_f32_e32 v101, 1.0, v103
	v_mul_f32_e32 v103, 0xbfb8aa3b, v104
	v_exp_f32_e32 v103, v103
	v_mul_f32_e32 v102, 0xbfb8aa3b, v102
	v_exp_f32_e32 v102, v102
	v_rcp_f32_e32 v106, v101
	v_add_f32_e32 v101, 1.0, v105
	v_rcp_f32_e32 v104, v101
	v_add_f32_e32 v101, 1.0, v103
	v_rcp_f32_e32 v107, v101
	v_add_f32_e32 v101, 1.0, v102
	v_rcp_f32_e32 v105, v101
	s_mov_b32 s2, 0xbf1b4598
	v_pk_mul_f32 v[102:103], v[110:111], s[2:3] op_sel_hi:[1,0]
	v_pk_mul_f32 v[108:109], v[108:109], s[2:3] op_sel_hi:[1,0]
	v_cvt_pk_f16_f32 v101, v102, v103
	v_cvt_pk_f16_f32 v102, v108, v109
	v_pk_mul_f32 v[104:105], v[104:105], s[2:3] op_sel_hi:[1,0]
	v_and_b32_e32 v103, 0xffff0000, v102
	v_lshlrev_b32_e32 v102, 16, v102
	v_pk_mul_f32 v[106:107], v[106:107], s[2:3] op_sel_hi:[1,0]
	v_cvt_pk_f16_f32 v104, v104, v105
	v_or_b32_sdwa v103, v103, v101 dst_sel:DWORD dst_unused:UNUSED_PAD src0_sel:DWORD src1_sel:WORD_1
	v_or_b32_sdwa v102, v102, v101 dst_sel:DWORD dst_unused:UNUSED_PAD src0_sel:DWORD src1_sel:WORD_0
	v_cvt_pk_f16_f32 v101, v106, v107
	v_and_b32_e32 v105, 0xffff0000, v104
	v_lshlrev_b32_e32 v104, 16, v104
	v_or_b32_sdwa v105, v105, v101 dst_sel:DWORD dst_unused:UNUSED_PAD src0_sel:DWORD src1_sel:WORD_1
	v_or_b32_sdwa v104, v104, v101 dst_sel:DWORD dst_unused:UNUSED_PAD src0_sel:DWORD src1_sel:WORD_0
	v_ashrrev_i32_e32 v101, 31, v100
	v_lshl_add_u64 v[100:101], v[126:127], 0, v[100:101]
	v_mov_b64_e32 v[106:107], s[4:5]
	v_mad_u64_u32 v[106:107], s[2:3], v100, s77, v[106:107]
	v_mad_i32_i24 v107, v101, s77, v107
	v_lshl_add_u64 v[100:101], v[124:125], 1, v[106:107]
	global_store_dwordx4 v[100:101], v[102:105], off sc1
.LBB0_875:
	v_add_u32_e32 v100, 0x80, v140
	s_nop 0
	v_add_f32_e32 v104, v96, v151
	v_add_f32_e32 v103, v97, v152
	v_add_f32_e32 v102, v98, v153
	v_add_f32_e32 v98, v99, v154
	v_add_f32_e32 v97, v92, v155
	v_add_f32_e32 v96, v93, v156
	v_add_f32_e32 v93, v94, v157
	v_add_f32_e32 v92, v95, v158
	s_cmp_lt_i32 s1, 1
	s_mov_b64 s[2:3], -1
	s_cbranch_scc1 .LBB0_881
	s_cmp_lg_u32 s1, 1
	s_cbranch_scc0 .LBB0_878
	v_ashrrev_i32_e32 v101, 31, v100
	v_lshlrev_b64 v[94:95], 11, v[100:101]
	v_lshl_add_u64 v[94:95], s[24:25], 0, v[94:95]
	v_lshl_add_u64 v[94:95], v[142:143], 1, v[94:95]
	v_cvt_pk_bf16_f32 v106, v104, v103
	v_cvt_pk_bf16_f32 v107, v102, v98
	v_cvt_pk_bf16_f32 v108, v97, v96
	v_cvt_pk_bf16_f32 v109, v93, v92
	global_store_dwordx4 v[94:95], v[106:109], off offset:-1792 sc1
	s_mov_b64 s[2:3], 0
.LBB0_878:
	s_andn2_b64 vcc, exec, s[2:3]
	s_cbranch_vccnz .LBB0_880
	v_mul_f32_e32 v99, 0xbfb8aa3b, v102
	v_mul_f32_e32 v101, 0xbfb8aa3b, v98
	v_mul_f32_e32 v94, 0xbfb8aa3b, v104
	v_mul_f32_e32 v95, 0xbfb8aa3b, v103
	v_exp_f32_e32 v99, v99
	v_exp_f32_e32 v101, v101
	v_mul_f32_e32 v105, 0xbfb8aa3b, v97
	v_mul_f32_e32 v106, 0xbfb8aa3b, v96
	v_mul_f32_e32 v107, 0xbfb8aa3b, v93
	v_mul_f32_e32 v108, 0xbfb8aa3b, v92
	v_exp_f32_e32 v94, v94
	v_exp_f32_e32 v95, v95
	v_exp_f32_e32 v105, v105
	v_exp_f32_e32 v106, v106
	v_exp_f32_e32 v107, v107
	v_exp_f32_e32 v108, v108
	v_add_f32_e32 v99, 1.0, v99
	v_add_f32_e32 v101, 1.0, v101
	v_add_f32_e32 v94, 1.0, v94
	v_add_f32_e32 v95, 1.0, v95
	v_rcp_f32_e32 v99, v99
	v_rcp_f32_e32 v101, v101
	v_add_f32_e32 v105, 1.0, v105
	v_add_f32_e32 v106, 1.0, v106
	v_add_f32_e32 v107, 1.0, v107
	v_add_f32_e32 v108, 1.0, v108
	v_rcp_f32_e32 v94, v94
	v_rcp_f32_e32 v95, v95
	v_rcp_f32_e32 v105, v105
	v_rcp_f32_e32 v106, v106
	v_rcp_f32_e32 v107, v107
	v_rcp_f32_e32 v108, v108
	v_cvt_f16_f32_e32 v99, v99
	v_cvt_f16_f32_sdwa v101, v101 dst_sel:WORD_1 dst_unused:UNUSED_PAD src0_sel:DWORD
	v_cvt_f16_f32_e32 v94, v94
	v_cvt_f16_f32_sdwa v95, v95 dst_sel:WORD_1 dst_unused:UNUSED_PAD src0_sel:DWORD
	v_cvt_f16_f32_e32 v105, v105
	v_cvt_f16_f32_sdwa v109, v106 dst_sel:WORD_1 dst_unused:UNUSED_PAD src0_sel:DWORD
	v_cvt_f16_f32_e32 v110, v107
	v_cvt_f16_f32_sdwa v111, v108 dst_sel:WORD_1 dst_unused:UNUSED_PAD src0_sel:DWORD
	v_readlane_b32 s2, v253, 19
	v_or_b32_e32 v107, v101, v99
	v_ashrrev_i32_e32 v101, 31, v100
	v_readlane_b32 s3, v253, 20
	v_or_b32_e32 v106, v95, v94
	v_or_b32_e32 v108, v109, v105
	v_or_b32_e32 v109, v111, v110
	v_lshl_add_u64 v[94:95], v[146:147], 0, v[100:101]
	v_mov_b64_e32 v[110:111], s[2:3]
	v_mad_u64_u32 v[110:111], s[2:3], v94, s77, v[110:111]
	v_mad_i32_i24 v111, v95, s77, v111
	v_lshl_add_u64 v[94:95], v[144:145], 1, v[110:111]
	global_store_dwordx4 v[94:95], v[106:109], off sc1

.LBB0_881:
	s_andn2_b64 vcc, exec, s[2:3]
	s_cbranch_vccnz .LBB0_883
	v_mul_f32_e32 v95, 0xbfb8aa3b, v103
	v_exp_f32_e32 v95, v95
	v_mul_f32_e32 v99, 0xbfb8aa3b, v102
	v_mul_f32_e32 v98, 0xbfb8aa3b, v98
	v_mul_f32_e32 v94, 0xbfb8aa3b, v104
	v_exp_f32_e32 v99, v99
	v_exp_f32_e32 v101, v98
	v_exp_f32_e32 v94, v94
	v_add_f32_e32 v95, 1.0, v95
	v_mul_f32_e32 v97, 0xbfb8aa3b, v97
	v_mul_f32_e32 v96, 0xbfb8aa3b, v96
	v_mul_f32_e32 v93, 0xbfb8aa3b, v93
	v_mul_f32_e32 v92, 0xbfb8aa3b, v92
	v_rcp_f32_e32 v98, v95
	v_add_f32_e32 v95, 1.0, v99
	v_add_f32_e32 v99, 1.0, v101
	v_exp_f32_e32 v97, v97
	v_exp_f32_e32 v101, v96
	v_exp_f32_e32 v93, v93
	v_exp_f32_e32 v92, v92
	v_add_f32_e32 v94, 1.0, v94
	v_rcp_f32_e32 v94, v94
	v_rcp_f32_e32 v95, v95
	v_rcp_f32_e32 v99, v99
	v_add_f32_e32 v96, 1.0, v97
	v_add_f32_e32 v97, 1.0, v101
	v_add_f32_e32 v93, 1.0, v93
	v_add_f32_e32 v92, 1.0, v92
	v_rcp_f32_e32 v96, v96
	v_rcp_f32_e32 v102, v97
	v_rcp_f32_e32 v97, v93
	v_rcp_f32_e32 v103, v92
	s_mov_b32 s2, 0xbf1b4598
	v_pk_mul_f32 v[92:93], v[94:95], s[2:3] op_sel_hi:[1,0]
	v_pk_mul_f32 v[94:95], v[98:99], s[2:3] op_sel_hi:[1,0]
	v_cvt_pk_f16_f32 v92, v92, v93
	v_cvt_pk_f16_f32 v93, v94, v95
	v_and_b32_e32 v94, 0xffff0000, v93
	v_lshlrev_b32_e32 v95, 16, v93
	v_or_b32_sdwa v93, v94, v92 dst_sel:DWORD dst_unused:UNUSED_PAD src0_sel:DWORD src1_sel:WORD_1
	v_or_b32_sdwa v92, v95, v92 dst_sel:DWORD dst_unused:UNUSED_PAD src0_sel:DWORD src1_sel:WORD_0
	v_pk_mul_f32 v[94:95], v[96:97], s[2:3] op_sel_hi:[1,0]
	v_pk_mul_f32 v[96:97], v[102:103], s[2:3] op_sel_hi:[1,0]
	v_cvt_pk_f16_f32 v94, v94, v95
	v_cvt_pk_f16_f32 v95, v96, v97
	v_and_b32_e32 v96, 0xffff0000, v95
	v_lshlrev_b32_e32 v97, 16, v95
	v_ashrrev_i32_e32 v101, 31, v100
	v_or_b32_sdwa v95, v96, v94 dst_sel:DWORD dst_unused:UNUSED_PAD src0_sel:DWORD src1_sel:WORD_1
	v_or_b32_sdwa v94, v97, v94 dst_sel:DWORD dst_unused:UNUSED_PAD src0_sel:DWORD src1_sel:WORD_0
	v_lshl_add_u64 v[96:97], v[126:127], 0, v[100:101]
	v_mov_b64_e32 v[98:99], s[4:5]
	v_mad_u64_u32 v[98:99], s[2:3], v96, s77, v[98:99]
	v_mad_i32_i24 v99, v97, s77, v99
	v_lshl_add_u64 v[96:97], v[124:125], 1, v[98:99]
	global_store_dwordx4 v[96:97], v[92:95], off sc1
.LBB0_883:
	s_nop 1
	v_add_f32_e32 v94, v88, v151
	v_add_f32_e32 v93, v89, v152
	v_add_f32_e32 v92, v90, v153
	v_add_f32_e32 v91, v91, v154
	v_add_f32_e32 v90, v84, v155
	v_add_f32_e32 v89, v85, v156
	v_add_f32_e32 v88, v86, v157
	v_add_f32_e32 v86, v87, v158
	v_add_u32_e32 v84, 0x90, v140
	s_cmp_lt_i32 s1, 1
	s_mov_b64 s[2:3], -1
	s_cbranch_scc1 .LBB0_889
	s_cmp_lg_u32 s1, 1
	s_cbranch_scc0 .LBB0_886
	v_ashrrev_i32_e32 v85, 31, v84
	v_lshlrev_b64 v[100:101], 11, v[84:85]
	v_lshl_add_u64 v[100:101], s[24:25], 0, v[100:101]
	v_lshl_add_u64 v[100:101], v[142:143], 1, v[100:101]
	v_cvt_pk_bf16_f32 v96, v94, v93
	v_cvt_pk_bf16_f32 v97, v92, v91
	v_cvt_pk_bf16_f32 v98, v90, v89
	v_cvt_pk_bf16_f32 v99, v88, v86
	global_store_dwordx4 v[100:101], v[96:99], off offset:-1792 sc1
	s_mov_b64 s[2:3], 0
.LBB0_886:
	s_andn2_b64 vcc, exec, s[2:3]
	s_cbranch_vccnz .LBB0_888
	v_mul_f32_e32 v85, 0xbfb8aa3b, v94
	v_mul_f32_e32 v87, 0xbfb8aa3b, v93
	v_exp_f32_e32 v85, v85
	v_exp_f32_e32 v87, v87
	v_mul_f32_e32 v95, 0xbfb8aa3b, v92
	v_mul_f32_e32 v96, 0xbfb8aa3b, v91
	v_mul_f32_e32 v97, 0xbfb8aa3b, v90
	v_mul_f32_e32 v98, 0xbfb8aa3b, v89
	v_mul_f32_e32 v99, 0xbfb8aa3b, v88
	v_mul_f32_e32 v100, 0xbfb8aa3b, v86
	v_exp_f32_e32 v95, v95
	v_exp_f32_e32 v96, v96
	v_exp_f32_e32 v97, v97
	v_exp_f32_e32 v98, v98
	v_exp_f32_e32 v99, v99
	v_exp_f32_e32 v100, v100
	v_add_f32_e32 v85, 1.0, v85
	v_add_f32_e32 v87, 1.0, v87
	v_rcp_f32_e32 v85, v85
	v_rcp_f32_e32 v87, v87
	v_add_f32_e32 v95, 1.0, v95
	v_add_f32_e32 v96, 1.0, v96
	v_add_f32_e32 v97, 1.0, v97
	v_add_f32_e32 v98, 1.0, v98
	v_add_f32_e32 v99, 1.0, v99
	v_add_f32_e32 v100, 1.0, v100
	v_rcp_f32_e32 v95, v95
	v_rcp_f32_e32 v96, v96
	v_rcp_f32_e32 v97, v97
	v_rcp_f32_e32 v98, v98
	v_rcp_f32_e32 v99, v99
	v_rcp_f32_e32 v100, v100
	v_cvt_f16_f32_e32 v85, v85
	v_cvt_f16_f32_sdwa v87, v87 dst_sel:WORD_1 dst_unused:UNUSED_PAD src0_sel:DWORD
	v_cvt_f16_f32_e32 v95, v95
	v_cvt_f16_f32_sdwa v101, v96 dst_sel:WORD_1 dst_unused:UNUSED_PAD src0_sel:DWORD
	v_cvt_f16_f32_e32 v102, v97
	v_cvt_f16_f32_sdwa v98, v98 dst_sel:WORD_1 dst_unused:UNUSED_PAD src0_sel:DWORD
	v_cvt_f16_f32_e32 v99, v99
	v_cvt_f16_f32_sdwa v100, v100 dst_sel:WORD_1 dst_unused:UNUSED_PAD src0_sel:DWORD
	v_readlane_b32 s2, v253, 19
	v_or_b32_e32 v96, v87, v85
	v_ashrrev_i32_e32 v85, 31, v84
	v_readlane_b32 s3, v253, 20
	v_or_b32_e32 v97, v101, v95
	v_or_b32_e32 v98, v98, v102
	v_or_b32_e32 v99, v100, v99
	v_lshl_add_u64 v[100:101], v[146:147], 0, v[84:85]
	v_mov_b64_e32 v[102:103], s[2:3]
	v_mad_u64_u32 v[102:103], s[2:3], v100, s77, v[102:103]
	v_mad_i32_i24 v103, v101, s77, v103
	v_lshl_add_u64 v[100:101], v[144:145], 1, v[102:103]
	global_store_dwordx4 v[100:101], v[96:99], off sc1

.LBB0_889:
	s_andn2_b64 vcc, exec, s[2:3]
	s_cbranch_vccnz .LBB0_891
	v_mul_f32_e32 v85, 0xbfb8aa3b, v94
	v_exp_f32_e32 v85, v85
	v_mul_f32_e32 v87, 0xbfb8aa3b, v93
	v_exp_f32_e32 v87, v87
	v_mul_f32_e32 v91, 0xbfb8aa3b, v91
	v_add_f32_e32 v85, 1.0, v85
	v_rcp_f32_e32 v94, v85
	v_mul_f32_e32 v85, 0xbfb8aa3b, v92
	v_add_f32_e32 v87, 1.0, v87
	v_exp_f32_e32 v85, v85
	v_exp_f32_e32 v91, v91
	v_rcp_f32_e32 v92, v87
	v_mul_f32_e32 v87, 0xbfb8aa3b, v90
	v_exp_f32_e32 v87, v87
	v_add_f32_e32 v85, 1.0, v85
	v_rcp_f32_e32 v95, v85
	v_add_f32_e32 v85, 1.0, v91
	v_mul_f32_e32 v89, 0xbfb8aa3b, v89
	v_exp_f32_e32 v89, v89
	v_rcp_f32_e32 v93, v85
	v_add_f32_e32 v85, 1.0, v87
	v_mul_f32_e32 v87, 0xbfb8aa3b, v88
	v_exp_f32_e32 v87, v87
	v_mul_f32_e32 v86, 0xbfb8aa3b, v86
	v_exp_f32_e32 v86, v86
	v_rcp_f32_e32 v90, v85
	v_add_f32_e32 v85, 1.0, v89
	v_rcp_f32_e32 v88, v85
	v_add_f32_e32 v85, 1.0, v87
	v_rcp_f32_e32 v91, v85
	v_add_f32_e32 v85, 1.0, v86
	v_rcp_f32_e32 v89, v85
	s_mov_b32 s2, 0xbf1b4598
	v_pk_mul_f32 v[86:87], v[94:95], s[2:3] op_sel_hi:[1,0]
	v_pk_mul_f32 v[92:93], v[92:93], s[2:3] op_sel_hi:[1,0]
	v_cvt_pk_f16_f32 v85, v86, v87
	v_cvt_pk_f16_f32 v86, v92, v93
	v_pk_mul_f32 v[88:89], v[88:89], s[2:3] op_sel_hi:[1,0]
	v_and_b32_e32 v87, 0xffff0000, v86
	v_lshlrev_b32_e32 v86, 16, v86
	v_pk_mul_f32 v[90:91], v[90:91], s[2:3] op_sel_hi:[1,0]
	v_cvt_pk_f16_f32 v88, v88, v89
	v_or_b32_sdwa v87, v87, v85 dst_sel:DWORD dst_unused:UNUSED_PAD src0_sel:DWORD src1_sel:WORD_1
	v_or_b32_sdwa v86, v86, v85 dst_sel:DWORD dst_unused:UNUSED_PAD src0_sel:DWORD src1_sel:WORD_0
	v_cvt_pk_f16_f32 v85, v90, v91
	v_and_b32_e32 v89, 0xffff0000, v88
	v_lshlrev_b32_e32 v88, 16, v88
	v_or_b32_sdwa v89, v89, v85 dst_sel:DWORD dst_unused:UNUSED_PAD src0_sel:DWORD src1_sel:WORD_1
	v_or_b32_sdwa v88, v88, v85 dst_sel:DWORD dst_unused:UNUSED_PAD src0_sel:DWORD src1_sel:WORD_0
	v_ashrrev_i32_e32 v85, 31, v84
	v_lshl_add_u64 v[84:85], v[126:127], 0, v[84:85]
	v_mov_b64_e32 v[90:91], s[4:5]
	v_mad_u64_u32 v[90:91], s[2:3], v84, s77, v[90:91]
	v_mad_i32_i24 v91, v85, s77, v91
	v_lshl_add_u64 v[84:85], v[124:125], 1, v[90:91]
	global_store_dwordx4 v[84:85], v[86:89], off sc1
.LBB0_891:
	s_nop 1
	v_add_f32_e32 v86, v80, v151
	v_add_f32_e32 v85, v81, v152
	v_add_f32_e32 v84, v82, v153
	v_add_f32_e32 v83, v83, v154
	v_add_f32_e32 v82, v76, v155
	v_add_f32_e32 v81, v77, v156
	v_add_f32_e32 v80, v78, v157
	v_add_f32_e32 v78, v79, v158
	v_add_u32_e32 v76, 0xa0, v140
	s_cmp_lt_i32 s1, 1
	s_mov_b64 s[2:3], -1
	s_cbranch_scc1 .LBB0_897
	s_cmp_lg_u32 s1, 1
	s_cbranch_scc0 .LBB0_894
	v_ashrrev_i32_e32 v77, 31, v76
	v_lshlrev_b64 v[92:93], 11, v[76:77]
	v_lshl_add_u64 v[92:93], s[24:25], 0, v[92:93]
	v_lshl_add_u64 v[92:93], v[142:143], 1, v[92:93]
	v_cvt_pk_bf16_f32 v88, v86, v85
	v_cvt_pk_bf16_f32 v89, v84, v83
	v_cvt_pk_bf16_f32 v90, v82, v81
	v_cvt_pk_bf16_f32 v91, v80, v78
	global_store_dwordx4 v[92:93], v[88:91], off offset:-1792 sc1
	s_mov_b64 s[2:3], 0
.LBB0_894:
	s_andn2_b64 vcc, exec, s[2:3]
	s_cbranch_vccnz .LBB0_896
	v_mul_f32_e32 v77, 0xbfb8aa3b, v86
	v_mul_f32_e32 v79, 0xbfb8aa3b, v85
	v_exp_f32_e32 v77, v77
	v_exp_f32_e32 v79, v79
	v_mul_f32_e32 v87, 0xbfb8aa3b, v84
	v_mul_f32_e32 v88, 0xbfb8aa3b, v83
	v_mul_f32_e32 v89, 0xbfb8aa3b, v82
	v_mul_f32_e32 v90, 0xbfb8aa3b, v81
	v_mul_f32_e32 v91, 0xbfb8aa3b, v80
	v_mul_f32_e32 v92, 0xbfb8aa3b, v78
	v_exp_f32_e32 v87, v87
	v_exp_f32_e32 v88, v88
	v_exp_f32_e32 v89, v89
	v_exp_f32_e32 v90, v90
	v_exp_f32_e32 v91, v91
	v_exp_f32_e32 v92, v92
	v_add_f32_e32 v77, 1.0, v77
	v_add_f32_e32 v79, 1.0, v79
	v_rcp_f32_e32 v77, v77
	v_rcp_f32_e32 v79, v79
	v_add_f32_e32 v87, 1.0, v87
	v_add_f32_e32 v88, 1.0, v88
	v_add_f32_e32 v89, 1.0, v89
	v_add_f32_e32 v90, 1.0, v90
	v_add_f32_e32 v91, 1.0, v91
	v_add_f32_e32 v92, 1.0, v92
	v_rcp_f32_e32 v87, v87
	v_rcp_f32_e32 v88, v88
	v_rcp_f32_e32 v89, v89
	v_rcp_f32_e32 v90, v90
	v_rcp_f32_e32 v91, v91
	v_rcp_f32_e32 v92, v92
	v_cvt_f16_f32_e32 v77, v77
	v_cvt_f16_f32_sdwa v79, v79 dst_sel:WORD_1 dst_unused:UNUSED_PAD src0_sel:DWORD
	v_cvt_f16_f32_e32 v87, v87
	v_cvt_f16_f32_sdwa v93, v88 dst_sel:WORD_1 dst_unused:UNUSED_PAD src0_sel:DWORD
	v_cvt_f16_f32_e32 v94, v89
	v_cvt_f16_f32_sdwa v90, v90 dst_sel:WORD_1 dst_unused:UNUSED_PAD src0_sel:DWORD
	v_cvt_f16_f32_e32 v91, v91
	v_cvt_f16_f32_sdwa v92, v92 dst_sel:WORD_1 dst_unused:UNUSED_PAD src0_sel:DWORD
	v_readlane_b32 s2, v253, 19
	v_or_b32_e32 v88, v79, v77
	v_ashrrev_i32_e32 v77, 31, v76
	v_readlane_b32 s3, v253, 20
	v_or_b32_e32 v89, v93, v87
	v_or_b32_e32 v90, v90, v94
	v_or_b32_e32 v91, v92, v91
	v_lshl_add_u64 v[92:93], v[146:147], 0, v[76:77]
	v_mov_b64_e32 v[94:95], s[2:3]
	v_mad_u64_u32 v[94:95], s[2:3], v92, s77, v[94:95]
	v_mad_i32_i24 v95, v93, s77, v95
	v_lshl_add_u64 v[92:93], v[144:145], 1, v[94:95]
	global_store_dwordx4 v[92:93], v[88:91], off sc1

.LBB0_897:
	s_andn2_b64 vcc, exec, s[2:3]
	s_cbranch_vccnz .LBB0_899
	v_mul_f32_e32 v77, 0xbfb8aa3b, v86
	v_exp_f32_e32 v77, v77
	v_mul_f32_e32 v79, 0xbfb8aa3b, v85
	v_exp_f32_e32 v79, v79
	v_mul_f32_e32 v83, 0xbfb8aa3b, v83
	v_add_f32_e32 v77, 1.0, v77
	v_rcp_f32_e32 v86, v77
	v_mul_f32_e32 v77, 0xbfb8aa3b, v84
	v_add_f32_e32 v79, 1.0, v79
	v_exp_f32_e32 v77, v77
	v_exp_f32_e32 v83, v83
	v_rcp_f32_e32 v84, v79
	v_mul_f32_e32 v79, 0xbfb8aa3b, v82
	v_exp_f32_e32 v79, v79
	v_add_f32_e32 v77, 1.0, v77
	v_rcp_f32_e32 v87, v77
	v_add_f32_e32 v77, 1.0, v83
	v_mul_f32_e32 v81, 0xbfb8aa3b, v81
	v_exp_f32_e32 v81, v81
	v_rcp_f32_e32 v85, v77
	v_add_f32_e32 v77, 1.0, v79
	v_mul_f32_e32 v79, 0xbfb8aa3b, v80
	v_exp_f32_e32 v79, v79
	v_mul_f32_e32 v78, 0xbfb8aa3b, v78
	v_exp_f32_e32 v78, v78
	v_rcp_f32_e32 v82, v77
	v_add_f32_e32 v77, 1.0, v81
	v_rcp_f32_e32 v80, v77
	v_add_f32_e32 v77, 1.0, v79
	v_rcp_f32_e32 v83, v77
	v_add_f32_e32 v77, 1.0, v78
	v_rcp_f32_e32 v81, v77
	s_mov_b32 s2, 0xbf1b4598
	v_pk_mul_f32 v[78:79], v[86:87], s[2:3] op_sel_hi:[1,0]
	v_pk_mul_f32 v[84:85], v[84:85], s[2:3] op_sel_hi:[1,0]
	v_cvt_pk_f16_f32 v77, v78, v79
	v_cvt_pk_f16_f32 v78, v84, v85
	v_pk_mul_f32 v[80:81], v[80:81], s[2:3] op_sel_hi:[1,0]
	v_and_b32_e32 v79, 0xffff0000, v78
	v_lshlrev_b32_e32 v78, 16, v78
	v_pk_mul_f32 v[82:83], v[82:83], s[2:3] op_sel_hi:[1,0]
	v_cvt_pk_f16_f32 v80, v80, v81
	v_or_b32_sdwa v79, v79, v77 dst_sel:DWORD dst_unused:UNUSED_PAD src0_sel:DWORD src1_sel:WORD_1
	v_or_b32_sdwa v78, v78, v77 dst_sel:DWORD dst_unused:UNUSED_PAD src0_sel:DWORD src1_sel:WORD_0
	v_cvt_pk_f16_f32 v77, v82, v83
	v_and_b32_e32 v81, 0xffff0000, v80
	v_lshlrev_b32_e32 v80, 16, v80
	v_or_b32_sdwa v81, v81, v77 dst_sel:DWORD dst_unused:UNUSED_PAD src0_sel:DWORD src1_sel:WORD_1
	v_or_b32_sdwa v80, v80, v77 dst_sel:DWORD dst_unused:UNUSED_PAD src0_sel:DWORD src1_sel:WORD_0
	v_ashrrev_i32_e32 v77, 31, v76
	v_lshl_add_u64 v[76:77], v[126:127], 0, v[76:77]
	v_mov_b64_e32 v[82:83], s[4:5]
	v_mad_u64_u32 v[82:83], s[2:3], v76, s77, v[82:83]
	v_mad_i32_i24 v83, v77, s77, v83
	v_lshl_add_u64 v[76:77], v[124:125], 1, v[82:83]
	global_store_dwordx4 v[76:77], v[78:81], off sc1
.LBB0_899:
	s_nop 1
	v_add_f32_e32 v78, v72, v151
	v_add_f32_e32 v77, v73, v152
	v_add_f32_e32 v76, v74, v153
	v_add_f32_e32 v75, v75, v154
	v_add_f32_e32 v74, v68, v155
	v_add_f32_e32 v73, v69, v156
	v_add_f32_e32 v72, v70, v157
	v_add_f32_e32 v70, v71, v158
	v_add_u32_e32 v68, 0xb0, v140
	s_cmp_lt_i32 s1, 1
	s_mov_b64 s[2:3], -1
	s_cbranch_scc1 .LBB0_905
	s_cmp_lg_u32 s1, 1
	s_cbranch_scc0 .LBB0_902
	v_ashrrev_i32_e32 v69, 31, v68
	v_lshlrev_b64 v[84:85], 11, v[68:69]
	v_lshl_add_u64 v[84:85], s[24:25], 0, v[84:85]
	v_lshl_add_u64 v[84:85], v[142:143], 1, v[84:85]
	v_cvt_pk_bf16_f32 v80, v78, v77
	v_cvt_pk_bf16_f32 v81, v76, v75
	v_cvt_pk_bf16_f32 v82, v74, v73
	v_cvt_pk_bf16_f32 v83, v72, v70
	global_store_dwordx4 v[84:85], v[80:83], off offset:-1792 sc1
	s_mov_b64 s[2:3], 0
.LBB0_902:
	s_andn2_b64 vcc, exec, s[2:3]
	s_cbranch_vccnz .LBB0_904
	v_mul_f32_e32 v69, 0xbfb8aa3b, v78
	v_mul_f32_e32 v71, 0xbfb8aa3b, v77
	v_exp_f32_e32 v69, v69
	v_exp_f32_e32 v71, v71
	v_mul_f32_e32 v79, 0xbfb8aa3b, v76
	v_mul_f32_e32 v80, 0xbfb8aa3b, v75
	v_mul_f32_e32 v81, 0xbfb8aa3b, v74
	v_mul_f32_e32 v82, 0xbfb8aa3b, v73
	v_mul_f32_e32 v83, 0xbfb8aa3b, v72
	v_mul_f32_e32 v84, 0xbfb8aa3b, v70
	v_exp_f32_e32 v79, v79
	v_exp_f32_e32 v80, v80
	v_exp_f32_e32 v81, v81
	v_exp_f32_e32 v82, v82
	v_exp_f32_e32 v83, v83
	v_exp_f32_e32 v84, v84
	v_add_f32_e32 v69, 1.0, v69
	v_add_f32_e32 v71, 1.0, v71
	v_rcp_f32_e32 v69, v69
	v_rcp_f32_e32 v71, v71
	v_add_f32_e32 v79, 1.0, v79
	v_add_f32_e32 v80, 1.0, v80
	v_add_f32_e32 v81, 1.0, v81
	v_add_f32_e32 v82, 1.0, v82
	v_add_f32_e32 v83, 1.0, v83
	v_add_f32_e32 v84, 1.0, v84
	v_rcp_f32_e32 v79, v79
	v_rcp_f32_e32 v80, v80
	v_rcp_f32_e32 v81, v81
	v_rcp_f32_e32 v82, v82
	v_rcp_f32_e32 v83, v83
	v_rcp_f32_e32 v84, v84
	v_cvt_f16_f32_e32 v69, v69
	v_cvt_f16_f32_sdwa v71, v71 dst_sel:WORD_1 dst_unused:UNUSED_PAD src0_sel:DWORD
	v_cvt_f16_f32_e32 v79, v79
	v_cvt_f16_f32_sdwa v85, v80 dst_sel:WORD_1 dst_unused:UNUSED_PAD src0_sel:DWORD
	v_cvt_f16_f32_e32 v86, v81
	v_cvt_f16_f32_sdwa v82, v82 dst_sel:WORD_1 dst_unused:UNUSED_PAD src0_sel:DWORD
	v_cvt_f16_f32_e32 v83, v83
	v_cvt_f16_f32_sdwa v84, v84 dst_sel:WORD_1 dst_unused:UNUSED_PAD src0_sel:DWORD
	v_readlane_b32 s2, v253, 19
	v_or_b32_e32 v80, v71, v69
	v_ashrrev_i32_e32 v69, 31, v68
	v_readlane_b32 s3, v253, 20
	v_or_b32_e32 v81, v85, v79
	v_or_b32_e32 v82, v82, v86
	v_or_b32_e32 v83, v84, v83
	v_lshl_add_u64 v[84:85], v[146:147], 0, v[68:69]
	v_mov_b64_e32 v[86:87], s[2:3]
	v_mad_u64_u32 v[86:87], s[2:3], v84, s77, v[86:87]
	v_mad_i32_i24 v87, v85, s77, v87
	v_lshl_add_u64 v[84:85], v[144:145], 1, v[86:87]
	global_store_dwordx4 v[84:85], v[80:83], off sc1

.LBB0_905:
	s_andn2_b64 vcc, exec, s[2:3]
	s_cbranch_vccnz .LBB0_907
	v_mul_f32_e32 v69, 0xbfb8aa3b, v78
	v_exp_f32_e32 v69, v69
	v_mul_f32_e32 v71, 0xbfb8aa3b, v77
	v_exp_f32_e32 v71, v71
	v_mul_f32_e32 v75, 0xbfb8aa3b, v75
	v_add_f32_e32 v69, 1.0, v69
	v_rcp_f32_e32 v78, v69
	v_mul_f32_e32 v69, 0xbfb8aa3b, v76
	v_add_f32_e32 v71, 1.0, v71
	v_exp_f32_e32 v69, v69
	v_exp_f32_e32 v75, v75
	v_rcp_f32_e32 v76, v71
	v_mul_f32_e32 v71, 0xbfb8aa3b, v74
	v_exp_f32_e32 v71, v71
	v_add_f32_e32 v69, 1.0, v69
	v_rcp_f32_e32 v79, v69
	v_add_f32_e32 v69, 1.0, v75
	v_mul_f32_e32 v73, 0xbfb8aa3b, v73
	v_exp_f32_e32 v73, v73
	v_rcp_f32_e32 v77, v69
	v_add_f32_e32 v69, 1.0, v71
	v_mul_f32_e32 v71, 0xbfb8aa3b, v72
	v_exp_f32_e32 v71, v71
	v_mul_f32_e32 v70, 0xbfb8aa3b, v70
	v_exp_f32_e32 v70, v70
	v_rcp_f32_e32 v74, v69
	v_add_f32_e32 v69, 1.0, v73
	v_rcp_f32_e32 v72, v69
	v_add_f32_e32 v69, 1.0, v71
	v_rcp_f32_e32 v75, v69
	v_add_f32_e32 v69, 1.0, v70
	v_rcp_f32_e32 v73, v69
	s_mov_b32 s2, 0xbf1b4598
	v_pk_mul_f32 v[70:71], v[78:79], s[2:3] op_sel_hi:[1,0]
	v_pk_mul_f32 v[76:77], v[76:77], s[2:3] op_sel_hi:[1,0]
	v_cvt_pk_f16_f32 v69, v70, v71
	v_cvt_pk_f16_f32 v70, v76, v77
	v_pk_mul_f32 v[72:73], v[72:73], s[2:3] op_sel_hi:[1,0]
	v_and_b32_e32 v71, 0xffff0000, v70
	v_lshlrev_b32_e32 v70, 16, v70
	v_pk_mul_f32 v[74:75], v[74:75], s[2:3] op_sel_hi:[1,0]
	v_cvt_pk_f16_f32 v72, v72, v73
	v_or_b32_sdwa v71, v71, v69 dst_sel:DWORD dst_unused:UNUSED_PAD src0_sel:DWORD src1_sel:WORD_1
	v_or_b32_sdwa v70, v70, v69 dst_sel:DWORD dst_unused:UNUSED_PAD src0_sel:DWORD src1_sel:WORD_0
	v_cvt_pk_f16_f32 v69, v74, v75
	v_and_b32_e32 v73, 0xffff0000, v72
	v_lshlrev_b32_e32 v72, 16, v72
	v_or_b32_sdwa v73, v73, v69 dst_sel:DWORD dst_unused:UNUSED_PAD src0_sel:DWORD src1_sel:WORD_1
	v_or_b32_sdwa v72, v72, v69 dst_sel:DWORD dst_unused:UNUSED_PAD src0_sel:DWORD src1_sel:WORD_0
	v_ashrrev_i32_e32 v69, 31, v68
	v_lshl_add_u64 v[68:69], v[126:127], 0, v[68:69]
	v_mov_b64_e32 v[74:75], s[4:5]
	v_mad_u64_u32 v[74:75], s[2:3], v68, s77, v[74:75]
	v_mad_i32_i24 v75, v69, s77, v75
	v_lshl_add_u64 v[68:69], v[124:125], 1, v[74:75]
	global_store_dwordx4 v[68:69], v[70:73], off sc1

.LBB0_960:
	v_mul_hi_i32 v70, v72, s85
	v_lshrrev_b32_e32 v71, 31, v70
	v_ashrrev_i32_e32 v70, 6, v70
	v_add_u32_e32 v82, v70, v71
	v_mul_i32_i24_e32 v70, 0x180, v82
	v_sub_u32_e32 v70, v72, v70
	v_ashrrev_i32_e32 v83, 31, v82
	v_lshlrev_b64 v[72:73], 15, v[82:83]
	v_ashrrev_i32_e32 v71, 31, v70
	s_waitcnt vmcnt(0)
	v_add_f32_e32 v85, v64, v74
	v_add_f32_e32 v84, v65, v75
	v_add_f32_e32 v83, v66, v76
	v_add_f32_e32 v82, v67, v77
	v_add_f32_e32 v67, v60, v78
	v_add_f32_e32 v66, v61, v79
	v_add_f32_e32 v65, v62, v80
	v_add_f32_e32 v64, v63, v81
	s_cmp_lt_i32 s0, 1
	s_mov_b64 s[2:3], -1
	s_cbranch_scc1 .LBB0_966
	s_cmp_lg_u32 s0, 1
	s_cbranch_scc0 .LBB0_963
	v_ashrrev_i32_e32 v141, 31, v140
	v_lshlrev_b64 v[86:87], 11, v[140:141]
	v_lshl_add_u64 v[86:87], s[24:25], 0, v[86:87]
	v_lshl_add_u64 v[86:87], v[68:69], 1, v[86:87]
	v_cvt_pk_bf16_f32 v60, v85, v84
	v_cvt_pk_bf16_f32 v61, v83, v82
	v_cvt_pk_bf16_f32 v62, v67, v66
	v_cvt_pk_bf16_f32 v63, v65, v64
	global_store_dwordx4 v[86:87], v[60:63], off offset:-1792 sc1
	s_mov_b64 s[2:3], 0
.LBB0_963:
	s_andn2_b64 vcc, exec, s[2:3]
	s_cbranch_vccnz .LBB0_965
	v_mul_f32_e32 v60, 0xbfb8aa3b, v85
	v_mul_f32_e32 v61, 0xbfb8aa3b, v84
	v_mul_f32_e32 v62, 0xbfb8aa3b, v83
	v_mul_f32_e32 v63, 0xbfb8aa3b, v82
	v_mul_f32_e32 v86, 0xbfb8aa3b, v67
	v_mul_f32_e32 v87, 0xbfb8aa3b, v66
	v_mul_f32_e32 v88, 0xbfb8aa3b, v65
	v_mul_f32_e32 v89, 0xbfb8aa3b, v64
	v_exp_f32_e32 v60, v60
	v_exp_f32_e32 v61, v61
	v_exp_f32_e32 v62, v62
	v_exp_f32_e32 v63, v63
	v_exp_f32_e32 v86, v86
	v_exp_f32_e32 v87, v87
	v_exp_f32_e32 v88, v88
	v_exp_f32_e32 v89, v89
	v_add_f32_e32 v60, 1.0, v60
	v_add_f32_e32 v61, 1.0, v61
	v_add_f32_e32 v62, 1.0, v62
	v_add_f32_e32 v63, 1.0, v63
	v_add_f32_e32 v86, 1.0, v86
	v_add_f32_e32 v87, 1.0, v87
	v_add_f32_e32 v88, 1.0, v88
	v_add_f32_e32 v89, 1.0, v89
	v_rcp_f32_e32 v60, v60
	v_rcp_f32_e32 v61, v61
	v_rcp_f32_e32 v62, v62
	v_rcp_f32_e32 v63, v63
	v_rcp_f32_e32 v86, v86
	v_rcp_f32_e32 v87, v87
	v_rcp_f32_e32 v88, v88
	v_rcp_f32_e32 v89, v89
	v_cvt_f16_f32_e32 v60, v60
	v_cvt_f16_f32_sdwa v61, v61 dst_sel:WORD_1 dst_unused:UNUSED_PAD src0_sel:DWORD
	v_cvt_f16_f32_e32 v62, v62
	v_cvt_f16_f32_sdwa v63, v63 dst_sel:WORD_1 dst_unused:UNUSED_PAD src0_sel:DWORD
	v_cvt_f16_f32_e32 v86, v86
	v_cvt_f16_f32_sdwa v87, v87 dst_sel:WORD_1 dst_unused:UNUSED_PAD src0_sel:DWORD
	v_cvt_f16_f32_e32 v88, v88
	v_cvt_f16_f32_sdwa v89, v89 dst_sel:WORD_1 dst_unused:UNUSED_PAD src0_sel:DWORD
	v_readlane_b32 s2, v253, 19
	v_ashrrev_i32_e32 v141, 31, v140
	v_readlane_b32 s3, v253, 20
	v_or_b32_e32 v60, v61, v60
	v_or_b32_e32 v61, v63, v62
	v_or_b32_e32 v62, v87, v86
	v_or_b32_e32 v63, v89, v88
	v_lshl_add_u64 v[86:87], v[72:73], 0, v[140:141]
	v_mov_b64_e32 v[88:89], s[2:3]
	v_mad_u64_u32 v[88:89], s[2:3], v86, s77, v[88:89]
	v_mad_i32_i24 v89, v87, s77, v89
	v_lshl_add_u64 v[86:87], v[70:71], 1, v[88:89]
	global_store_dwordx4 v[86:87], v[60:63], off sc1

.LBB0_966:
	s_nop 0
	v_mul_hi_i32 v60, v68, s85
	v_lshrrev_b32_e32 v61, 31, v60
	v_ashrrev_i32_e32 v60, 6, v60
	v_add_u32_e32 v62, v60, v61
	v_mul_i32_i24_e32 v60, 0x180, v62
	v_sub_u32_e32 v60, v68, v60
	v_ashrrev_i32_e32 v63, 31, v62
	v_lshlrev_b64 v[62:63], 15, v[62:63]
	s_andn2_b64 vcc, exec, s[2:3]
	v_ashrrev_i32_e32 v61, 31, v60
	s_cbranch_vccnz .LBB0_968
	v_mul_f32_e32 v84, 0xbfb8aa3b, v84
	v_mul_f32_e32 v85, 0xbfb8aa3b, v85
	v_exp_f32_e32 v84, v84
	v_mul_f32_e32 v83, 0xbfb8aa3b, v83
	v_exp_f32_e32 v85, v85
	v_exp_f32_e32 v83, v83
	v_mul_f32_e32 v82, 0xbfb8aa3b, v82
	v_exp_f32_e32 v87, v82
	v_add_f32_e32 v86, 1.0, v84
	v_mul_f32_e32 v67, 0xbfb8aa3b, v67
	v_mul_f32_e32 v66, 0xbfb8aa3b, v66
	v_mul_f32_e32 v65, 0xbfb8aa3b, v65
	v_mul_f32_e32 v64, 0xbfb8aa3b, v64
	v_add_f32_e32 v85, 1.0, v85
	v_rcp_f32_e32 v82, v86
	v_add_f32_e32 v83, 1.0, v83
	v_exp_f32_e32 v67, v67
	v_exp_f32_e32 v86, v66
	v_exp_f32_e32 v65, v65
	v_exp_f32_e32 v64, v64
	v_rcp_f32_e32 v84, v85
	v_rcp_f32_e32 v85, v83
	v_add_f32_e32 v83, 1.0, v87
	v_rcp_f32_e32 v83, v83
	v_add_f32_e32 v66, 1.0, v67
	v_add_f32_e32 v67, 1.0, v86
	v_add_f32_e32 v65, 1.0, v65
	v_add_f32_e32 v64, 1.0, v64
	v_rcp_f32_e32 v66, v66
	v_rcp_f32_e32 v86, v67
	v_rcp_f32_e32 v67, v65
	v_rcp_f32_e32 v87, v64
	s_mov_b32 s2, 0xbf1b4598
	v_pk_mul_f32 v[64:65], v[84:85], s[2:3] op_sel_hi:[1,0]
	v_pk_mul_f32 v[82:83], v[82:83], s[2:3] op_sel_hi:[1,0]
	v_cvt_pk_f16_f32 v64, v64, v65
	v_cvt_pk_f16_f32 v65, v82, v83
	v_and_b32_e32 v82, 0xffff0000, v65
	v_lshlrev_b32_e32 v83, 16, v65
	v_or_b32_sdwa v65, v82, v64 dst_sel:DWORD dst_unused:UNUSED_PAD src0_sel:DWORD src1_sel:WORD_1
	v_or_b32_sdwa v64, v83, v64 dst_sel:DWORD dst_unused:UNUSED_PAD src0_sel:DWORD src1_sel:WORD_0
	v_pk_mul_f32 v[66:67], v[66:67], s[2:3] op_sel_hi:[1,0]
	v_pk_mul_f32 v[82:83], v[86:87], s[2:3] op_sel_hi:[1,0]
	v_cvt_pk_f16_f32 v66, v66, v67
	v_cvt_pk_f16_f32 v67, v82, v83
	v_and_b32_e32 v82, 0xffff0000, v67
	v_lshlrev_b32_e32 v83, 16, v67
	v_ashrrev_i32_e32 v141, 31, v140
	v_or_b32_sdwa v67, v82, v66 dst_sel:DWORD dst_unused:UNUSED_PAD src0_sel:DWORD src1_sel:WORD_1
	v_or_b32_sdwa v66, v83, v66 dst_sel:DWORD dst_unused:UNUSED_PAD src0_sel:DWORD src1_sel:WORD_0
	v_lshl_add_u64 v[82:83], v[62:63], 0, v[140:141]
	v_mov_b64_e32 v[84:85], s[4:5]
	v_mad_u64_u32 v[84:85], s[2:3], v82, s77, v[84:85]
	v_mad_i32_i24 v85, v83, s77, v85
	v_lshl_add_u64 v[82:83], v[60:61], 1, v[84:85]
	global_store_dwordx4 v[82:83], v[64:67], off sc1
.LBB0_968:
	s_nop 1
	v_add_f32_e32 v66, v56, v74
	v_add_f32_e32 v65, v57, v75
	v_add_f32_e32 v64, v58, v76
	v_add_f32_e32 v59, v59, v77
	v_add_f32_e32 v58, v52, v78
	v_add_f32_e32 v57, v53, v79
	v_add_f32_e32 v56, v54, v80
	v_add_f32_e32 v54, v55, v81
	v_or_b32_e32 v52, 16, v140
	s_cmp_lt_i32 s0, 1
	s_mov_b64 s[2:3], -1
	s_cbranch_scc1 .LBB0_974
	s_cmp_lg_u32 s0, 1
	s_cbranch_scc0 .LBB0_971
	v_ashrrev_i32_e32 v53, 31, v52
	v_lshlrev_b64 v[86:87], 11, v[52:53]
	v_lshl_add_u64 v[86:87], s[24:25], 0, v[86:87]
	v_lshl_add_u64 v[86:87], v[68:69], 1, v[86:87]
	v_cvt_pk_bf16_f32 v82, v66, v65
	v_cvt_pk_bf16_f32 v83, v64, v59
	v_cvt_pk_bf16_f32 v84, v58, v57
	v_cvt_pk_bf16_f32 v85, v56, v54
	global_store_dwordx4 v[86:87], v[82:85], off offset:-1792 sc1
	s_mov_b64 s[2:3], 0
.LBB0_971:
	s_andn2_b64 vcc, exec, s[2:3]
	s_cbranch_vccnz .LBB0_973
	v_mul_f32_e32 v53, 0xbfb8aa3b, v66
	v_mul_f32_e32 v55, 0xbfb8aa3b, v65
	v_exp_f32_e32 v53, v53
	v_exp_f32_e32 v55, v55
	v_mul_f32_e32 v67, 0xbfb8aa3b, v64
	v_mul_f32_e32 v82, 0xbfb8aa3b, v59
	v_mul_f32_e32 v83, 0xbfb8aa3b, v58
	v_mul_f32_e32 v84, 0xbfb8aa3b, v57
	v_mul_f32_e32 v85, 0xbfb8aa3b, v56
	v_mul_f32_e32 v86, 0xbfb8aa3b, v54
	v_exp_f32_e32 v67, v67
	v_exp_f32_e32 v82, v82
	v_exp_f32_e32 v83, v83
	v_exp_f32_e32 v84, v84
	v_exp_f32_e32 v85, v85
	v_exp_f32_e32 v86, v86
	v_add_f32_e32 v53, 1.0, v53
	v_add_f32_e32 v55, 1.0, v55
	v_rcp_f32_e32 v53, v53
	v_rcp_f32_e32 v55, v55
	v_add_f32_e32 v67, 1.0, v67
	v_add_f32_e32 v82, 1.0, v82
	v_add_f32_e32 v83, 1.0, v83
	v_add_f32_e32 v84, 1.0, v84
	v_add_f32_e32 v85, 1.0, v85
	v_add_f32_e32 v86, 1.0, v86
	v_rcp_f32_e32 v67, v67
	v_rcp_f32_e32 v82, v82
	v_rcp_f32_e32 v83, v83
	v_rcp_f32_e32 v84, v84
	v_rcp_f32_e32 v85, v85
	v_rcp_f32_e32 v86, v86
	v_cvt_f16_f32_e32 v53, v53
	v_cvt_f16_f32_sdwa v55, v55 dst_sel:WORD_1 dst_unused:UNUSED_PAD src0_sel:DWORD
	v_cvt_f16_f32_e32 v67, v67
	v_cvt_f16_f32_sdwa v87, v82 dst_sel:WORD_1 dst_unused:UNUSED_PAD src0_sel:DWORD
	v_cvt_f16_f32_e32 v88, v83
	v_cvt_f16_f32_sdwa v84, v84 dst_sel:WORD_1 dst_unused:UNUSED_PAD src0_sel:DWORD
	v_cvt_f16_f32_e32 v85, v85
	v_cvt_f16_f32_sdwa v86, v86 dst_sel:WORD_1 dst_unused:UNUSED_PAD src0_sel:DWORD
	v_readlane_b32 s2, v253, 19
	v_or_b32_e32 v82, v55, v53
	v_ashrrev_i32_e32 v53, 31, v52
	v_readlane_b32 s3, v253, 20
	v_or_b32_e32 v83, v87, v67
	v_or_b32_e32 v84, v84, v88
	v_or_b32_e32 v85, v86, v85
	v_lshl_add_u64 v[86:87], v[72:73], 0, v[52:53]
	v_mov_b64_e32 v[88:89], s[2:3]
	v_mad_u64_u32 v[88:89], s[2:3], v86, s77, v[88:89]
	v_mad_i32_i24 v89, v87, s77, v89
	v_lshl_add_u64 v[86:87], v[70:71], 1, v[88:89]
	global_store_dwordx4 v[86:87], v[82:85], off sc1

.LBB0_974:
	s_andn2_b64 vcc, exec, s[2:3]
	s_cbranch_vccnz .LBB0_976
	v_mul_f32_e32 v53, 0xbfb8aa3b, v66
	v_exp_f32_e32 v53, v53
	v_mul_f32_e32 v55, 0xbfb8aa3b, v65
	v_exp_f32_e32 v55, v55
	v_mul_f32_e32 v59, 0xbfb8aa3b, v59
	v_add_f32_e32 v53, 1.0, v53
	v_rcp_f32_e32 v66, v53
	v_mul_f32_e32 v53, 0xbfb8aa3b, v64
	v_add_f32_e32 v55, 1.0, v55
	v_exp_f32_e32 v53, v53
	v_exp_f32_e32 v59, v59
	v_rcp_f32_e32 v64, v55
	v_mul_f32_e32 v55, 0xbfb8aa3b, v58
	v_exp_f32_e32 v55, v55
	v_add_f32_e32 v53, 1.0, v53
	v_rcp_f32_e32 v67, v53
	v_add_f32_e32 v53, 1.0, v59
	v_mul_f32_e32 v57, 0xbfb8aa3b, v57
	v_exp_f32_e32 v57, v57
	v_rcp_f32_e32 v65, v53
	v_add_f32_e32 v53, 1.0, v55
	v_mul_f32_e32 v55, 0xbfb8aa3b, v56
	v_exp_f32_e32 v55, v55
	v_mul_f32_e32 v54, 0xbfb8aa3b, v54
	v_exp_f32_e32 v54, v54
	v_rcp_f32_e32 v58, v53
	v_add_f32_e32 v53, 1.0, v57
	v_rcp_f32_e32 v56, v53
	v_add_f32_e32 v53, 1.0, v55
	v_rcp_f32_e32 v59, v53
	v_add_f32_e32 v53, 1.0, v54
	v_rcp_f32_e32 v57, v53
	s_mov_b32 s2, 0xbf1b4598
	v_pk_mul_f32 v[54:55], v[66:67], s[2:3] op_sel_hi:[1,0]
	v_pk_mul_f32 v[64:65], v[64:65], s[2:3] op_sel_hi:[1,0]
	v_cvt_pk_f16_f32 v53, v54, v55
	v_cvt_pk_f16_f32 v54, v64, v65
	v_pk_mul_f32 v[56:57], v[56:57], s[2:3] op_sel_hi:[1,0]
	v_and_b32_e32 v55, 0xffff0000, v54
	v_lshlrev_b32_e32 v54, 16, v54
	v_pk_mul_f32 v[58:59], v[58:59], s[2:3] op_sel_hi:[1,0]
	v_cvt_pk_f16_f32 v56, v56, v57
	v_or_b32_sdwa v55, v55, v53 dst_sel:DWORD dst_unused:UNUSED_PAD src0_sel:DWORD src1_sel:WORD_1
	v_or_b32_sdwa v54, v54, v53 dst_sel:DWORD dst_unused:UNUSED_PAD src0_sel:DWORD src1_sel:WORD_0
	v_cvt_pk_f16_f32 v53, v58, v59
	v_and_b32_e32 v57, 0xffff0000, v56
	v_lshlrev_b32_e32 v56, 16, v56
	v_or_b32_sdwa v57, v57, v53 dst_sel:DWORD dst_unused:UNUSED_PAD src0_sel:DWORD src1_sel:WORD_1
	v_or_b32_sdwa v56, v56, v53 dst_sel:DWORD dst_unused:UNUSED_PAD src0_sel:DWORD src1_sel:WORD_0
	v_ashrrev_i32_e32 v53, 31, v52
	v_lshl_add_u64 v[52:53], v[62:63], 0, v[52:53]
	v_mov_b64_e32 v[58:59], s[4:5]
	v_mad_u64_u32 v[58:59], s[2:3], v52, s77, v[58:59]
	v_mad_i32_i24 v59, v53, s77, v59
	v_lshl_add_u64 v[52:53], v[60:61], 1, v[58:59]
	global_store_dwordx4 v[52:53], v[54:57], off sc1
.LBB0_976:
	s_nop 1
	v_add_f32_e32 v54, v44, v74
	v_add_f32_e32 v53, v45, v75
	v_add_f32_e32 v52, v46, v76
	v_add_f32_e32 v47, v47, v77
	v_add_f32_e32 v46, v40, v78
	v_add_f32_e32 v45, v41, v79
	v_add_f32_e32 v44, v42, v80
	v_add_f32_e32 v42, v43, v81
	v_or_b32_e32 v40, 32, v140
	s_cmp_lt_i32 s0, 1
	s_mov_b64 s[2:3], -1
	s_cbranch_scc1 .LBB0_982
	s_cmp_lg_u32 s0, 1
	s_cbranch_scc0 .LBB0_979
	v_ashrrev_i32_e32 v41, 31, v40
	v_lshlrev_b64 v[64:65], 11, v[40:41]
	v_lshl_add_u64 v[64:65], s[24:25], 0, v[64:65]
	v_lshl_add_u64 v[64:65], v[68:69], 1, v[64:65]
	v_cvt_pk_bf16_f32 v56, v54, v53
	v_cvt_pk_bf16_f32 v57, v52, v47
	v_cvt_pk_bf16_f32 v58, v46, v45
	v_cvt_pk_bf16_f32 v59, v44, v42
	global_store_dwordx4 v[64:65], v[56:59], off offset:-1792 sc1
	s_mov_b64 s[2:3], 0
.LBB0_979:
	s_andn2_b64 vcc, exec, s[2:3]
	s_cbranch_vccnz .LBB0_981
	v_mul_f32_e32 v41, 0xbfb8aa3b, v54
	v_mul_f32_e32 v43, 0xbfb8aa3b, v53
	v_exp_f32_e32 v41, v41
	v_exp_f32_e32 v43, v43
	v_mul_f32_e32 v55, 0xbfb8aa3b, v52
	v_mul_f32_e32 v56, 0xbfb8aa3b, v47
	v_mul_f32_e32 v57, 0xbfb8aa3b, v46
	v_mul_f32_e32 v58, 0xbfb8aa3b, v45
	v_mul_f32_e32 v59, 0xbfb8aa3b, v44
	v_mul_f32_e32 v64, 0xbfb8aa3b, v42
	v_exp_f32_e32 v55, v55
	v_exp_f32_e32 v56, v56
	v_exp_f32_e32 v57, v57
	v_exp_f32_e32 v58, v58
	v_exp_f32_e32 v59, v59
	v_exp_f32_e32 v64, v64
	v_add_f32_e32 v41, 1.0, v41
	v_add_f32_e32 v43, 1.0, v43
	v_rcp_f32_e32 v41, v41
	v_rcp_f32_e32 v43, v43
	v_add_f32_e32 v55, 1.0, v55
	v_add_f32_e32 v56, 1.0, v56
	v_add_f32_e32 v57, 1.0, v57
	v_add_f32_e32 v58, 1.0, v58
	v_add_f32_e32 v59, 1.0, v59
	v_add_f32_e32 v64, 1.0, v64
	v_rcp_f32_e32 v55, v55
	v_rcp_f32_e32 v56, v56
	v_rcp_f32_e32 v57, v57
	v_rcp_f32_e32 v58, v58
	v_rcp_f32_e32 v59, v59
	v_rcp_f32_e32 v64, v64
	v_cvt_f16_f32_e32 v41, v41
	v_cvt_f16_f32_sdwa v43, v43 dst_sel:WORD_1 dst_unused:UNUSED_PAD src0_sel:DWORD
	v_cvt_f16_f32_e32 v55, v55
	v_cvt_f16_f32_sdwa v65, v56 dst_sel:WORD_1 dst_unused:UNUSED_PAD src0_sel:DWORD
	v_cvt_f16_f32_e32 v66, v57
	v_cvt_f16_f32_sdwa v58, v58 dst_sel:WORD_1 dst_unused:UNUSED_PAD src0_sel:DWORD
	v_cvt_f16_f32_e32 v59, v59
	v_cvt_f16_f32_sdwa v64, v64 dst_sel:WORD_1 dst_unused:UNUSED_PAD src0_sel:DWORD
	v_readlane_b32 s2, v253, 19
	v_or_b32_e32 v56, v43, v41
	v_ashrrev_i32_e32 v41, 31, v40
	v_readlane_b32 s3, v253, 20
	v_or_b32_e32 v57, v65, v55
	v_or_b32_e32 v58, v58, v66
	v_or_b32_e32 v59, v64, v59
	v_lshl_add_u64 v[64:65], v[72:73], 0, v[40:41]
	v_mov_b64_e32 v[66:67], s[2:3]
	v_mad_u64_u32 v[66:67], s[2:3], v64, s77, v[66:67]
	v_mad_i32_i24 v67, v65, s77, v67
	v_lshl_add_u64 v[64:65], v[70:71], 1, v[66:67]
	global_store_dwordx4 v[64:65], v[56:59], off sc1

.LBB0_982:
	s_andn2_b64 vcc, exec, s[2:3]
	s_cbranch_vccnz .LBB0_984
	v_mul_f32_e32 v41, 0xbfb8aa3b, v54
	v_exp_f32_e32 v41, v41
	v_mul_f32_e32 v43, 0xbfb8aa3b, v53
	v_exp_f32_e32 v43, v43
	v_mul_f32_e32 v47, 0xbfb8aa3b, v47
	v_add_f32_e32 v41, 1.0, v41
	v_rcp_f32_e32 v54, v41
	v_mul_f32_e32 v41, 0xbfb8aa3b, v52
	v_add_f32_e32 v43, 1.0, v43
	v_exp_f32_e32 v41, v41
	v_exp_f32_e32 v47, v47
	v_rcp_f32_e32 v52, v43
	v_mul_f32_e32 v43, 0xbfb8aa3b, v46
	v_exp_f32_e32 v43, v43
	v_add_f32_e32 v41, 1.0, v41
	v_rcp_f32_e32 v55, v41
	v_add_f32_e32 v41, 1.0, v47
	v_mul_f32_e32 v45, 0xbfb8aa3b, v45
	v_exp_f32_e32 v45, v45
	v_rcp_f32_e32 v53, v41
	v_add_f32_e32 v41, 1.0, v43
	v_mul_f32_e32 v43, 0xbfb8aa3b, v44
	v_exp_f32_e32 v43, v43
	v_mul_f32_e32 v42, 0xbfb8aa3b, v42
	v_exp_f32_e32 v42, v42
	v_rcp_f32_e32 v46, v41
	v_add_f32_e32 v41, 1.0, v45
	v_rcp_f32_e32 v44, v41
	v_add_f32_e32 v41, 1.0, v43
	v_rcp_f32_e32 v47, v41
	v_add_f32_e32 v41, 1.0, v42
	v_rcp_f32_e32 v45, v41
	s_mov_b32 s2, 0xbf1b4598
	v_pk_mul_f32 v[42:43], v[54:55], s[2:3] op_sel_hi:[1,0]
	v_pk_mul_f32 v[52:53], v[52:53], s[2:3] op_sel_hi:[1,0]
	v_cvt_pk_f16_f32 v41, v42, v43
	v_cvt_pk_f16_f32 v42, v52, v53
	v_pk_mul_f32 v[44:45], v[44:45], s[2:3] op_sel_hi:[1,0]
	v_and_b32_e32 v43, 0xffff0000, v42
	v_lshlrev_b32_e32 v42, 16, v42
	v_pk_mul_f32 v[46:47], v[46:47], s[2:3] op_sel_hi:[1,0]
	v_cvt_pk_f16_f32 v44, v44, v45
	v_or_b32_sdwa v43, v43, v41 dst_sel:DWORD dst_unused:UNUSED_PAD src0_sel:DWORD src1_sel:WORD_1
	v_or_b32_sdwa v42, v42, v41 dst_sel:DWORD dst_unused:UNUSED_PAD src0_sel:DWORD src1_sel:WORD_0
	v_cvt_pk_f16_f32 v41, v46, v47
	v_and_b32_e32 v45, 0xffff0000, v44
	v_lshlrev_b32_e32 v44, 16, v44
	v_or_b32_sdwa v45, v45, v41 dst_sel:DWORD dst_unused:UNUSED_PAD src0_sel:DWORD src1_sel:WORD_1
	v_or_b32_sdwa v44, v44, v41 dst_sel:DWORD dst_unused:UNUSED_PAD src0_sel:DWORD src1_sel:WORD_0
	v_ashrrev_i32_e32 v41, 31, v40
	v_lshl_add_u64 v[40:41], v[62:63], 0, v[40:41]
	v_mov_b64_e32 v[46:47], s[4:5]
	v_mad_u64_u32 v[46:47], s[2:3], v40, s77, v[46:47]
	v_mad_i32_i24 v47, v41, s77, v47
	v_lshl_add_u64 v[40:41], v[60:61], 1, v[46:47]
	global_store_dwordx4 v[40:41], v[42:45], off sc1
.LBB0_984:
	s_nop 1
	v_add_f32_e32 v42, v36, v74
	v_add_f32_e32 v41, v37, v75
	v_add_f32_e32 v40, v38, v76
	v_add_f32_e32 v39, v39, v77
	v_add_f32_e32 v38, v32, v78
	v_add_f32_e32 v37, v33, v79
	v_add_f32_e32 v36, v34, v80
	v_add_f32_e32 v34, v35, v81
	v_or_b32_e32 v32, 48, v140
	s_cmp_lt_i32 s0, 1
	s_mov_b64 s[2:3], -1
	s_cbranch_scc1 .LBB0_990
	s_cmp_lg_u32 s0, 1
	s_cbranch_scc0 .LBB0_987
	v_ashrrev_i32_e32 v33, 31, v32
	v_lshlrev_b64 v[52:53], 11, v[32:33]
	v_lshl_add_u64 v[52:53], s[24:25], 0, v[52:53]
	v_lshl_add_u64 v[52:53], v[68:69], 1, v[52:53]
	v_cvt_pk_bf16_f32 v44, v42, v41
	v_cvt_pk_bf16_f32 v45, v40, v39
	v_cvt_pk_bf16_f32 v46, v38, v37
	v_cvt_pk_bf16_f32 v47, v36, v34
	global_store_dwordx4 v[52:53], v[44:47], off offset:-1792 sc1
	s_mov_b64 s[2:3], 0
.LBB0_987:
	s_andn2_b64 vcc, exec, s[2:3]
	s_cbranch_vccnz .LBB0_989
	v_mul_f32_e32 v33, 0xbfb8aa3b, v42
	v_mul_f32_e32 v35, 0xbfb8aa3b, v41
	v_exp_f32_e32 v33, v33
	v_exp_f32_e32 v35, v35
	v_mul_f32_e32 v43, 0xbfb8aa3b, v40
	v_mul_f32_e32 v44, 0xbfb8aa3b, v39
	v_mul_f32_e32 v45, 0xbfb8aa3b, v38
	v_mul_f32_e32 v46, 0xbfb8aa3b, v37
	v_mul_f32_e32 v47, 0xbfb8aa3b, v36
	v_mul_f32_e32 v52, 0xbfb8aa3b, v34
	v_exp_f32_e32 v43, v43
	v_exp_f32_e32 v44, v44
	v_exp_f32_e32 v45, v45
	v_exp_f32_e32 v46, v46
	v_exp_f32_e32 v47, v47
	v_exp_f32_e32 v52, v52
	v_add_f32_e32 v33, 1.0, v33
	v_add_f32_e32 v35, 1.0, v35
	v_rcp_f32_e32 v33, v33
	v_rcp_f32_e32 v35, v35
	v_add_f32_e32 v43, 1.0, v43
	v_add_f32_e32 v44, 1.0, v44
	v_add_f32_e32 v45, 1.0, v45
	v_add_f32_e32 v46, 1.0, v46
	v_add_f32_e32 v47, 1.0, v47
	v_add_f32_e32 v52, 1.0, v52
	v_rcp_f32_e32 v43, v43
	v_rcp_f32_e32 v44, v44
	v_rcp_f32_e32 v45, v45
	v_rcp_f32_e32 v46, v46
	v_rcp_f32_e32 v47, v47
	v_rcp_f32_e32 v52, v52
	v_cvt_f16_f32_e32 v33, v33
	v_cvt_f16_f32_sdwa v35, v35 dst_sel:WORD_1 dst_unused:UNUSED_PAD src0_sel:DWORD
	v_cvt_f16_f32_e32 v43, v43
	v_cvt_f16_f32_sdwa v53, v44 dst_sel:WORD_1 dst_unused:UNUSED_PAD src0_sel:DWORD
	v_cvt_f16_f32_e32 v54, v45
	v_cvt_f16_f32_sdwa v46, v46 dst_sel:WORD_1 dst_unused:UNUSED_PAD src0_sel:DWORD
	v_cvt_f16_f32_e32 v47, v47
	v_cvt_f16_f32_sdwa v52, v52 dst_sel:WORD_1 dst_unused:UNUSED_PAD src0_sel:DWORD
	v_readlane_b32 s2, v253, 19
	v_or_b32_e32 v44, v35, v33
	v_ashrrev_i32_e32 v33, 31, v32
	v_readlane_b32 s3, v253, 20
	v_or_b32_e32 v45, v53, v43
	v_or_b32_e32 v46, v46, v54
	v_or_b32_e32 v47, v52, v47
	v_lshl_add_u64 v[52:53], v[72:73], 0, v[32:33]
	v_mov_b64_e32 v[54:55], s[2:3]
	v_mad_u64_u32 v[54:55], s[2:3], v52, s77, v[54:55]
	v_mad_i32_i24 v55, v53, s77, v55
	v_lshl_add_u64 v[52:53], v[70:71], 1, v[54:55]
	global_store_dwordx4 v[52:53], v[44:47], off sc1

.LBB0_990:
	s_andn2_b64 vcc, exec, s[2:3]
	s_cbranch_vccnz .LBB0_992
	v_mul_f32_e32 v33, 0xbfb8aa3b, v42
	v_exp_f32_e32 v33, v33
	v_mul_f32_e32 v35, 0xbfb8aa3b, v41
	v_exp_f32_e32 v35, v35
	v_mul_f32_e32 v39, 0xbfb8aa3b, v39
	v_add_f32_e32 v33, 1.0, v33
	v_rcp_f32_e32 v42, v33
	v_mul_f32_e32 v33, 0xbfb8aa3b, v40
	v_add_f32_e32 v35, 1.0, v35
	v_exp_f32_e32 v33, v33
	v_exp_f32_e32 v39, v39
	v_rcp_f32_e32 v40, v35
	v_mul_f32_e32 v35, 0xbfb8aa3b, v38
	v_exp_f32_e32 v35, v35
	v_add_f32_e32 v33, 1.0, v33
	v_rcp_f32_e32 v43, v33
	v_add_f32_e32 v33, 1.0, v39
	v_mul_f32_e32 v37, 0xbfb8aa3b, v37
	v_exp_f32_e32 v37, v37
	v_rcp_f32_e32 v41, v33
	v_add_f32_e32 v33, 1.0, v35
	v_mul_f32_e32 v35, 0xbfb8aa3b, v36
	v_exp_f32_e32 v35, v35
	v_mul_f32_e32 v34, 0xbfb8aa3b, v34
	v_exp_f32_e32 v34, v34
	v_rcp_f32_e32 v38, v33
	v_add_f32_e32 v33, 1.0, v37
	v_rcp_f32_e32 v36, v33
	v_add_f32_e32 v33, 1.0, v35
	v_rcp_f32_e32 v39, v33
	v_add_f32_e32 v33, 1.0, v34
	v_rcp_f32_e32 v37, v33
	s_mov_b32 s2, 0xbf1b4598
	v_pk_mul_f32 v[34:35], v[42:43], s[2:3] op_sel_hi:[1,0]
	v_pk_mul_f32 v[40:41], v[40:41], s[2:3] op_sel_hi:[1,0]
	v_cvt_pk_f16_f32 v33, v34, v35
	v_cvt_pk_f16_f32 v34, v40, v41
	v_pk_mul_f32 v[36:37], v[36:37], s[2:3] op_sel_hi:[1,0]
	v_and_b32_e32 v35, 0xffff0000, v34
	v_lshlrev_b32_e32 v34, 16, v34
	v_pk_mul_f32 v[38:39], v[38:39], s[2:3] op_sel_hi:[1,0]
	v_cvt_pk_f16_f32 v36, v36, v37
	v_or_b32_sdwa v35, v35, v33 dst_sel:DWORD dst_unused:UNUSED_PAD src0_sel:DWORD src1_sel:WORD_1
	v_or_b32_sdwa v34, v34, v33 dst_sel:DWORD dst_unused:UNUSED_PAD src0_sel:DWORD src1_sel:WORD_0
	v_cvt_pk_f16_f32 v33, v38, v39
	v_and_b32_e32 v37, 0xffff0000, v36
	v_lshlrev_b32_e32 v36, 16, v36
	v_or_b32_sdwa v37, v37, v33 dst_sel:DWORD dst_unused:UNUSED_PAD src0_sel:DWORD src1_sel:WORD_1
	v_or_b32_sdwa v36, v36, v33 dst_sel:DWORD dst_unused:UNUSED_PAD src0_sel:DWORD src1_sel:WORD_0
	v_ashrrev_i32_e32 v33, 31, v32
	v_lshl_add_u64 v[32:33], v[62:63], 0, v[32:33]
	v_mov_b64_e32 v[38:39], s[4:5]
	v_mad_u64_u32 v[38:39], s[2:3], v32, s77, v[38:39]
	v_mad_i32_i24 v39, v33, s77, v39
	v_lshl_add_u64 v[32:33], v[60:61], 1, v[38:39]
	global_store_dwordx4 v[32:33], v[34:37], off sc1
.LBB0_992:
	v_add_u32_e32 v32, 0x80, v140
	s_nop 0
	v_add_f32_e32 v36, v28, v74
	v_add_f32_e32 v35, v29, v75
	v_add_f32_e32 v34, v30, v76
	v_add_f32_e32 v30, v31, v77
	v_add_f32_e32 v29, v24, v78
	v_add_f32_e32 v28, v25, v79
	v_add_f32_e32 v25, v26, v80
	v_add_f32_e32 v24, v27, v81
	s_cmp_lt_i32 s0, 1
	s_mov_b64 s[2:3], -1
	s_cbranch_scc1 .LBB0_998
	s_cmp_lg_u32 s0, 1
	s_cbranch_scc0 .LBB0_995
	v_ashrrev_i32_e32 v33, 31, v32
	v_lshlrev_b64 v[26:27], 11, v[32:33]
	v_lshl_add_u64 v[26:27], s[24:25], 0, v[26:27]
	v_lshl_add_u64 v[26:27], v[68:69], 1, v[26:27]
	v_cvt_pk_bf16_f32 v38, v36, v35
	v_cvt_pk_bf16_f32 v39, v34, v30
	v_cvt_pk_bf16_f32 v40, v29, v28
	v_cvt_pk_bf16_f32 v41, v25, v24
	global_store_dwordx4 v[26:27], v[38:41], off offset:-1792 sc1
	s_mov_b64 s[2:3], 0
.LBB0_995:
	s_andn2_b64 vcc, exec, s[2:3]
	s_cbranch_vccnz .LBB0_997
	v_mul_f32_e32 v31, 0xbfb8aa3b, v34
	v_mul_f32_e32 v33, 0xbfb8aa3b, v30
	v_mul_f32_e32 v26, 0xbfb8aa3b, v36
	v_mul_f32_e32 v27, 0xbfb8aa3b, v35
	v_exp_f32_e32 v31, v31
	v_exp_f32_e32 v33, v33
	v_mul_f32_e32 v37, 0xbfb8aa3b, v29
	v_mul_f32_e32 v38, 0xbfb8aa3b, v28
	v_mul_f32_e32 v39, 0xbfb8aa3b, v25
	v_mul_f32_e32 v40, 0xbfb8aa3b, v24
	v_exp_f32_e32 v26, v26
	v_exp_f32_e32 v27, v27
	v_exp_f32_e32 v37, v37
	v_exp_f32_e32 v38, v38
	v_exp_f32_e32 v39, v39
	v_exp_f32_e32 v40, v40
	v_add_f32_e32 v31, 1.0, v31
	v_add_f32_e32 v33, 1.0, v33
	v_add_f32_e32 v26, 1.0, v26
	v_add_f32_e32 v27, 1.0, v27
	v_rcp_f32_e32 v31, v31
	v_rcp_f32_e32 v33, v33
	v_add_f32_e32 v37, 1.0, v37
	v_add_f32_e32 v38, 1.0, v38
	v_add_f32_e32 v39, 1.0, v39
	v_add_f32_e32 v40, 1.0, v40
	v_rcp_f32_e32 v26, v26
	v_rcp_f32_e32 v27, v27
	v_rcp_f32_e32 v37, v37
	v_rcp_f32_e32 v38, v38
	v_rcp_f32_e32 v39, v39
	v_rcp_f32_e32 v40, v40
	v_cvt_f16_f32_e32 v31, v31
	v_cvt_f16_f32_sdwa v33, v33 dst_sel:WORD_1 dst_unused:UNUSED_PAD src0_sel:DWORD
	v_cvt_f16_f32_e32 v26, v26
	v_cvt_f16_f32_sdwa v27, v27 dst_sel:WORD_1 dst_unused:UNUSED_PAD src0_sel:DWORD
	v_cvt_f16_f32_e32 v37, v37
	v_cvt_f16_f32_sdwa v41, v38 dst_sel:WORD_1 dst_unused:UNUSED_PAD src0_sel:DWORD
	v_cvt_f16_f32_e32 v42, v39
	v_cvt_f16_f32_sdwa v43, v40 dst_sel:WORD_1 dst_unused:UNUSED_PAD src0_sel:DWORD
	v_readlane_b32 s2, v253, 19
	v_or_b32_e32 v39, v33, v31
	v_ashrrev_i32_e32 v33, 31, v32
	v_readlane_b32 s3, v253, 20
	v_or_b32_e32 v38, v27, v26
	v_or_b32_e32 v40, v41, v37
	v_or_b32_e32 v41, v43, v42
	v_lshl_add_u64 v[26:27], v[72:73], 0, v[32:33]
	v_mov_b64_e32 v[42:43], s[2:3]
	v_mad_u64_u32 v[42:43], s[2:3], v26, s77, v[42:43]
	v_mad_i32_i24 v43, v27, s77, v43
	v_lshl_add_u64 v[26:27], v[70:71], 1, v[42:43]
	global_store_dwordx4 v[26:27], v[38:41], off sc1

.LBB0_998:
	s_andn2_b64 vcc, exec, s[2:3]
	s_cbranch_vccnz .LBB0_1000
	v_mul_f32_e32 v27, 0xbfb8aa3b, v35
	v_exp_f32_e32 v27, v27
	v_mul_f32_e32 v31, 0xbfb8aa3b, v34
	v_mul_f32_e32 v30, 0xbfb8aa3b, v30
	v_mul_f32_e32 v26, 0xbfb8aa3b, v36
	v_exp_f32_e32 v31, v31
	v_exp_f32_e32 v33, v30
	v_exp_f32_e32 v26, v26
	v_add_f32_e32 v27, 1.0, v27
	v_mul_f32_e32 v29, 0xbfb8aa3b, v29
	v_mul_f32_e32 v28, 0xbfb8aa3b, v28
	v_mul_f32_e32 v25, 0xbfb8aa3b, v25
	v_mul_f32_e32 v24, 0xbfb8aa3b, v24
	v_rcp_f32_e32 v30, v27
	v_add_f32_e32 v27, 1.0, v31
	v_add_f32_e32 v31, 1.0, v33
	v_exp_f32_e32 v29, v29
	v_exp_f32_e32 v33, v28
	v_exp_f32_e32 v25, v25
	v_exp_f32_e32 v24, v24
	v_add_f32_e32 v26, 1.0, v26
	v_rcp_f32_e32 v26, v26
	v_rcp_f32_e32 v27, v27
	v_rcp_f32_e32 v31, v31
	v_add_f32_e32 v28, 1.0, v29
	v_add_f32_e32 v29, 1.0, v33
	v_add_f32_e32 v25, 1.0, v25
	v_add_f32_e32 v24, 1.0, v24
	v_rcp_f32_e32 v28, v28
	v_rcp_f32_e32 v34, v29
	v_rcp_f32_e32 v29, v25
	v_rcp_f32_e32 v35, v24
	s_mov_b32 s2, 0xbf1b4598
	v_pk_mul_f32 v[24:25], v[26:27], s[2:3] op_sel_hi:[1,0]
	v_pk_mul_f32 v[26:27], v[30:31], s[2:3] op_sel_hi:[1,0]
	v_cvt_pk_f16_f32 v24, v24, v25
	v_cvt_pk_f16_f32 v25, v26, v27
	v_and_b32_e32 v26, 0xffff0000, v25
	v_lshlrev_b32_e32 v27, 16, v25
	v_or_b32_sdwa v25, v26, v24 dst_sel:DWORD dst_unused:UNUSED_PAD src0_sel:DWORD src1_sel:WORD_1
	v_or_b32_sdwa v24, v27, v24 dst_sel:DWORD dst_unused:UNUSED_PAD src0_sel:DWORD src1_sel:WORD_0
	v_pk_mul_f32 v[26:27], v[28:29], s[2:3] op_sel_hi:[1,0]
	v_pk_mul_f32 v[28:29], v[34:35], s[2:3] op_sel_hi:[1,0]
	v_cvt_pk_f16_f32 v26, v26, v27
	v_cvt_pk_f16_f32 v27, v28, v29
	v_and_b32_e32 v28, 0xffff0000, v27
	v_lshlrev_b32_e32 v29, 16, v27
	v_ashrrev_i32_e32 v33, 31, v32
	v_or_b32_sdwa v27, v28, v26 dst_sel:DWORD dst_unused:UNUSED_PAD src0_sel:DWORD src1_sel:WORD_1
	v_or_b32_sdwa v26, v29, v26 dst_sel:DWORD dst_unused:UNUSED_PAD src0_sel:DWORD src1_sel:WORD_0
	v_lshl_add_u64 v[28:29], v[62:63], 0, v[32:33]
	v_mov_b64_e32 v[30:31], s[4:5]
	v_mad_u64_u32 v[30:31], s[2:3], v28, s77, v[30:31]
	v_mad_i32_i24 v31, v29, s77, v31
	v_lshl_add_u64 v[28:29], v[60:61], 1, v[30:31]
	global_store_dwordx4 v[28:29], v[24:27], off sc1
.LBB0_1000:
	s_nop 1
	v_add_f32_e32 v26, v20, v74
	v_add_f32_e32 v25, v21, v75
	v_add_f32_e32 v24, v22, v76
	v_add_f32_e32 v23, v23, v77
	v_add_f32_e32 v22, v16, v78
	v_add_f32_e32 v21, v17, v79
	v_add_f32_e32 v20, v18, v80
	v_add_f32_e32 v18, v19, v81
	v_add_u32_e32 v16, 0x90, v140
	s_cmp_lt_i32 s0, 1
	s_mov_b64 s[2:3], -1
	s_cbranch_scc1 .LBB0_1006
	s_cmp_lg_u32 s0, 1
	s_cbranch_scc0 .LBB0_1003
	v_ashrrev_i32_e32 v17, 31, v16
	v_lshlrev_b64 v[32:33], 11, v[16:17]
	v_lshl_add_u64 v[32:33], s[24:25], 0, v[32:33]
	v_lshl_add_u64 v[32:33], v[68:69], 1, v[32:33]
	v_cvt_pk_bf16_f32 v28, v26, v25
	v_cvt_pk_bf16_f32 v29, v24, v23
	v_cvt_pk_bf16_f32 v30, v22, v21
	v_cvt_pk_bf16_f32 v31, v20, v18
	global_store_dwordx4 v[32:33], v[28:31], off offset:-1792 sc1
	s_mov_b64 s[2:3], 0
.LBB0_1003:
	s_andn2_b64 vcc, exec, s[2:3]
	s_cbranch_vccnz .LBB0_1005
	v_mul_f32_e32 v17, 0xbfb8aa3b, v26
	v_mul_f32_e32 v19, 0xbfb8aa3b, v25
	v_exp_f32_e32 v17, v17
	v_exp_f32_e32 v19, v19
	v_mul_f32_e32 v27, 0xbfb8aa3b, v24
	v_mul_f32_e32 v28, 0xbfb8aa3b, v23
	v_mul_f32_e32 v29, 0xbfb8aa3b, v22
	v_mul_f32_e32 v30, 0xbfb8aa3b, v21
	v_mul_f32_e32 v31, 0xbfb8aa3b, v20
	v_mul_f32_e32 v32, 0xbfb8aa3b, v18
	v_exp_f32_e32 v27, v27
	v_exp_f32_e32 v28, v28
	v_exp_f32_e32 v29, v29
	v_exp_f32_e32 v30, v30
	v_exp_f32_e32 v31, v31
	v_exp_f32_e32 v32, v32
	v_add_f32_e32 v17, 1.0, v17
	v_add_f32_e32 v19, 1.0, v19
	v_rcp_f32_e32 v17, v17
	v_rcp_f32_e32 v19, v19
	v_add_f32_e32 v27, 1.0, v27
	v_add_f32_e32 v28, 1.0, v28
	v_add_f32_e32 v29, 1.0, v29
	v_add_f32_e32 v30, 1.0, v30
	v_add_f32_e32 v31, 1.0, v31
	v_add_f32_e32 v32, 1.0, v32
	v_rcp_f32_e32 v27, v27
	v_rcp_f32_e32 v28, v28
	v_rcp_f32_e32 v29, v29
	v_rcp_f32_e32 v30, v30
	v_rcp_f32_e32 v31, v31
	v_rcp_f32_e32 v32, v32
	v_cvt_f16_f32_e32 v17, v17
	v_cvt_f16_f32_sdwa v19, v19 dst_sel:WORD_1 dst_unused:UNUSED_PAD src0_sel:DWORD
	v_cvt_f16_f32_e32 v27, v27
	v_cvt_f16_f32_sdwa v33, v28 dst_sel:WORD_1 dst_unused:UNUSED_PAD src0_sel:DWORD
	v_cvt_f16_f32_e32 v34, v29
	v_cvt_f16_f32_sdwa v30, v30 dst_sel:WORD_1 dst_unused:UNUSED_PAD src0_sel:DWORD
	v_cvt_f16_f32_e32 v31, v31
	v_cvt_f16_f32_sdwa v32, v32 dst_sel:WORD_1 dst_unused:UNUSED_PAD src0_sel:DWORD
	v_readlane_b32 s2, v253, 19
	v_or_b32_e32 v28, v19, v17
	v_ashrrev_i32_e32 v17, 31, v16
	v_readlane_b32 s3, v253, 20
	v_or_b32_e32 v29, v33, v27
	v_or_b32_e32 v30, v30, v34
	v_or_b32_e32 v31, v32, v31
	v_lshl_add_u64 v[32:33], v[72:73], 0, v[16:17]
	v_mov_b64_e32 v[34:35], s[2:3]
	v_mad_u64_u32 v[34:35], s[2:3], v32, s77, v[34:35]
	v_mad_i32_i24 v35, v33, s77, v35
	v_lshl_add_u64 v[32:33], v[70:71], 1, v[34:35]
	global_store_dwordx4 v[32:33], v[28:31], off sc1

.LBB0_1006:
	s_andn2_b64 vcc, exec, s[2:3]
	s_cbranch_vccnz .LBB0_1008
	v_mul_f32_e32 v17, 0xbfb8aa3b, v26
	v_exp_f32_e32 v17, v17
	v_mul_f32_e32 v19, 0xbfb8aa3b, v25
	v_exp_f32_e32 v19, v19
	v_mul_f32_e32 v23, 0xbfb8aa3b, v23
	v_add_f32_e32 v17, 1.0, v17
	v_rcp_f32_e32 v26, v17
	v_mul_f32_e32 v17, 0xbfb8aa3b, v24
	v_add_f32_e32 v19, 1.0, v19
	v_exp_f32_e32 v17, v17
	v_exp_f32_e32 v23, v23
	v_rcp_f32_e32 v24, v19
	v_mul_f32_e32 v19, 0xbfb8aa3b, v22
	v_exp_f32_e32 v19, v19
	v_add_f32_e32 v17, 1.0, v17
	v_rcp_f32_e32 v27, v17
	v_add_f32_e32 v17, 1.0, v23
	v_mul_f32_e32 v21, 0xbfb8aa3b, v21
	v_exp_f32_e32 v21, v21
	v_rcp_f32_e32 v25, v17
	v_add_f32_e32 v17, 1.0, v19
	v_mul_f32_e32 v19, 0xbfb8aa3b, v20
	v_exp_f32_e32 v19, v19
	v_mul_f32_e32 v18, 0xbfb8aa3b, v18
	v_exp_f32_e32 v18, v18
	v_rcp_f32_e32 v22, v17
	v_add_f32_e32 v17, 1.0, v21
	v_rcp_f32_e32 v20, v17
	v_add_f32_e32 v17, 1.0, v19
	v_rcp_f32_e32 v23, v17
	v_add_f32_e32 v17, 1.0, v18
	v_rcp_f32_e32 v21, v17
	s_mov_b32 s2, 0xbf1b4598
	v_pk_mul_f32 v[18:19], v[26:27], s[2:3] op_sel_hi:[1,0]
	v_pk_mul_f32 v[24:25], v[24:25], s[2:3] op_sel_hi:[1,0]
	v_cvt_pk_f16_f32 v17, v18, v19
	v_cvt_pk_f16_f32 v18, v24, v25
	v_pk_mul_f32 v[20:21], v[20:21], s[2:3] op_sel_hi:[1,0]
	v_and_b32_e32 v19, 0xffff0000, v18
	v_lshlrev_b32_e32 v18, 16, v18
	v_pk_mul_f32 v[22:23], v[22:23], s[2:3] op_sel_hi:[1,0]
	v_cvt_pk_f16_f32 v20, v20, v21
	v_or_b32_sdwa v19, v19, v17 dst_sel:DWORD dst_unused:UNUSED_PAD src0_sel:DWORD src1_sel:WORD_1
	v_or_b32_sdwa v18, v18, v17 dst_sel:DWORD dst_unused:UNUSED_PAD src0_sel:DWORD src1_sel:WORD_0
	v_cvt_pk_f16_f32 v17, v22, v23
	v_and_b32_e32 v21, 0xffff0000, v20
	v_lshlrev_b32_e32 v20, 16, v20
	v_or_b32_sdwa v21, v21, v17 dst_sel:DWORD dst_unused:UNUSED_PAD src0_sel:DWORD src1_sel:WORD_1
	v_or_b32_sdwa v20, v20, v17 dst_sel:DWORD dst_unused:UNUSED_PAD src0_sel:DWORD src1_sel:WORD_0
	v_ashrrev_i32_e32 v17, 31, v16
	v_lshl_add_u64 v[16:17], v[62:63], 0, v[16:17]
	v_mov_b64_e32 v[22:23], s[4:5]
	v_mad_u64_u32 v[22:23], s[2:3], v16, s77, v[22:23]
	v_mad_i32_i24 v23, v17, s77, v23
	v_lshl_add_u64 v[16:17], v[60:61], 1, v[22:23]
	global_store_dwordx4 v[16:17], v[18:21], off sc1
.LBB0_1008:
	s_nop 1
	v_add_f32_e32 v18, v12, v74
	v_add_f32_e32 v17, v13, v75
	v_add_f32_e32 v16, v14, v76
	v_add_f32_e32 v15, v15, v77
	v_add_f32_e32 v14, v8, v78
	v_add_f32_e32 v13, v9, v79
	v_add_f32_e32 v12, v10, v80
	v_add_f32_e32 v10, v11, v81
	v_add_u32_e32 v8, 0xa0, v140
	s_cmp_lt_i32 s0, 1
	s_mov_b64 s[2:3], -1
	s_cbranch_scc1 .LBB0_1014
	s_cmp_lg_u32 s0, 1
	s_cbranch_scc0 .LBB0_1011
	v_ashrrev_i32_e32 v9, 31, v8
	v_lshlrev_b64 v[24:25], 11, v[8:9]
	v_lshl_add_u64 v[24:25], s[24:25], 0, v[24:25]
	v_lshl_add_u64 v[24:25], v[68:69], 1, v[24:25]
	v_cvt_pk_bf16_f32 v20, v18, v17
	v_cvt_pk_bf16_f32 v21, v16, v15
	v_cvt_pk_bf16_f32 v22, v14, v13
	v_cvt_pk_bf16_f32 v23, v12, v10
	global_store_dwordx4 v[24:25], v[20:23], off offset:-1792 sc1
	s_mov_b64 s[2:3], 0
.LBB0_1011:
	s_andn2_b64 vcc, exec, s[2:3]
	s_cbranch_vccnz .LBB0_1013
	v_mul_f32_e32 v9, 0xbfb8aa3b, v18
	v_mul_f32_e32 v11, 0xbfb8aa3b, v17
	v_exp_f32_e32 v9, v9
	v_exp_f32_e32 v11, v11
	v_mul_f32_e32 v19, 0xbfb8aa3b, v16
	v_mul_f32_e32 v20, 0xbfb8aa3b, v15
	v_mul_f32_e32 v21, 0xbfb8aa3b, v14
	v_mul_f32_e32 v22, 0xbfb8aa3b, v13
	v_mul_f32_e32 v23, 0xbfb8aa3b, v12
	v_mul_f32_e32 v24, 0xbfb8aa3b, v10
	v_exp_f32_e32 v19, v19
	v_exp_f32_e32 v20, v20
	v_exp_f32_e32 v21, v21
	v_exp_f32_e32 v22, v22
	v_exp_f32_e32 v23, v23
	v_exp_f32_e32 v24, v24
	v_add_f32_e32 v9, 1.0, v9
	v_add_f32_e32 v11, 1.0, v11
	v_rcp_f32_e32 v9, v9
	v_rcp_f32_e32 v11, v11
	v_add_f32_e32 v19, 1.0, v19
	v_add_f32_e32 v20, 1.0, v20
	v_add_f32_e32 v21, 1.0, v21
	v_add_f32_e32 v22, 1.0, v22
	v_add_f32_e32 v23, 1.0, v23
	v_add_f32_e32 v24, 1.0, v24
	v_rcp_f32_e32 v19, v19
	v_rcp_f32_e32 v20, v20
	v_rcp_f32_e32 v21, v21
	v_rcp_f32_e32 v22, v22
	v_rcp_f32_e32 v23, v23
	v_rcp_f32_e32 v24, v24
	v_cvt_f16_f32_e32 v9, v9
	v_cvt_f16_f32_sdwa v11, v11 dst_sel:WORD_1 dst_unused:UNUSED_PAD src0_sel:DWORD
	v_cvt_f16_f32_e32 v19, v19
	v_cvt_f16_f32_sdwa v25, v20 dst_sel:WORD_1 dst_unused:UNUSED_PAD src0_sel:DWORD
	v_cvt_f16_f32_e32 v26, v21
	v_cvt_f16_f32_sdwa v22, v22 dst_sel:WORD_1 dst_unused:UNUSED_PAD src0_sel:DWORD
	v_cvt_f16_f32_e32 v23, v23
	v_cvt_f16_f32_sdwa v24, v24 dst_sel:WORD_1 dst_unused:UNUSED_PAD src0_sel:DWORD
	v_readlane_b32 s2, v253, 19
	v_or_b32_e32 v20, v11, v9
	v_ashrrev_i32_e32 v9, 31, v8
	v_readlane_b32 s3, v253, 20
	v_or_b32_e32 v21, v25, v19
	v_or_b32_e32 v22, v22, v26
	v_or_b32_e32 v23, v24, v23
	v_lshl_add_u64 v[24:25], v[72:73], 0, v[8:9]
	v_mov_b64_e32 v[26:27], s[2:3]
	v_mad_u64_u32 v[26:27], s[2:3], v24, s77, v[26:27]
	v_mad_i32_i24 v27, v25, s77, v27
	v_lshl_add_u64 v[24:25], v[70:71], 1, v[26:27]
	global_store_dwordx4 v[24:25], v[20:23], off sc1

.LBB0_1014:
	s_andn2_b64 vcc, exec, s[2:3]
	s_cbranch_vccnz .LBB0_1016
	v_mul_f32_e32 v9, 0xbfb8aa3b, v18
	v_exp_f32_e32 v9, v9
	v_mul_f32_e32 v11, 0xbfb8aa3b, v17
	v_exp_f32_e32 v11, v11
	v_mul_f32_e32 v15, 0xbfb8aa3b, v15
	v_add_f32_e32 v9, 1.0, v9
	v_rcp_f32_e32 v18, v9
	v_mul_f32_e32 v9, 0xbfb8aa3b, v16
	v_add_f32_e32 v11, 1.0, v11
	v_exp_f32_e32 v9, v9
	v_exp_f32_e32 v15, v15
	v_rcp_f32_e32 v16, v11
	v_mul_f32_e32 v11, 0xbfb8aa3b, v14
	v_exp_f32_e32 v11, v11
	v_add_f32_e32 v9, 1.0, v9
	v_rcp_f32_e32 v19, v9
	v_add_f32_e32 v9, 1.0, v15
	v_mul_f32_e32 v13, 0xbfb8aa3b, v13
	v_exp_f32_e32 v13, v13
	v_rcp_f32_e32 v17, v9
	v_add_f32_e32 v9, 1.0, v11
	v_mul_f32_e32 v11, 0xbfb8aa3b, v12
	v_exp_f32_e32 v11, v11
	v_mul_f32_e32 v10, 0xbfb8aa3b, v10
	v_exp_f32_e32 v10, v10
	v_rcp_f32_e32 v14, v9
	v_add_f32_e32 v9, 1.0, v13
	v_rcp_f32_e32 v12, v9
	v_add_f32_e32 v9, 1.0, v11
	v_rcp_f32_e32 v15, v9
	v_add_f32_e32 v9, 1.0, v10
	v_rcp_f32_e32 v13, v9
	s_mov_b32 s2, 0xbf1b4598
	v_pk_mul_f32 v[10:11], v[18:19], s[2:3] op_sel_hi:[1,0]
	v_pk_mul_f32 v[16:17], v[16:17], s[2:3] op_sel_hi:[1,0]
	v_cvt_pk_f16_f32 v9, v10, v11
	v_cvt_pk_f16_f32 v10, v16, v17
	v_pk_mul_f32 v[12:13], v[12:13], s[2:3] op_sel_hi:[1,0]
	v_and_b32_e32 v11, 0xffff0000, v10
	v_lshlrev_b32_e32 v10, 16, v10
	v_pk_mul_f32 v[14:15], v[14:15], s[2:3] op_sel_hi:[1,0]
	v_cvt_pk_f16_f32 v12, v12, v13
	v_or_b32_sdwa v11, v11, v9 dst_sel:DWORD dst_unused:UNUSED_PAD src0_sel:DWORD src1_sel:WORD_1
	v_or_b32_sdwa v10, v10, v9 dst_sel:DWORD dst_unused:UNUSED_PAD src0_sel:DWORD src1_sel:WORD_0
	v_cvt_pk_f16_f32 v9, v14, v15
	v_and_b32_e32 v13, 0xffff0000, v12
	v_lshlrev_b32_e32 v12, 16, v12
	v_or_b32_sdwa v13, v13, v9 dst_sel:DWORD dst_unused:UNUSED_PAD src0_sel:DWORD src1_sel:WORD_1
	v_or_b32_sdwa v12, v12, v9 dst_sel:DWORD dst_unused:UNUSED_PAD src0_sel:DWORD src1_sel:WORD_0
	v_ashrrev_i32_e32 v9, 31, v8
	v_lshl_add_u64 v[8:9], v[62:63], 0, v[8:9]
	v_mov_b64_e32 v[14:15], s[4:5]
	v_mad_u64_u32 v[14:15], s[2:3], v8, s77, v[14:15]
	v_mad_i32_i24 v15, v9, s77, v15
	v_lshl_add_u64 v[8:9], v[60:61], 1, v[14:15]
	global_store_dwordx4 v[8:9], v[10:13], off sc1
.LBB0_1016:
	s_nop 1
	v_add_f32_e32 v10, v4, v74
	v_add_f32_e32 v9, v5, v75
	v_add_f32_e32 v8, v6, v76
	v_add_f32_e32 v7, v7, v77
	v_add_f32_e32 v6, v0, v78
	v_add_f32_e32 v5, v1, v79
	v_add_f32_e32 v4, v2, v80
	v_add_f32_e32 v2, v3, v81
	v_add_u32_e32 v0, 0xb0, v140
	s_cmp_lt_i32 s0, 1
	s_mov_b64 s[2:3], -1
	s_cbranch_scc1 .LBB0_1022
	s_cmp_lg_u32 s0, 1
	s_cbranch_scc0 .LBB0_1019
	v_ashrrev_i32_e32 v1, 31, v0
	v_lshlrev_b64 v[16:17], 11, v[0:1]
	v_lshl_add_u64 v[16:17], s[24:25], 0, v[16:17]
	v_lshl_add_u64 v[16:17], v[68:69], 1, v[16:17]
	v_cvt_pk_bf16_f32 v12, v10, v9
	v_cvt_pk_bf16_f32 v13, v8, v7
	v_cvt_pk_bf16_f32 v14, v6, v5
	v_cvt_pk_bf16_f32 v15, v4, v2
	global_store_dwordx4 v[16:17], v[12:15], off offset:-1792 sc1
	s_mov_b64 s[2:3], 0
.LBB0_1019:
	s_andn2_b64 vcc, exec, s[2:3]
	s_cbranch_vccnz .LBB0_1021
	v_mul_f32_e32 v1, 0xbfb8aa3b, v10
	v_mul_f32_e32 v3, 0xbfb8aa3b, v9
	v_exp_f32_e32 v1, v1
	v_exp_f32_e32 v3, v3
	v_mul_f32_e32 v11, 0xbfb8aa3b, v8
	v_mul_f32_e32 v12, 0xbfb8aa3b, v7
	v_mul_f32_e32 v13, 0xbfb8aa3b, v6
	v_mul_f32_e32 v14, 0xbfb8aa3b, v5
	v_mul_f32_e32 v15, 0xbfb8aa3b, v4
	v_mul_f32_e32 v16, 0xbfb8aa3b, v2
	v_exp_f32_e32 v11, v11
	v_exp_f32_e32 v12, v12
	v_exp_f32_e32 v13, v13
	v_exp_f32_e32 v14, v14
	v_exp_f32_e32 v15, v15
	v_exp_f32_e32 v16, v16
	v_add_f32_e32 v1, 1.0, v1
	v_add_f32_e32 v3, 1.0, v3
	v_rcp_f32_e32 v1, v1
	v_rcp_f32_e32 v3, v3
	v_add_f32_e32 v11, 1.0, v11
	v_add_f32_e32 v12, 1.0, v12
	v_add_f32_e32 v13, 1.0, v13
	v_add_f32_e32 v14, 1.0, v14
	v_add_f32_e32 v15, 1.0, v15
	v_add_f32_e32 v16, 1.0, v16
	v_rcp_f32_e32 v11, v11
	v_rcp_f32_e32 v12, v12
	v_rcp_f32_e32 v13, v13
	v_rcp_f32_e32 v14, v14
	v_rcp_f32_e32 v15, v15
	v_rcp_f32_e32 v16, v16
	v_cvt_f16_f32_e32 v1, v1
	v_cvt_f16_f32_sdwa v3, v3 dst_sel:WORD_1 dst_unused:UNUSED_PAD src0_sel:DWORD
	v_cvt_f16_f32_e32 v11, v11
	v_cvt_f16_f32_sdwa v17, v12 dst_sel:WORD_1 dst_unused:UNUSED_PAD src0_sel:DWORD
	v_cvt_f16_f32_e32 v18, v13
	v_cvt_f16_f32_sdwa v14, v14 dst_sel:WORD_1 dst_unused:UNUSED_PAD src0_sel:DWORD
	v_cvt_f16_f32_e32 v15, v15
	v_cvt_f16_f32_sdwa v16, v16 dst_sel:WORD_1 dst_unused:UNUSED_PAD src0_sel:DWORD
	v_readlane_b32 s0, v253, 19
	v_or_b32_e32 v12, v3, v1
	v_ashrrev_i32_e32 v1, 31, v0
	v_readlane_b32 s1, v253, 20
	v_or_b32_e32 v13, v17, v11
	v_or_b32_e32 v14, v14, v18
	v_or_b32_e32 v15, v16, v15
	v_lshl_add_u64 v[16:17], v[72:73], 0, v[0:1]
	v_mov_b64_e32 v[18:19], s[0:1]
	v_mad_u64_u32 v[18:19], s[0:1], v16, s77, v[18:19]
	v_mad_i32_i24 v19, v17, s77, v19
	v_lshl_add_u64 v[16:17], v[70:71], 1, v[18:19]
	global_store_dwordx4 v[16:17], v[12:15], off sc1

.LBB0_1022:
	s_andn2_b64 vcc, exec, s[2:3]
	s_cbranch_vccnz .LBB0_1024
	v_mul_f32_e32 v1, 0xbfb8aa3b, v10
	v_exp_f32_e32 v1, v1
	v_mul_f32_e32 v3, 0xbfb8aa3b, v9
	v_exp_f32_e32 v3, v3
	v_mul_f32_e32 v7, 0xbfb8aa3b, v7
	v_add_f32_e32 v1, 1.0, v1
	v_rcp_f32_e32 v10, v1
	v_mul_f32_e32 v1, 0xbfb8aa3b, v8
	v_add_f32_e32 v3, 1.0, v3
	v_exp_f32_e32 v1, v1
	v_exp_f32_e32 v7, v7
	v_rcp_f32_e32 v8, v3
	v_mul_f32_e32 v3, 0xbfb8aa3b, v6
	v_exp_f32_e32 v3, v3
	v_add_f32_e32 v1, 1.0, v1
	v_rcp_f32_e32 v11, v1
	v_add_f32_e32 v1, 1.0, v7
	v_mul_f32_e32 v5, 0xbfb8aa3b, v5
	v_exp_f32_e32 v5, v5
	v_rcp_f32_e32 v9, v1
	v_add_f32_e32 v1, 1.0, v3
	v_mul_f32_e32 v3, 0xbfb8aa3b, v4
	v_exp_f32_e32 v3, v3
	v_mul_f32_e32 v2, 0xbfb8aa3b, v2
	v_exp_f32_e32 v2, v2
	v_rcp_f32_e32 v6, v1
	v_add_f32_e32 v1, 1.0, v5
	v_rcp_f32_e32 v4, v1
	v_add_f32_e32 v1, 1.0, v3
	v_rcp_f32_e32 v7, v1
	v_add_f32_e32 v1, 1.0, v2
	v_rcp_f32_e32 v5, v1
	s_mov_b32 s0, 0xbf1b4598
	v_pk_mul_f32 v[2:3], v[10:11], s[0:1] op_sel_hi:[1,0]
	v_pk_mul_f32 v[8:9], v[8:9], s[0:1] op_sel_hi:[1,0]
	v_cvt_pk_f16_f32 v1, v2, v3
	v_cvt_pk_f16_f32 v2, v8, v9
	v_pk_mul_f32 v[4:5], v[4:5], s[0:1] op_sel_hi:[1,0]
	v_and_b32_e32 v3, 0xffff0000, v2
	v_lshlrev_b32_e32 v2, 16, v2
	v_pk_mul_f32 v[6:7], v[6:7], s[0:1] op_sel_hi:[1,0]
	v_cvt_pk_f16_f32 v4, v4, v5
	v_or_b32_sdwa v3, v3, v1 dst_sel:DWORD dst_unused:UNUSED_PAD src0_sel:DWORD src1_sel:WORD_1
	v_or_b32_sdwa v2, v2, v1 dst_sel:DWORD dst_unused:UNUSED_PAD src0_sel:DWORD src1_sel:WORD_0
	v_cvt_pk_f16_f32 v1, v6, v7
	v_and_b32_e32 v5, 0xffff0000, v4
	v_lshlrev_b32_e32 v4, 16, v4
	v_or_b32_sdwa v5, v5, v1 dst_sel:DWORD dst_unused:UNUSED_PAD src0_sel:DWORD src1_sel:WORD_1
	v_or_b32_sdwa v4, v4, v1 dst_sel:DWORD dst_unused:UNUSED_PAD src0_sel:DWORD src1_sel:WORD_0
	v_ashrrev_i32_e32 v1, 31, v0
	v_lshl_add_u64 v[0:1], v[62:63], 0, v[0:1]
	v_mov_b64_e32 v[6:7], s[4:5]
	v_mad_u64_u32 v[6:7], s[0:1], v0, s77, v[6:7]
	v_mad_i32_i24 v7, v1, s77, v7
	v_lshl_add_u64 v[0:1], v[60:61], 1, v[6:7]
	global_store_dwordx4 v[0:1], v[2:5], off sc1

.LBB0_1253:
	s_waitcnt vmcnt(0)
	ds_write2_b32 v20, v0, v1 offset1:65
	ds_write2_b32 v20, v2, v3 offset0:130 offset1:195
	v_add_u32_e32 v0, 0x400, v20
	s_mul_hi_i32 s6, s14, 0x2e8ba2e9
	ds_write2_b32 v0, v4, v5 offset0:4 offset1:69
	ds_write2_b32 v0, v6, v7 offset0:134 offset1:199
	s_waitcnt lgkmcnt(0)
	s_barrier
	ds_read2_b32 v[0:1], v21 offset1:65
	ds_read2_b32 v[2:3], v21 offset0:130 offset1:195
	v_add_u32_e32 v6, 0x400, v21
	s_lshr_b32 s7, s6, 31
	s_ashr_i32 s6, s6, 4
	ds_read2_b32 v[4:5], v6 offset0:4 offset1:69
	ds_read2_b32 v[6:7], v6 offset0:134 offset1:199
	s_add_i32 s7, s6, s7
	s_lshl_b32 s6, s7, 6
	s_mulk_i32 s7, 0xea00
	s_add_i32 s7, s7, s12
	s_waitcnt lgkmcnt(3)
	v_cvt_pk_bf16_f32 v0, v0, v1
	s_waitcnt lgkmcnt(2)
	v_cvt_pk_bf16_f32 v1, v2, v3
	s_waitcnt lgkmcnt(1)
	v_cvt_pk_bf16_f32 v2, v4, v5
	v_add_u32_e32 v4, s7, v19
	v_ashrrev_i32_e32 v5, 31, v4
	v_readlane_b32 s8, v251, 53
	v_lshlrev_b64 v[4:5], 11, v[4:5]
	v_readlane_b32 s9, v251, 54
	s_ashr_i32 s7, s6, 31
	s_andn2_b64 vcc, exec, s[2:3]
	v_lshl_add_u64 v[4:5], s[8:9], 0, v[4:5]
	v_lshl_add_u64 v[4:5], s[6:7], 1, v[4:5]
	v_lshl_add_u64 v[4:5], v[4:5], 0, v[50:51]
	s_add_i32 s10, s10, s11
	s_waitcnt lgkmcnt(0)
	v_cvt_pk_bf16_f32 v3, v6, v7
	global_store_dwordx4 v[4:5], v[0:3], off sc1
	s_barrier
	s_cbranch_vccz .LBB0_1255
	v_mov_b64_e32 v[0:1], v[8:9]
	s_mov_b32 s12, s13
	s_mov_b32 s14, s0
	v_mov_b64_e32 v[2:3], v[10:11]
	v_mov_b64_e32 v[4:5], v[12:13]
	v_mov_b64_e32 v[6:7], v[14:15]
	s_branch .LBB0_1232

.LBB0_1275:
	s_add_i32 s1, s0, 0xfffffa80
	s_ashr_i32 s2, s1, 31
	v_add_u32_e32 v0, 0x400, v11
	s_lshr_b32 s2, s2, 28
	s_waitcnt vmcnt(0)
	ds_write2_b32 v11, v5, v6 offset1:65
	ds_write2_b32 v11, v7, v8 offset0:130 offset1:195
	ds_write2_b32 v0, v9, v13 offset0:4 offset1:69
	ds_write2_b32 v0, v14, v15 offset0:134 offset1:199
	s_waitcnt lgkmcnt(0)
	s_barrier
	ds_read2_b32 v[2:3], v12 offset1:65
	ds_read2_b32 v[8:9], v12 offset0:130 offset1:195
	s_add_i32 s2, s1, s2
	s_and_b32 s3, s2, 0x3fffff0
	v_add_u32_e32 v0, 0x400, v12
	v_readlane_b32 s6, v253, 34
	s_sub_i32 s1, s1, s3
	s_lshl_b32 s2, s2, 2
	ds_read2_b32 v[14:15], v0 offset0:4 offset1:69
	ds_read2_b32 v[26:27], v0 offset0:134 offset1:199
	v_readlane_b32 s7, v253, 35
	s_andn2_b32 s2, s2, 63
	v_readlane_b32 s3, v253, 46
	s_waitcnt lgkmcnt(3)
	v_cvt_pk_bf16_f32 v6, v2, v3
	v_lshl_add_u32 v0, s1, 6, v10
	v_mov_b64_e32 v[2:3], s[6:7]
	s_movk_i32 s1, 0x1600
	s_add_i32 s0, s0, s3
	v_mad_i64_i32 v[2:3], s[6:7], v0, s1, v[2:3]
	s_ashr_i32 s3, s2, 31
	v_lshl_add_u64 v[2:3], s[2:3], 1, v[2:3]
	v_lshl_add_u64 v[2:3], v[2:3], 0, v[50:51]
	s_cmpk_lt_i32 s0, 0x840
	s_waitcnt lgkmcnt(2)
	v_cvt_pk_bf16_f32 v7, v8, v9
	s_waitcnt lgkmcnt(1)
	v_cvt_pk_bf16_f32 v8, v14, v15
	s_waitcnt lgkmcnt(0)
	v_cvt_pk_bf16_f32 v9, v26, v27
	global_store_dwordx4 v[2:3], v[6:9], off sc1
	s_barrier
	s_cbranch_scc0 .LBB0_1277
	v_mov_b32_e32 v5, v1
	v_mov_b32_e32 v6, v16
	v_mov_b32_e32 v7, v18
	v_mov_b32_e32 v8, v17
	v_mov_b32_e32 v9, v20
	v_mov_b32_e32 v13, v19
	v_mov_b32_e32 v14, v22
	v_mov_b32_e32 v15, v21
	s_branch .LBB0_1257

.LBB0_1296:
	s_add_i32 s1, s0, 0xfffff7c0
	s_mul_hi_i32 s2, s1, 0x92492493
	s_waitcnt vmcnt(0)
	ds_write2_b32 v20, v0, v1 offset1:65
	ds_write2_b32 v20, v2, v3 offset0:130 offset1:195
	v_add_u32_e32 v0, 0x400, v20
	s_add_i32 s2, s2, s1
	ds_write2_b32 v0, v4, v5 offset0:4 offset1:69
	ds_write2_b32 v0, v6, v7 offset0:134 offset1:199
	s_waitcnt lgkmcnt(0)
	s_barrier
	ds_read2_b32 v[0:1], v21 offset1:65
	ds_read2_b32 v[2:3], v21 offset0:130 offset1:195
	v_add_u32_e32 v6, 0x400, v21
	s_lshr_b32 s3, s2, 31
	s_ashr_i32 s2, s2, 5
	ds_read2_b32 v[4:5], v6 offset0:4 offset1:69
	ds_read2_b32 v[6:7], v6 offset0:134 offset1:199
	s_add_i32 s2, s2, s3
	s_mul_i32 s3, s2, 56
	s_sub_i32 s1, s1, s3
	s_waitcnt lgkmcnt(3)
	v_cvt_pk_bf16_f32 v0, v0, v1
	s_waitcnt lgkmcnt(2)
	v_cvt_pk_bf16_f32 v1, v2, v3
	s_waitcnt lgkmcnt(1)
	v_cvt_pk_bf16_f32 v2, v4, v5
	v_lshl_add_u32 v4, s1, 6, v19
	v_ashrrev_i32_e32 v5, 31, v4
	v_readlane_b32 s6, v251, 56
	s_lshl_b32 s2, s2, 6
	v_readlane_b32 s3, v253, 46
	v_lshlrev_b64 v[4:5], 11, v[4:5]
	v_readlane_b32 s7, v251, 57
	s_add_i32 s0, s0, s3
	s_ashr_i32 s3, s2, 31
	v_lshl_add_u64 v[4:5], s[6:7], 0, v[4:5]
	v_lshl_add_u64 v[4:5], s[2:3], 1, v[4:5]
	s_waitcnt lgkmcnt(0)
	v_cvt_pk_bf16_f32 v3, v6, v7
	v_lshl_add_u64 v[4:5], v[4:5], 0, v[50:51]
	global_store_dwordx4 v[4:5], v[0:3], off sc1
	s_cmpk_lt_i32 s0, 0xbc0
	s_nop 0
	v_mov_b64_e32 v[0:1], v[8:9]
	v_mov_b64_e32 v[2:3], v[10:11]
	v_mov_b64_e32 v[4:5], v[12:13]
	v_mov_b64_e32 v[6:7], v[14:15]
	s_barrier
	s_cbranch_scc0 .LBB0_1315

.LBB0_1417:
	s_or_b64 exec, exec, s[2:3]
	s_waitcnt vmcnt(0)
	v_cvt_f32_f16_e32 v75, v52
	v_cvt_f32_f16_sdwa v76, v52 dst_sel:DWORD dst_unused:UNUSED_PAD src0_sel:WORD_1
	v_cvt_f32_f16_e32 v77, v53
	v_cvt_f32_f16_sdwa v78, v53 dst_sel:DWORD dst_unused:UNUSED_PAD src0_sel:WORD_1
	v_cvt_f32_f16_e32 v66, v40
	v_cvt_f32_f16_sdwa v67, v40 dst_sel:DWORD dst_unused:UNUSED_PAD src0_sel:WORD_1
	v_cvt_f32_f16_e32 v68, v41
	v_cvt_f32_f16_sdwa v69, v41 dst_sel:DWORD dst_unused:UNUSED_PAD src0_sel:WORD_1
	v_cvt_f32_f16_sdwa v41, v42 dst_sel:DWORD dst_unused:UNUSED_PAD src0_sel:WORD_1
	v_cvt_f32_f16_e32 v40, v42
	v_cvt_f32_f16_sdwa v53, v43 dst_sel:DWORD dst_unused:UNUSED_PAD src0_sel:WORD_1
	v_cvt_f32_f16_e32 v52, v43
	v_cvt_f32_f16_sdwa v43, v34 dst_sel:DWORD dst_unused:UNUSED_PAD src0_sel:WORD_1
	v_cvt_f32_f16_e32 v42, v34
	v_cvt_f32_f16_e32 v34, v28
	v_cvt_f32_f16_sdwa v28, v28 dst_sel:DWORD dst_unused:UNUSED_PAD src0_sel:WORD_1
	v_cvt_f32_f16_e32 v79, v54
	v_cvt_f32_f16_sdwa v80, v54 dst_sel:DWORD dst_unused:UNUSED_PAD src0_sel:WORD_1
	v_cvt_f32_f16_e32 v81, v55
	v_cvt_f32_f16_sdwa v82, v55 dst_sel:DWORD dst_unused:UNUSED_PAD src0_sel:WORD_1
	v_cvt_f32_f16_sdwa v55, v35 dst_sel:DWORD dst_unused:UNUSED_PAD src0_sel:WORD_1
	v_cvt_f32_f16_e32 v54, v35
	v_cvt_f32_f16_e32 v35, v29
	v_cvt_f32_f16_sdwa v29, v29 dst_sel:DWORD dst_unused:UNUSED_PAD src0_sel:WORD_1
	v_add_f32_e32 v28, v67, v28
	v_fma_mix_f32 v28, v28, s76, -v32 op_sel:[0,0,1] op_sel_hi:[0,0,1]
	v_fma_mix_f32 v84, v45, v28, v32 op_sel:[0,0,1] op_sel_hi:[0,0,1]
	v_add_f32_e32 v28, v68, v35
	v_fma_mix_f32 v28, v28, s76, -v33 op_sel_hi:[0,0,1]
	v_fma_mix_f32 v35, v46, v28, v33 op_sel_hi:[0,0,1]
	v_add_f32_e32 v28, v69, v29
	v_fma_mix_f32 v28, v28, s76, -v33 op_sel:[0,0,1] op_sel_hi:[0,0,1]
	v_fma_mix_f32 v33, v47, v28, v33 op_sel:[0,0,1] op_sel_hi:[0,0,1]
	v_cvt_f32_f16_sdwa v29, v30 dst_sel:DWORD dst_unused:UNUSED_PAD src0_sel:WORD_1
	v_cvt_f32_f16_e32 v28, v30
	v_add_f32_e32 v34, v66, v34
	v_fma_mix_f32 v34, v34, s76, -v32 op_sel_hi:[0,0,1]
	v_fma_mix_f32 v83, v44, v34, v32 op_sel_hi:[0,0,1]
	v_pk_add_f32 v[28:29], v[40:41], v[28:29]
	v_cvt_f32_f16_e32 v30, v22
	v_pk_fma_f32 v[28:29], v[28:29], 0.5, v[42:43] op_sel_hi:[1,0,1] neg_lo:[0,0,1] neg_hi:[0,0,1]
	v_cvt_f32_f16_sdwa v34, v22 dst_sel:DWORD dst_unused:UNUSED_PAD src0_sel:WORD_1
	v_pk_fma_f32 v[66:67], v[28:29], v[36:37], v[42:43]
	v_cvt_f32_f16_sdwa v29, v31 dst_sel:DWORD dst_unused:UNUSED_PAD src0_sel:WORD_1
	v_cvt_f32_f16_e32 v28, v31
	v_cvt_f32_f16_e32 v32, v23
	v_cvt_f32_f16_sdwa v31, v8 dst_sel:DWORD dst_unused:UNUSED_PAD src0_sel:WORD_1
	v_cvt_f32_f16_e32 v37, v9
	v_pk_add_f32 v[28:29], v[52:53], v[28:29]
	v_cvt_f32_f16_e32 v22, v11
	v_pk_fma_f32 v[28:29], v[28:29], 0.5, v[54:55] op_sel_hi:[1,0,1] neg_lo:[0,0,1] neg_hi:[0,0,1]
	v_cvt_f32_f16_sdwa v45, v3 dst_sel:DWORD dst_unused:UNUSED_PAD src0_sel:WORD_1
	v_pk_fma_f32 v[68:69], v[28:29], v[38:39], v[54:55]
	v_cvt_f32_f16_sdwa v28, v23 dst_sel:DWORD dst_unused:UNUSED_PAD src0_sel:WORD_1
	v_cvt_f32_f16_e32 v29, v8
	v_cvt_f32_f16_sdwa v39, v9 dst_sel:DWORD dst_unused:UNUSED_PAD src0_sel:WORD_1
	v_cvt_f32_f16_sdwa v9, v10 dst_sel:DWORD dst_unused:UNUSED_PAD src0_sel:WORD_1
	v_cvt_f32_f16_e32 v8, v10
	v_cvt_f32_f16_sdwa v23, v11 dst_sel:DWORD dst_unused:UNUSED_PAD src0_sel:WORD_1
	v_cvt_f32_f16_sdwa v11, v2 dst_sel:DWORD dst_unused:UNUSED_PAD src0_sel:WORD_1
	v_cvt_f32_f16_e32 v10, v2
	v_cvt_f32_f16_e32 v2, v4
	v_cvt_f32_f16_e32 v44, v3
	v_cvt_f32_f16_sdwa v3, v4 dst_sel:DWORD dst_unused:UNUSED_PAD src0_sel:WORD_1
	v_cvt_f32_f16_e32 v4, v5
	v_add_f32_e32 v2, v29, v2
	v_fma_mix_f32 v2, v2, s76, -v0 op_sel_hi:[0,0,1]
	v_cvt_f32_f16_sdwa v5, v5 dst_sel:DWORD dst_unused:UNUSED_PAD src0_sel:WORD_1
	v_fma_mix_f32 v16, v16, v2, v0 op_sel_hi:[0,0,1]
	v_add_f32_e32 v2, v31, v3
	v_fma_mix_f32 v2, v2, s76, -v0 op_sel:[0,0,1] op_sel_hi:[0,0,1]
	v_fma_mix_f32 v29, v17, v2, v0 op_sel:[0,0,1] op_sel_hi:[0,0,1]
	v_add_f32_e32 v0, v37, v4
	v_fma_mix_f32 v0, v0, s76, -v1 op_sel_hi:[0,0,1]
	v_fma_mix_f32 v37, v18, v0, v1 op_sel_hi:[0,0,1]
	v_add_f32_e32 v0, v39, v5
	v_fma_mix_f32 v0, v0, s76, -v1 op_sel:[0,0,1] op_sel_hi:[0,0,1]
	v_fma_mix_f32 v39, v19, v0, v1 op_sel:[0,0,1] op_sel_hi:[0,0,1]
	v_cvt_f32_f16_sdwa v1, v6 dst_sel:DWORD dst_unused:UNUSED_PAD src0_sel:WORD_1
	v_cvt_f32_f16_e32 v0, v6
	s_mov_b32 s1, 0x800000
	v_cvt_f32_f16_e32 v17, v26
	v_cvt_f32_f16_sdwa v18, v26 dst_sel:DWORD dst_unused:UNUSED_PAD src0_sel:WORD_1
	v_pk_add_f32 v[0:1], v[8:9], v[0:1]
	v_cvt_f32_f16_e32 v19, v27
	v_pk_fma_f32 v[0:1], v[0:1], 0.5, v[10:11] op_sel_hi:[1,0,1] neg_lo:[0,0,1] neg_hi:[0,0,1]
	v_readlane_b32 s8, v251, 34
	v_pk_fma_f32 v[8:9], v[0:1], v[12:13], v[10:11]
	v_cvt_f32_f16_sdwa v1, v7 dst_sel:DWORD dst_unused:UNUSED_PAD src0_sel:WORD_1
	v_cvt_f32_f16_e32 v0, v7
	v_cvt_f32_f16_e32 v12, v24
	v_cvt_f32_f16_sdwa v13, v24 dst_sel:DWORD dst_unused:UNUSED_PAD src0_sel:WORD_1
	v_readlane_b32 s12, v251, 38
	v_pk_add_f32 v[0:1], v[22:23], v[0:1]
	v_add_f32_e32 v12, v75, v12
	v_pk_fma_f32 v[0:1], v[0:1], 0.5, v[44:45] op_sel_hi:[1,0,1] neg_lo:[0,0,1] neg_hi:[0,0,1]
	v_fma_mix_f32 v54, v12, s76, -v20 op_sel_hi:[0,0,1]
	v_pk_fma_f32 v[10:11], v[0:1], v[14:15], v[44:45]
	v_cvt_f32_f16_e32 v14, v25
	v_add_f32_e32 v0, v73, v74
	v_cvt_f32_f16_sdwa v15, v25 dst_sel:DWORD dst_unused:UNUSED_PAD src0_sel:WORD_1
	v_fmamk_f32 v0, v0, 0x3c800000, v247
	v_cmp_gt_f32_e32 vcc, s1, v0
	v_mul_f32_e32 v1, 0x4b800000, v0
	v_add_f32_e32 v12, v76, v13
	v_cndmask_b32_e32 v0, v0, v1, vcc
	v_fma_mix_f32 v52, v12, s76, -v20 op_sel:[0,0,1] op_sel_hi:[0,0,1]
	v_add_f32_e32 v12, v77, v14
	v_rsq_f32_e32 v0, v0
	v_cvt_f32_f16_sdwa v22, v27 dst_sel:DWORD dst_unused:UNUSED_PAD src0_sel:WORD_1
	v_fma_mix_f32 v46, v12, s76, -v21 op_sel_hi:[0,0,1]
	v_add_f32_e32 v12, v78, v15
	v_fma_mix_f32 v44, v12, s76, -v21 op_sel:[0,0,1] op_sel_hi:[0,0,1]
	v_add_f32_e32 v12, v79, v17
	v_mul_f32_e32 v26, 0.5, v12
	v_add_f32_e32 v12, v80, v18
	v_mul_f32_e32 v25, 0.5, v12
	v_add_f32_e32 v12, v81, v19
	v_mul_f32_e32 v1, 0x45800000, v0
	v_mul_f32_e32 v24, 0.5, v12
	v_add_f32_e32 v12, v82, v22
	v_readlane_b32 s1, v255, 9
	v_cndmask_b32_e32 v31, v0, v1, vcc
	global_load_dwordx4 v[0:3], v[70:71], off offset:3088
	global_load_dwordx4 v[4:7], v[70:71], off offset:3072
	v_mul_f32_e32 v70, 0.5, v12
	v_add_u32_e32 v12, s1, v64
	v_readlane_b32 s13, v251, 39
	v_readlane_b32 s14, v251, 40
	v_readlane_b32 s15, v251, 41
	v_readlane_b32 s16, v251, 42
	v_readlane_b32 s17, v251, 43
	v_readlane_b32 s18, v251, 44
	v_readlane_b32 s19, v251, 45
	v_ashrrev_i32_e32 v13, 31, v12
	v_readlane_b32 s20, v251, 46
	v_readlane_b32 s21, v251, 47
	v_readlane_b32 s22, v251, 48
	v_readlane_b32 s23, v251, 49
	s_mov_b64 s[12:13], s[16:17]
	v_cvt_f32_f16_e32 v42, v20
	v_cvt_f32_f16_sdwa v40, v20 dst_sel:DWORD dst_unused:UNUSED_PAD src0_sel:WORD_1
	v_cvt_f32_f16_e32 v38, v21
	v_cvt_f32_f16_sdwa v36, v21 dst_sel:DWORD dst_unused:UNUSED_PAD src0_sel:WORD_1
	v_lshlrev_b64 v[20:21], 2, v[12:13]
	s_mov_b64 s[14:15], s[18:19]
	s_mov_b64 s[16:17], s[20:21]
	v_mul_f32_e32 v22, v16, v83
	v_lshl_add_u64 v[16:17], s[16:17], 0, v[20:21]
	global_load_dwordx4 v[12:15], v[16:17], off
	s_nop 0
	global_load_dwordx4 v[16:19], v[16:17], off offset:16
	v_pk_mul_f32 v[8:9], v[8:9], v[66:67]
	v_ashrrev_i32_e32 v63, 31, v62
	s_mov_b32 s1, 0x2c00000
	s_mov_b64 s[18:19], s[22:23]
	v_mul_f32_e32 v53, v61, v31
	v_mul_f32_e32 v47, v59, v31
	v_mul_f32_e32 v55, v60, v31
	v_mul_f32_e32 v45, v58, v31
	s_add_i32 s0, s0, s82
	s_cmpk_lt_i32 s0, 0x6000
	v_readlane_b32 s9, v251, 35
	v_readlane_b32 s10, v251, 36
	v_readlane_b32 s11, v251, 37
	s_waitcnt vmcnt(1)
	v_fma_f32 v12, v22, v12, 0
	v_mul_f32_e32 v22, v29, v84
	v_fmac_f32_e32 v12, v22, v13
	v_mul_f32_e32 v13, v37, v35
	v_fmac_f32_e32 v12, v13, v14
	v_mul_f32_e32 v13, v39, v33
	v_fmac_f32_e32 v12, v13, v15
	s_waitcnt vmcnt(0)
	v_pk_mul_f32 v[8:9], v[8:9], v[16:17]
	s_nop 0
	v_add_f32_e32 v8, v12, v8
	v_add_f32_e32 v12, v8, v9
	v_pk_mul_f32 v[8:9], v[10:11], v[68:69]
	s_nop 0
	v_pk_mul_f32 v[8:9], v[8:9], v[18:19]
	s_nop 0
	v_add_f32_e32 v8, v12, v8
	v_add_f32_e32 v8, v8, v9
	v_lshl_add_u64 v[12:13], s[18:19], 0, v[20:21]
	v_lshl_add_u64 v[20:21], s[88:89], 0, v[20:21]
	v_add_f32_dpp v8, v8, v8 quad_perm:[1,0,3,2] row_mask:0xf bank_mask:0xf bound_ctrl:1
	s_nop 1
	v_add_f32_dpp v8, v8, v8 quad_perm:[2,3,0,1] row_mask:0xf bank_mask:0xf bound_ctrl:1
	s_nop 1
	v_add_f32_dpp v66, v8, v8 row_half_mirror row_mask:0xf bank_mask:0xf bound_ctrl:1
	v_lshlrev_b64 v[8:9], 11, v[62:63]
	v_lshl_add_u64 v[8:9], s[92:93], 0, v[8:9]
	v_lshl_add_u64 v[8:9], v[64:65], 1, v[8:9]
	v_add_co_u32_e32 v62, vcc, s1, v8
	v_mov_b32_e32 v64, v4
	s_nop 0
	v_addc_co_u32_e32 v63, vcc, 0, v9, vcc
	global_load_dwordx4 v[8:11], v[62:63], off offset:1280
	v_readlane_b32 s1, v254, 9
	s_waitcnt vmcnt(0)
	v_lshlrev_b32_e32 v27, 16, v8
	v_and_b32_e32 v29, 0xffff0000, v8
	v_lshlrev_b32_e32 v33, 16, v9
	v_and_b32_e32 v35, 0xffff0000, v9
	v_lshlrev_b32_e32 v67, 16, v10
	v_and_b32_e32 v68, 0xffff0000, v10
	v_lshlrev_b32_e32 v69, 16, v11
	v_and_b32_e32 v71, 0xffff0000, v11
	global_load_dwordx4 v[8:11], v[12:13], off offset:16
	global_load_dwordx4 v[16:19], v[12:13], off
	s_nop 0
	global_load_dwordx4 v[12:15], v[20:21], off offset:16
	s_nop 0
	global_load_dwordx4 v[20:23], v[20:21], off
	v_add_u32_e32 v72, s1, v72
	s_waitcnt vmcnt(2)
	v_mov_b32_e32 v65, v16
	v_mov_b32_e32 v16, v5
	s_waitcnt vmcnt(0)
	v_mov_b32_e32 v41, v21
	v_pk_fma_f32 v[4:5], v[16:17], v[52:53], v[40:41]
	v_mov_b32_e32 v39, v22
	v_fmac_f32_e32 v5, v4, v66
	v_mul_f32_e32 v21, v5, v29
	v_mov_b32_e32 v4, v6
	v_mov_b32_e32 v5, v18
	v_mov_b32_e32 v43, v20
	v_pk_fma_f32 v[4:5], v[4:5], v[46:47], v[38:39]
	v_pk_fma_f32 v[42:43], v[64:65], v[54:55], v[42:43]
	v_fmac_f32_e32 v5, v4, v66
	v_mov_b32_e32 v18, v7
	v_mov_b32_e32 v37, v23
	v_fmac_f32_e32 v43, v42, v66
	v_mul_f32_e32 v22, v5, v33
	v_pk_fma_f32 v[4:5], v[18:19], v[44:45], v[36:37]
	v_mul_f32_e32 v20, v43, v27
	v_fmac_f32_e32 v5, v4, v66
	v_mov_b32_e32 v27, v57
	v_mul_f32_e32 v18, v5, v35
	v_pk_add_f32 v[4:5], v[26:27], v[30:31] neg_lo:[0,1] neg_hi:[0,1]
	v_pk_mul_f32 v[6:7], v[56:57], v[30:31]
	v_mov_b32_e32 v16, v30
	v_mov_b32_e32 v5, v7
	v_mov_b32_e32 v6, v0
	v_mov_b32_e32 v7, v8
	v_mov_b32_e32 v17, v12
	v_pk_fma_f32 v[4:5], v[4:5], v[6:7], v[16:17]
	v_mov_b32_e32 v35, v31
	v_fmac_f32_e32 v5, v4, v66
	v_pk_mul_f32 v[6:7], v[56:57], v[34:35] op_sel_hi:[0,1]
	v_mul_f32_e32 v12, v5, v67
	v_sub_f32_e32 v4, v25, v34
	v_mov_b32_e32 v5, v7
	v_mov_b32_e32 v8, v1
	v_mov_b32_e32 v35, v13
	v_pk_fma_f32 v[0:1], v[4:5], v[8:9], v[34:35]
	v_mov_b32_e32 v25, v49
	v_fmac_f32_e32 v1, v0, v66
	v_mov_b32_e32 v33, v31
	v_mul_f32_e32 v6, v1, v68
	v_pk_add_f32 v[0:1], v[24:25], v[32:33] neg_lo:[0,1] neg_hi:[0,1]
	v_pk_mul_f32 v[4:5], v[48:49], v[32:33]
	v_mov_b32_e32 v33, v14
	v_mov_b32_e32 v1, v5
	v_mov_b32_e32 v4, v2
	v_mov_b32_e32 v5, v10
	v_pk_fma_f32 v[0:1], v[0:1], v[4:5], v[32:33]
	v_mov_b32_e32 v29, v31
	v_fmac_f32_e32 v1, v0, v66
	v_pk_mul_f32 v[4:5], v[48:49], v[28:29] op_sel_hi:[0,1]
	v_mul_f32_e32 v7, v1, v69
	v_sub_f32_e32 v0, v70, v28
	v_mov_b32_e32 v1, v5
	v_mov_b32_e32 v10, v3
	v_mov_b32_e32 v29, v15
	v_pk_fma_f32 v[0:1], v[0:1], v[10:11], v[28:29]
	s_nop 0
	v_fmac_f32_e32 v1, v0, v66
	v_mul_f32_e32 v3, v1, v71
	v_cvt_pk_bf16_f32 v0, v20, v21
	v_cvt_pk_bf16_f32 v1, v22, v18
	v_cvt_pk_bf16_f32 v2, v12, v6
	v_cvt_pk_bf16_f32 v3, v7, v3
	global_store_dwordx4 v[62:63], v[0:3], off offset:1280 sc1
	s_cbranch_scc0 .LBB0_1430

.LBB0_1541:
	v_readlane_b32 s60, v251, 2
	v_lshlrev_b64 v[16:17], 10, v[208:209]
	s_and_b64 s[22:23], s[46:47], exec
	v_readlane_b32 s61, v251, 3
	s_cselect_b32 s13, s60, s81
	s_cselect_b32 s35, s61, s84
	s_and_b64 s[22:23], exec, s[26:27]
	v_lshl_add_u64 v[16:17], v[16:17], 0, v[14:15]
	s_cselect_b32 s27, s35, s91
	s_cselect_b32 s26, s13, s90
	v_lshlrev_b64 v[48:49], 2, v[16:17]
	v_lshl_add_u64 v[22:23], s[26:27], 0, v[48:49]
	global_load_dwordx4 v[32:35], v[22:23], off
	v_mov_b32_e32 v16, v9
	v_mov_b32_e32 v17, v202
	v_lshlrev_b64 v[20:21], 10, v[214:215]
	s_waitcnt vmcnt(1)
	v_pk_add_f32 v[12:13], v[12:13], 1.0 op_sel_hi:[1,0]
	v_pk_add_f32 v[10:11], v[10:11], 1.0 op_sel_hi:[1,0]
	v_lshl_add_u64 v[20:21], v[20:21], 0, v[14:15]
	v_lshlrev_b64 v[20:21], 2, v[20:21]
	v_lshl_add_u64 v[28:29], s[90:91], 0, v[48:49]
	v_lshl_add_u64 v[30:31], s[26:27], 0, v[20:21]
	s_mov_b64 s[8:9], 0x80000
	s_and_b64 vcc, exec, s[40:41]
	v_mov_b32_e32 v211, 1.0
	v_mov_b32_e32 v213, 0
	v_readlane_b32 s62, v251, 4
	v_readlane_b32 s63, v251, 5
	v_readlane_b32 s64, v251, 6
	v_readlane_b32 s65, v251, 7
	v_readlane_b32 s66, v251, 8
	v_readlane_b32 s67, v251, 9
	v_readlane_b32 s68, v251, 10
	v_readlane_b32 s69, v251, 11
	v_readlane_b32 s70, v251, 12
	v_readlane_b32 s71, v251, 13
	v_readlane_b32 s72, v251, 14
	v_readlane_b32 s73, v251, 15
	v_readlane_b32 s74, v251, 16
	v_readlane_b32 s75, v251, 17
	s_waitcnt vmcnt(0)
	v_sub_f32_e32 v33, v33, v0
	v_sub_f32_e32 v32, v32, v0
	v_sub_f32_e32 v35, v35, v0
	v_sub_f32_e32 v34, v34, v0
	v_pk_mul_f32 v[34:35], v[16:17], v[34:35] op_sel_hi:[0,1]
	v_pk_mul_f32 v[32:33], v[16:17], v[32:33] op_sel_hi:[0,1]
	v_pk_fma_f32 v[32:33], v[222:223], v[32:33], v[226:227]
	v_pk_fma_f32 v[34:35], v[220:221], v[34:35], v[224:225]
	v_pk_fma_f32 v[32:33], v[176:177], v[10:11], v[32:33]
	v_pk_fma_f32 v[34:35], v[178:179], v[12:13], v[34:35]
	global_store_dwordx4 v[28:29], v[32:35], off sc1
	global_load_dwordx4 v[38:41], v[30:31], off
	s_nop 0
	v_lshlrev_b64 v[32:33], 10, v[216:217]
	v_lshl_add_u64 v[32:33], v[32:33], 0, v[14:15]
	v_lshlrev_b64 v[34:35], 2, v[32:33]
	v_lshl_add_u64 v[32:33], s[90:91], 0, v[20:21]
	v_lshl_add_u64 v[36:37], s[26:27], 0, v[34:35]
	s_waitcnt vmcnt(0)
	v_sub_f32_e32 v21, v39, v1
	v_sub_f32_e32 v20, v38, v1
	v_sub_f32_e32 v39, v41, v1
	v_sub_f32_e32 v38, v40, v1
	v_pk_mul_f32 v[38:39], v[16:17], v[38:39] op_sel:[1,0]
	v_pk_mul_f32 v[20:21], v[16:17], v[20:21] op_sel:[1,0]
	v_pk_fma_f32 v[38:39], v[220:221], v[38:39], v[224:225]
	v_pk_fma_f32 v[20:21], v[222:223], v[20:21], v[226:227]
	v_pk_fma_f32 v[40:41], v[174:175], v[12:13], v[38:39]
	v_pk_fma_f32 v[38:39], v[172:173], v[10:11], v[20:21]
	global_store_dwordx4 v[32:33], v[38:41], off sc1
	global_load_dwordx4 v[172:175], v[36:37], off
	v_mov_b32_e32 v20, v207
	v_mov_b32_e32 v21, v204
	v_lshl_add_u64 v[40:41], s[90:91], 0, v[34:35]
	v_lshlrev_b64 v[38:39], 10, v[218:219]
	v_lshl_add_u64 v[38:39], v[38:39], 0, v[14:15]
	v_lshlrev_b64 v[38:39], 2, v[38:39]
	v_lshl_add_u64 v[46:47], s[26:27], 0, v[38:39]
	v_lshl_add_u64 v[38:39], s[90:91], 0, v[38:39]
	s_waitcnt vmcnt(0)
	v_sub_f32_e32 v35, v173, v2
	v_sub_f32_e32 v34, v172, v2
	v_sub_f32_e32 v173, v175, v2
	v_sub_f32_e32 v172, v174, v2
	v_pk_mul_f32 v[172:173], v[20:21], v[172:173] op_sel_hi:[0,1]
	v_pk_mul_f32 v[34:35], v[20:21], v[34:35] op_sel_hi:[0,1]
	v_pk_fma_f32 v[34:35], v[222:223], v[34:35], v[226:227]
	v_pk_fma_f32 v[172:173], v[220:221], v[172:173], v[224:225]
	v_pk_fma_f32 v[168:169], v[168:169], v[10:11], v[34:35]
	v_pk_fma_f32 v[170:171], v[170:171], v[12:13], v[172:173]
	global_store_dwordx4 v[40:41], v[168:171], off sc1
	global_load_dwordx4 v[168:171], v[46:47], off
	v_lshl_add_u64 v[172:173], v[48:49], 0, s[8:9]
	v_lshl_add_u64 v[48:49], s[26:27], 0, v[172:173]
	s_waitcnt vmcnt(0)
	v_sub_f32_e32 v35, v169, v3
	v_sub_f32_e32 v34, v168, v3
	v_sub_f32_e32 v169, v171, v3
	v_sub_f32_e32 v168, v170, v3
	v_pk_mul_f32 v[168:169], v[204:205], v[168:169] op_sel_hi:[0,1]
	v_pk_mul_f32 v[34:35], v[204:205], v[34:35] op_sel_hi:[0,1]
	v_pk_fma_f32 v[34:35], v[222:223], v[34:35], v[226:227]
	v_pk_fma_f32 v[168:169], v[220:221], v[168:169], v[224:225]
	v_pk_fma_f32 v[164:165], v[164:165], v[10:11], v[34:35]
	v_pk_fma_f32 v[166:167], v[166:167], v[12:13], v[168:169]
	global_store_dwordx4 v[38:39], v[164:167], off sc1
	global_load_dwordx4 v[168:171], v[48:49], off
	v_mov_b32_e32 v34, v45
	v_add_u32_e32 v164, 0x90, v208
	v_mov_b32_e32 v35, v42
	v_ashrrev_i32_e32 v165, 31, v164
	v_lshlrev_b64 v[164:165], 10, v[164:165]
	v_lshl_add_u64 v[166:167], v[164:165], 0, v[14:15]
	v_lshl_add_u64 v[164:165], s[90:91], 0, v[172:173]
	v_lshlrev_b64 v[172:173], 2, v[166:167]
	v_lshl_add_u64 v[166:167], s[26:27], 0, v[172:173]
	s_waitcnt vmcnt(0)
	v_sub_f32_e32 v169, v169, v4
	v_sub_f32_e32 v168, v168, v4
	v_sub_f32_e32 v171, v171, v4
	v_sub_f32_e32 v170, v170, v4
	v_pk_mul_f32 v[170:171], v[34:35], v[170:171] op_sel_hi:[0,1]
	v_pk_mul_f32 v[168:169], v[34:35], v[168:169] op_sel_hi:[0,1]
	v_pk_fma_f32 v[168:169], v[222:223], v[168:169], v[226:227]
	v_pk_fma_f32 v[170:171], v[220:221], v[170:171], v[224:225]
	v_pk_fma_f32 v[160:161], v[160:161], v[10:11], v[168:169]
	v_pk_fma_f32 v[162:163], v[162:163], v[12:13], v[170:171]
	global_store_dwordx4 v[164:165], v[160:163], off sc1
	global_load_dwordx4 v[168:171], v[166:167], off
	s_waitcnt vmcnt(0)
	v_sub_f32_e32 v169, v169, v5
	v_add_u32_e32 v160, 0xa0, v208
	v_ashrrev_i32_e32 v161, 31, v160
	v_sub_f32_e32 v168, v168, v5
	v_sub_f32_e32 v171, v171, v5
	v_sub_f32_e32 v170, v170, v5
	v_lshlrev_b64 v[160:161], 10, v[160:161]
	v_pk_mul_f32 v[170:171], v[42:43], v[170:171] op_sel_hi:[0,1]
	v_pk_mul_f32 v[168:169], v[42:43], v[168:169] op_sel_hi:[0,1]
	v_lshl_add_u64 v[160:161], v[160:161], 0, v[14:15]
	v_pk_fma_f32 v[168:169], v[222:223], v[168:169], v[226:227]
	v_pk_fma_f32 v[170:171], v[220:221], v[170:171], v[224:225]
	v_lshlrev_b64 v[174:175], 2, v[160:161]
	v_lshl_add_u64 v[160:161], s[90:91], 0, v[172:173]
	v_pk_fma_f32 v[158:159], v[158:159], v[12:13], v[170:171]
	v_pk_fma_f32 v[156:157], v[156:157], v[10:11], v[168:169]
	v_lshl_add_u64 v[162:163], s[26:27], 0, v[174:175]
	global_store_dwordx4 v[160:161], v[156:159], off sc1
	global_load_dwordx4 v[168:171], v[162:163], off
	s_waitcnt vmcnt(0)
	v_sub_f32_e32 v169, v169, v6
	v_add_u32_e32 v156, 0xb0, v208
	v_ashrrev_i32_e32 v157, 31, v156
	v_sub_f32_e32 v168, v168, v6
	v_sub_f32_e32 v171, v171, v6
	v_sub_f32_e32 v170, v170, v6
	v_lshlrev_b64 v[156:157], 10, v[156:157]
	v_pk_mul_f32 v[170:171], v[24:25], v[170:171] op_sel_hi:[0,1]
	v_pk_mul_f32 v[168:169], v[24:25], v[168:169] op_sel_hi:[0,1]
	v_lshl_add_u64 v[156:157], v[156:157], 0, v[14:15]
	v_pk_fma_f32 v[168:169], v[222:223], v[168:169], v[226:227]
	v_pk_fma_f32 v[170:171], v[220:221], v[170:171], v[224:225]
	v_lshlrev_b64 v[172:173], 2, v[156:157]
	v_lshl_add_u64 v[156:157], s[90:91], 0, v[174:175]
	v_pk_fma_f32 v[154:155], v[154:155], v[12:13], v[170:171]
	v_pk_fma_f32 v[152:153], v[152:153], v[10:11], v[168:169]
	v_lshl_add_u64 v[158:159], s[26:27], 0, v[172:173]
	global_store_dwordx4 v[156:157], v[152:155], off sc1
	global_load_dwordx4 v[168:171], v[158:159], off
	s_nop 0
	v_lshl_add_u64 v[152:153], s[90:91], 0, v[172:173]
	s_waitcnt vmcnt(0)
	v_sub_f32_e32 v155, v169, v7
	v_sub_f32_e32 v154, v168, v7
	v_sub_f32_e32 v169, v171, v7
	v_sub_f32_e32 v168, v170, v7
	v_pk_mul_f32 v[168:169], v[26:27], v[168:169] op_sel_hi:[0,1]
	v_pk_mul_f32 v[154:155], v[26:27], v[154:155] op_sel_hi:[0,1]
	v_pk_fma_f32 v[154:155], v[222:223], v[154:155], v[226:227]
	v_pk_fma_f32 v[168:169], v[220:221], v[168:169], v[224:225]
	v_pk_fma_f32 v[10:11], v[148:149], v[10:11], v[154:155]
	v_pk_fma_f32 v[12:13], v[150:151], v[12:13], v[168:169]
	global_store_dwordx4 v[152:153], v[10:13], off sc1
	global_load_dwordx4 v[10:13], v[18:19], off offset:64
	v_mov_b32_e32 v150, 1.0
	v_mov_b32_e32 v151, 1.0
	v_mov_b32_e32 v154, 0
	v_mov_b32_e32 v155, 0
	s_cbranch_vccnz .LBB0_1543
	v_lshlrev_b64 v[154:155], 2, v[14:15]
	v_lshl_add_u64 v[148:149], s[48:49], 0, v[154:155]
	v_lshl_add_u64 v[154:155], s[50:51], 0, v[154:155]
	global_load_dwordx4 v[148:151], v[148:149], off offset:64
	s_waitcnt vmcnt(0)
	v_pk_mul_f32 v[150:151], v[150:151], s[28:29] op_sel_hi:[1,0]
	global_load_dwordx4 v[168:171], v[154:155], off offset:64
	v_pk_mul_f32 v[210:211], v[148:149], s[28:29] op_sel_hi:[1,0]
	s_waitcnt vmcnt(0)
	v_pk_mul_f32 v[154:155], v[170:171], s[28:29] op_sel_hi:[1,0]
	v_pk_mul_f32 v[212:213], v[168:169], s[28:29] op_sel_hi:[1,0]
.LBB0_1543:
	global_load_dwordx4 v[168:171], v[22:23], off offset:64
	v_mov_b32_e32 v8, v16
	s_waitcnt vmcnt(1)
	v_pk_add_f32 v[172:173], v[12:13], 1.0 op_sel_hi:[1,0]
	v_pk_add_f32 v[174:175], v[10:11], 1.0 op_sel_hi:[1,0]
	v_mov_b32_e32 v148, v16
	v_mov_b32_e32 v149, v9
	v_mov_b32_e32 v203, v17
	v_mov_b32_e32 v206, v20
	v_mov_b32_e32 v205, v21
	v_mov_b32_e32 v44, v34
	v_mov_b32_e32 v43, v35
	v_mov_b32_e32 v25, v24
	v_mov_b32_e32 v27, v26
	v_readlane_b32 s70, v255, 18
	s_and_b64 vcc, exec, s[40:41]
	s_movk_i32 s60, 0x306
	s_movk_i32 s61, 0x5a
	s_movk_i32 s62, 0xa5
	s_movk_i32 s63, 0x130
	s_movk_i32 s66, 0x22e
	s_movk_i32 s67, 0x210
	s_movk_i32 s68, 0x1000
	v_readlane_b32 s71, v255, 19
	s_waitcnt vmcnt(0)
	v_sub_f32_e32 v11, v169, v0
	v_sub_f32_e32 v10, v168, v0
	v_sub_f32_e32 v13, v171, v0
	v_sub_f32_e32 v12, v170, v0
	v_pk_mul_f32 v[12:13], v[148:149], v[12:13]
	v_pk_mul_f32 v[10:11], v[8:9], v[10:11]
	v_pk_fma_f32 v[12:13], v[150:151], v[12:13], v[154:155]
	v_pk_fma_f32 v[10:11], v[210:211], v[10:11], v[212:213]
	v_pk_fma_f32 v[12:13], v[146:147], v[172:173], v[12:13]
	v_pk_fma_f32 v[10:11], v[144:145], v[174:175], v[10:11]
	global_store_dwordx4 v[28:29], v[10:13], off offset:64 sc1
	global_load_dwordx4 v[10:13], v[30:31], off offset:64
	v_mov_b32_e32 v144, v202
	v_mov_b32_e32 v145, v17
	s_waitcnt vmcnt(0)
	v_sub_f32_e32 v11, v11, v1
	v_sub_f32_e32 v10, v10, v1
	v_sub_f32_e32 v13, v13, v1
	v_sub_f32_e32 v12, v12, v1
	v_pk_mul_f32 v[12:13], v[144:145], v[12:13]
	v_pk_mul_f32 v[10:11], v[202:203], v[10:11]
	v_pk_fma_f32 v[12:13], v[150:151], v[12:13], v[154:155]
	v_pk_fma_f32 v[10:11], v[210:211], v[10:11], v[212:213]
	v_pk_fma_f32 v[12:13], v[142:143], v[172:173], v[12:13]
	v_pk_fma_f32 v[10:11], v[140:141], v[174:175], v[10:11]
	global_store_dwordx4 v[32:33], v[10:13], off offset:64 sc1
	global_load_dwordx4 v[10:13], v[36:37], off offset:64
	v_mov_b32_e32 v140, v20
	v_mov_b32_e32 v141, v207
	s_waitcnt vmcnt(0)
	v_sub_f32_e32 v11, v11, v2
	v_sub_f32_e32 v10, v10, v2
	v_sub_f32_e32 v13, v13, v2
	v_sub_f32_e32 v12, v12, v2
	v_pk_mul_f32 v[12:13], v[140:141], v[12:13]
	v_pk_mul_f32 v[10:11], v[206:207], v[10:11]
	v_pk_fma_f32 v[12:13], v[150:151], v[12:13], v[154:155]
	v_pk_fma_f32 v[10:11], v[210:211], v[10:11], v[212:213]
	v_pk_fma_f32 v[12:13], v[138:139], v[172:173], v[12:13]
	v_pk_fma_f32 v[10:11], v[136:137], v[174:175], v[10:11]
	global_store_dwordx4 v[40:41], v[10:13], off offset:64 sc1
	global_load_dwordx4 v[10:13], v[46:47], off offset:64
	v_mov_b32_e32 v136, v204
	v_mov_b32_e32 v137, v21
	s_waitcnt vmcnt(0)
	v_sub_f32_e32 v11, v11, v3
	v_sub_f32_e32 v10, v10, v3
	v_sub_f32_e32 v13, v13, v3
	v_sub_f32_e32 v12, v12, v3
	v_pk_mul_f32 v[12:13], v[136:137], v[12:13]
	v_pk_mul_f32 v[10:11], v[204:205], v[10:11]
	v_pk_fma_f32 v[12:13], v[150:151], v[12:13], v[154:155]
	v_pk_fma_f32 v[10:11], v[210:211], v[10:11], v[212:213]
	v_pk_fma_f32 v[12:13], v[134:135], v[172:173], v[12:13]
	v_pk_fma_f32 v[10:11], v[132:133], v[174:175], v[10:11]
	global_store_dwordx4 v[38:39], v[10:13], off offset:64 sc1
	global_load_dwordx4 v[10:13], v[48:49], off offset:64
	v_mov_b32_e32 v132, v34
	v_mov_b32_e32 v133, v45
	v_mov_b32_e32 v134, 0
	v_mov_b32_e32 v135, 0
	s_waitcnt vmcnt(0)
	v_sub_f32_e32 v11, v11, v4
	v_sub_f32_e32 v10, v10, v4
	v_sub_f32_e32 v13, v13, v4
	v_sub_f32_e32 v12, v12, v4
	v_pk_mul_f32 v[12:13], v[132:133], v[12:13]
	v_pk_mul_f32 v[10:11], v[44:45], v[10:11]
	v_pk_fma_f32 v[12:13], v[150:151], v[12:13], v[154:155]
	v_pk_fma_f32 v[10:11], v[210:211], v[10:11], v[212:213]
	v_pk_fma_f32 v[12:13], v[130:131], v[172:173], v[12:13]
	v_pk_fma_f32 v[10:11], v[128:129], v[174:175], v[10:11]
	global_store_dwordx4 v[164:165], v[10:13], off offset:64 sc1
	global_load_dwordx4 v[10:13], v[166:167], off offset:64
	v_mov_b32_e32 v128, v42
	v_mov_b32_e32 v129, v35
	v_mov_b32_e32 v130, 0
	v_mov_b32_e32 v131, 0
	s_waitcnt vmcnt(0)
	v_sub_f32_e32 v11, v11, v5
	v_sub_f32_e32 v10, v10, v5
	v_sub_f32_e32 v13, v13, v5
	v_sub_f32_e32 v12, v12, v5
	v_pk_mul_f32 v[12:13], v[128:129], v[12:13]
	v_pk_mul_f32 v[10:11], v[42:43], v[10:11]
	v_pk_fma_f32 v[12:13], v[150:151], v[12:13], v[154:155]
	v_pk_fma_f32 v[10:11], v[210:211], v[10:11], v[212:213]
	v_pk_fma_f32 v[12:13], v[126:127], v[172:173], v[12:13]
	v_pk_fma_f32 v[10:11], v[124:125], v[174:175], v[10:11]
	global_store_dwordx4 v[160:161], v[10:13], off offset:64 sc1
	global_load_dwordx4 v[10:13], v[162:163], off offset:64
	v_mov_b32_e32 v124, v24
	v_mov_b32_e32 v125, v24
	v_mov_b32_e32 v126, 1.0
	v_mov_b32_e32 v127, 1.0
	s_waitcnt vmcnt(0)
	v_sub_f32_e32 v11, v11, v6
	v_sub_f32_e32 v10, v10, v6
	v_sub_f32_e32 v13, v13, v6
	v_sub_f32_e32 v12, v12, v6
	v_pk_mul_f32 v[12:13], v[124:125], v[12:13]
	v_pk_mul_f32 v[10:11], v[24:25], v[10:11]
	v_pk_fma_f32 v[12:13], v[150:151], v[12:13], v[154:155]
	v_pk_fma_f32 v[10:11], v[210:211], v[10:11], v[212:213]
	v_pk_fma_f32 v[12:13], v[122:123], v[172:173], v[12:13]
	v_pk_fma_f32 v[10:11], v[120:121], v[174:175], v[10:11]
	global_store_dwordx4 v[156:157], v[10:13], off offset:64 sc1
	global_load_dwordx4 v[10:13], v[158:159], off offset:64
	v_mov_b32_e32 v120, v26
	v_mov_b32_e32 v121, v26
	v_mov_b32_e32 v122, 1.0
	v_mov_b32_e32 v123, 1.0
	s_waitcnt vmcnt(0)
	v_sub_f32_e32 v11, v11, v7
	v_sub_f32_e32 v10, v10, v7
	v_sub_f32_e32 v13, v13, v7
	v_sub_f32_e32 v12, v12, v7
	v_pk_mul_f32 v[12:13], v[120:121], v[12:13]
	v_pk_mul_f32 v[10:11], v[26:27], v[10:11]
	v_pk_fma_f32 v[12:13], v[150:151], v[12:13], v[154:155]
	v_pk_fma_f32 v[10:11], v[210:211], v[10:11], v[212:213]
	v_pk_fma_f32 v[12:13], v[118:119], v[172:173], v[12:13]
	v_pk_fma_f32 v[10:11], v[116:117], v[174:175], v[10:11]
	global_store_dwordx4 v[152:153], v[10:13], off offset:64 sc1
	global_load_dwordx4 v[10:13], v[18:19], off offset:512
	v_mov_b32_e32 v118, 0
	v_mov_b32_e32 v116, 1.0
	s_cbranch_vccnz .LBB0_1545
	v_lshlrev_b64 v[122:123], 2, v[14:15]
	v_lshl_add_u64 v[126:127], s[48:49], 0, v[122:123]
	v_lshl_add_u64 v[122:123], s[50:51], 0, v[122:123]
	global_load_dwordx4 v[168:171], v[126:127], off offset:512
	global_load_dwordx4 v[172:175], v[122:123], off offset:512
	s_waitcnt vmcnt(1)
	v_pk_mul_f32 v[122:123], v[170:171], s[28:29] op_sel_hi:[1,0]
	v_pk_mul_f32 v[126:127], v[168:169], s[28:29] op_sel_hi:[1,0]
	s_waitcnt vmcnt(0)
	v_pk_mul_f32 v[130:131], v[174:175], s[28:29] op_sel_hi:[1,0]
	v_pk_mul_f32 v[134:135], v[172:173], s[28:29] op_sel_hi:[1,0]
.LBB0_1545:
	global_load_dwordx4 v[168:171], v[22:23], off offset:512
	s_waitcnt vmcnt(1)
	v_pk_add_f32 v[138:139], v[12:13], 1.0 op_sel_hi:[1,0]
	v_pk_add_f32 v[142:143], v[10:11], 1.0 op_sel_hi:[1,0]
	s_and_b64 vcc, exec, s[40:41]
	v_mov_b32_e32 v117, 1.0
	v_mov_b32_e32 v119, 0
	s_waitcnt vmcnt(0)
	v_sub_f32_e32 v11, v169, v0
	v_sub_f32_e32 v10, v168, v0
	v_sub_f32_e32 v13, v171, v0
	v_sub_f32_e32 v12, v170, v0
	v_pk_mul_f32 v[12:13], v[148:149], v[12:13]
	v_pk_mul_f32 v[10:11], v[8:9], v[10:11]
	v_pk_fma_f32 v[12:13], v[122:123], v[12:13], v[130:131]
	v_pk_fma_f32 v[10:11], v[126:127], v[10:11], v[134:135]
	v_pk_fma_f32 v[12:13], v[114:115], v[138:139], v[12:13]
	v_pk_fma_f32 v[10:11], v[112:113], v[142:143], v[10:11]
	global_store_dwordx4 v[28:29], v[10:13], off offset:512 sc1
	global_load_dwordx4 v[10:13], v[30:31], off offset:512
	s_waitcnt vmcnt(0)
	v_sub_f32_e32 v11, v11, v1
	v_sub_f32_e32 v10, v10, v1
	v_sub_f32_e32 v13, v13, v1
	v_sub_f32_e32 v12, v12, v1
	v_pk_mul_f32 v[12:13], v[144:145], v[12:13]
	v_pk_mul_f32 v[10:11], v[202:203], v[10:11]
	v_pk_fma_f32 v[12:13], v[122:123], v[12:13], v[130:131]
	v_pk_fma_f32 v[10:11], v[126:127], v[10:11], v[134:135]
	v_pk_fma_f32 v[12:13], v[110:111], v[138:139], v[12:13]
	v_pk_fma_f32 v[10:11], v[108:109], v[142:143], v[10:11]
	global_store_dwordx4 v[32:33], v[10:13], off offset:512 sc1
	global_load_dwordx4 v[10:13], v[36:37], off offset:512
	s_waitcnt vmcnt(0)
	v_sub_f32_e32 v11, v11, v2
	v_sub_f32_e32 v10, v10, v2
	v_sub_f32_e32 v13, v13, v2
	v_sub_f32_e32 v12, v12, v2
	v_pk_mul_f32 v[12:13], v[140:141], v[12:13]
	v_pk_mul_f32 v[10:11], v[206:207], v[10:11]
	v_pk_fma_f32 v[12:13], v[122:123], v[12:13], v[130:131]
	v_pk_fma_f32 v[10:11], v[126:127], v[10:11], v[134:135]
	v_pk_fma_f32 v[12:13], v[106:107], v[138:139], v[12:13]
	v_pk_fma_f32 v[10:11], v[104:105], v[142:143], v[10:11]
	global_store_dwordx4 v[40:41], v[10:13], off offset:512 sc1
	global_load_dwordx4 v[10:13], v[46:47], off offset:512
	s_waitcnt vmcnt(0)
	v_sub_f32_e32 v11, v11, v3
	v_sub_f32_e32 v10, v10, v3
	v_sub_f32_e32 v13, v13, v3
	v_sub_f32_e32 v12, v12, v3
	v_pk_mul_f32 v[12:13], v[136:137], v[12:13]
	v_pk_mul_f32 v[10:11], v[204:205], v[10:11]
	v_pk_fma_f32 v[12:13], v[122:123], v[12:13], v[130:131]
	v_pk_fma_f32 v[10:11], v[126:127], v[10:11], v[134:135]
	v_pk_fma_f32 v[12:13], v[102:103], v[138:139], v[12:13]
	v_pk_fma_f32 v[10:11], v[100:101], v[142:143], v[10:11]
	global_store_dwordx4 v[38:39], v[10:13], off offset:512 sc1
	global_load_dwordx4 v[10:13], v[48:49], off offset:512
	s_waitcnt vmcnt(0)
	v_sub_f32_e32 v11, v11, v4
	v_sub_f32_e32 v10, v10, v4
	v_sub_f32_e32 v13, v13, v4
	v_sub_f32_e32 v12, v12, v4
	v_pk_mul_f32 v[12:13], v[132:133], v[12:13]
	v_pk_mul_f32 v[10:11], v[44:45], v[10:11]
	v_pk_fma_f32 v[12:13], v[122:123], v[12:13], v[130:131]
	v_pk_fma_f32 v[10:11], v[126:127], v[10:11], v[134:135]
	v_pk_fma_f32 v[12:13], v[98:99], v[138:139], v[12:13]
	v_pk_fma_f32 v[10:11], v[96:97], v[142:143], v[10:11]
	global_store_dwordx4 v[164:165], v[10:13], off offset:512 sc1
	global_load_dwordx4 v[10:13], v[166:167], off offset:512
	s_waitcnt vmcnt(0)
	v_sub_f32_e32 v11, v11, v5
	v_sub_f32_e32 v10, v10, v5
	v_sub_f32_e32 v13, v13, v5
	v_sub_f32_e32 v12, v12, v5
	v_pk_mul_f32 v[12:13], v[128:129], v[12:13]
	v_pk_mul_f32 v[10:11], v[42:43], v[10:11]
	v_pk_fma_f32 v[12:13], v[122:123], v[12:13], v[130:131]
	v_pk_fma_f32 v[10:11], v[126:127], v[10:11], v[134:135]
	v_pk_fma_f32 v[12:13], v[94:95], v[138:139], v[12:13]
	v_pk_fma_f32 v[10:11], v[92:93], v[142:143], v[10:11]
	global_store_dwordx4 v[160:161], v[10:13], off offset:512 sc1
	global_load_dwordx4 v[10:13], v[162:163], off offset:512
	s_waitcnt vmcnt(0)
	v_sub_f32_e32 v11, v11, v6
	v_sub_f32_e32 v10, v10, v6
	v_sub_f32_e32 v13, v13, v6
	v_sub_f32_e32 v12, v12, v6
	v_pk_mul_f32 v[12:13], v[124:125], v[12:13]
	v_pk_mul_f32 v[10:11], v[24:25], v[10:11]
	v_pk_fma_f32 v[12:13], v[122:123], v[12:13], v[130:131]
	v_pk_fma_f32 v[10:11], v[126:127], v[10:11], v[134:135]
	v_pk_fma_f32 v[12:13], v[90:91], v[138:139], v[12:13]
	v_pk_fma_f32 v[10:11], v[88:89], v[142:143], v[10:11]
	global_store_dwordx4 v[156:157], v[10:13], off offset:512 sc1
	global_load_dwordx4 v[10:13], v[158:159], off offset:512
	s_waitcnt vmcnt(0)
	v_sub_f32_e32 v11, v11, v7
	v_sub_f32_e32 v10, v10, v7
	v_sub_f32_e32 v13, v13, v7
	v_sub_f32_e32 v12, v12, v7
	v_pk_mul_f32 v[12:13], v[120:121], v[12:13]
	v_pk_mul_f32 v[10:11], v[26:27], v[10:11]
	v_pk_fma_f32 v[12:13], v[122:123], v[12:13], v[130:131]
	v_pk_fma_f32 v[10:11], v[126:127], v[10:11], v[134:135]
	v_pk_fma_f32 v[12:13], v[86:87], v[138:139], v[12:13]
	v_pk_fma_f32 v[10:11], v[84:85], v[142:143], v[10:11]
	global_store_dwordx4 v[152:153], v[10:13], off offset:512 sc1
	global_load_dwordx4 v[10:13], v[18:19], off offset:576
	v_mov_b32_e32 v18, 1.0
	v_mov_b32_e32 v19, 1.0
	v_mov_b32_e32 v84, 0
	v_mov_b32_e32 v85, 0
	s_cbranch_vccnz .LBB0_1547
	v_lshlrev_b64 v[14:15], 2, v[14:15]
	v_lshl_add_u64 v[18:19], s[48:49], 0, v[14:15]
	v_lshl_add_u64 v[14:15], s[50:51], 0, v[14:15]
	global_load_dwordx4 v[84:87], v[18:19], off offset:576
	global_load_dwordx4 v[88:91], v[14:15], off offset:576
	s_waitcnt vmcnt(1)
	v_pk_mul_f32 v[18:19], v[86:87], s[28:29] op_sel_hi:[1,0]
	v_pk_mul_f32 v[116:117], v[84:85], s[28:29] op_sel_hi:[1,0]
	s_waitcnt vmcnt(0)
	v_pk_mul_f32 v[84:85], v[90:91], s[28:29] op_sel_hi:[1,0]
	v_pk_mul_f32 v[118:119], v[88:89], s[28:29] op_sel_hi:[1,0]
.LBB0_1547:
	global_load_dwordx4 v[86:89], v[22:23], off offset:576
	s_waitcnt vmcnt(1)
	v_pk_add_f32 v[14:15], v[10:11], 1.0 op_sel_hi:[1,0]
	v_mov_b32_e32 v10, v16
	v_mov_b32_e32 v11, v9
	v_pk_add_f32 v[12:13], v[12:13], 1.0 op_sel_hi:[1,0]
	v_mov_b32_e32 v16, v202
	s_andn2_b64 vcc, exec, s[38:39]
	s_mov_b64 s[26:27], -1
	s_waitcnt vmcnt(0)
	v_sub_f32_e32 v23, v87, v0
	v_sub_f32_e32 v22, v86, v0
	v_sub_f32_e32 v87, v89, v0
	v_sub_f32_e32 v86, v88, v0
	v_pk_mul_f32 v[10:11], v[10:11], v[86:87]
	v_pk_mul_f32 v[8:9], v[8:9], v[22:23]
	v_pk_fma_f32 v[10:11], v[18:19], v[10:11], v[84:85]
	v_pk_fma_f32 v[8:9], v[116:117], v[8:9], v[118:119]
	v_pk_fma_f32 v[10:11], v[82:83], v[12:13], v[10:11]
	v_pk_fma_f32 v[8:9], v[80:81], v[14:15], v[8:9]
	global_store_dwordx4 v[28:29], v[8:11], off offset:576 sc1
	global_load_dwordx4 v[8:11], v[30:31], off offset:576
	s_waitcnt vmcnt(0)
	v_sub_f32_e32 v9, v9, v1
	v_sub_f32_e32 v8, v8, v1
	v_sub_f32_e32 v11, v11, v1
	v_sub_f32_e32 v10, v10, v1
	v_pk_mul_f32 v[0:1], v[16:17], v[10:11]
	v_pk_mul_f32 v[8:9], v[202:203], v[8:9]
	v_pk_fma_f32 v[0:1], v[18:19], v[0:1], v[84:85]
	v_pk_fma_f32 v[8:9], v[116:117], v[8:9], v[118:119]
	v_pk_fma_f32 v[10:11], v[78:79], v[12:13], v[0:1]
	v_pk_fma_f32 v[8:9], v[76:77], v[14:15], v[8:9]
	global_store_dwordx4 v[32:33], v[8:11], off offset:576 sc1
	global_load_dwordx4 v[8:11], v[36:37], off offset:576
	v_mov_b32_e32 v0, v20
	v_mov_b32_e32 v1, v207
	v_mov_b32_e32 v20, v204
	s_waitcnt vmcnt(0)
	v_sub_f32_e32 v9, v9, v2
	v_sub_f32_e32 v8, v8, v2
	v_sub_f32_e32 v11, v11, v2
	v_sub_f32_e32 v10, v10, v2
	v_pk_mul_f32 v[0:1], v[0:1], v[10:11]
	v_pk_mul_f32 v[8:9], v[206:207], v[8:9]
	v_pk_fma_f32 v[0:1], v[18:19], v[0:1], v[84:85]
	v_pk_fma_f32 v[8:9], v[116:117], v[8:9], v[118:119]
	v_pk_fma_f32 v[10:11], v[74:75], v[12:13], v[0:1]
	v_pk_fma_f32 v[8:9], v[72:73], v[14:15], v[8:9]
	global_store_dwordx4 v[40:41], v[8:11], off offset:576 sc1
	global_load_dwordx4 v[8:11], v[46:47], off offset:576
	s_waitcnt vmcnt(0)
	v_sub_f32_e32 v1, v9, v3
	v_sub_f32_e32 v0, v8, v3
	v_sub_f32_e32 v9, v11, v3
	v_sub_f32_e32 v8, v10, v3
	v_pk_mul_f32 v[2:3], v[20:21], v[8:9]
	v_pk_mul_f32 v[0:1], v[204:205], v[0:1]
	v_pk_fma_f32 v[2:3], v[18:19], v[2:3], v[84:85]
	v_pk_fma_f32 v[0:1], v[116:117], v[0:1], v[118:119]
	v_pk_fma_f32 v[2:3], v[70:71], v[12:13], v[2:3]
	v_pk_fma_f32 v[0:1], v[68:69], v[14:15], v[0:1]
	global_store_dwordx4 v[38:39], v[0:3], off offset:576 sc1
	global_load_dwordx4 v[0:3], v[48:49], off offset:576
	v_mov_b32_e32 v8, v34
	v_mov_b32_e32 v9, v45
	v_mov_b32_e32 v34, v42
	s_waitcnt vmcnt(0)
	v_sub_f32_e32 v1, v1, v4
	v_sub_f32_e32 v0, v0, v4
	v_sub_f32_e32 v3, v3, v4
	v_sub_f32_e32 v2, v2, v4
	v_pk_mul_f32 v[2:3], v[8:9], v[2:3]
	v_pk_mul_f32 v[0:1], v[44:45], v[0:1]
	v_pk_fma_f32 v[2:3], v[18:19], v[2:3], v[84:85]
	v_pk_fma_f32 v[0:1], v[116:117], v[0:1], v[118:119]
	v_pk_fma_f32 v[2:3], v[66:67], v[12:13], v[2:3]
	v_pk_fma_f32 v[0:1], v[64:65], v[14:15], v[0:1]
	global_store_dwordx4 v[164:165], v[0:3], off offset:576 sc1
	global_load_dwordx4 v[0:3], v[166:167], off offset:576
	v_mov_b32_e32 v4, v24
	s_waitcnt vmcnt(0)
	v_sub_f32_e32 v1, v1, v5
	v_sub_f32_e32 v0, v0, v5
	v_sub_f32_e32 v3, v3, v5
	v_sub_f32_e32 v2, v2, v5
	v_pk_mul_f32 v[2:3], v[34:35], v[2:3]
	v_pk_mul_f32 v[0:1], v[42:43], v[0:1]
	v_pk_fma_f32 v[2:3], v[18:19], v[2:3], v[84:85]
	v_pk_fma_f32 v[0:1], v[116:117], v[0:1], v[118:119]
	v_pk_fma_f32 v[2:3], v[62:63], v[12:13], v[2:3]
	v_pk_fma_f32 v[0:1], v[60:61], v[14:15], v[0:1]
	global_store_dwordx4 v[160:161], v[0:3], off offset:576 sc1
	global_load_dwordx4 v[0:3], v[162:163], off offset:576
	v_mov_b32_e32 v5, v24
	s_waitcnt vmcnt(0)
	v_sub_f32_e32 v1, v1, v6
	v_sub_f32_e32 v0, v0, v6
	v_sub_f32_e32 v3, v3, v6
	v_sub_f32_e32 v2, v2, v6
	v_pk_mul_f32 v[2:3], v[4:5], v[2:3]
	v_pk_mul_f32 v[0:1], v[24:25], v[0:1]
	v_pk_fma_f32 v[2:3], v[18:19], v[2:3], v[84:85]
	v_pk_fma_f32 v[0:1], v[116:117], v[0:1], v[118:119]
	v_pk_fma_f32 v[2:3], v[58:59], v[12:13], v[2:3]
	v_pk_fma_f32 v[0:1], v[56:57], v[14:15], v[0:1]
	global_store_dwordx4 v[156:157], v[0:3], off offset:576 sc1
	global_load_dwordx4 v[0:3], v[158:159], off offset:576
	v_mov_b32_e32 v4, v26
	v_mov_b32_e32 v5, v26
	s_waitcnt vmcnt(0)
	v_sub_f32_e32 v1, v1, v7
	v_sub_f32_e32 v0, v0, v7
	v_sub_f32_e32 v3, v3, v7
	v_sub_f32_e32 v2, v2, v7
	v_pk_mul_f32 v[2:3], v[4:5], v[2:3]
	v_pk_mul_f32 v[0:1], v[26:27], v[0:1]
	v_pk_fma_f32 v[2:3], v[18:19], v[2:3], v[84:85]
	v_pk_fma_f32 v[0:1], v[116:117], v[0:1], v[118:119]
	v_pk_fma_f32 v[2:3], v[54:55], v[12:13], v[2:3]
	v_pk_fma_f32 v[0:1], v[52:53], v[14:15], v[0:1]
	global_store_dwordx4 v[152:153], v[0:3], off offset:576 sc1
	s_cbranch_vccnz .LBB0_1511
	s_andn2_b64 vcc, exec, s[2:3]
	s_cbranch_vccnz .LBB0_1510
	s_barrier
	s_branch .LBB0_1510

.LBB0_1709:
	s_lshl_b32 s26, s46, 8
	v_mbcnt_lo_u32_b32 v143, -1, 0
	v_mbcnt_hi_u32_b32 v143, -1, v143
	s_add_i32 s26, s26, s19
	v_and_or_b32 v142, v143, 15, s26
	s_lshl_b32 s26, s36, 7
	v_ashrrev_i32_e32 v143, 1, v143
	s_or_b32 s26, s26, s20
	v_and_b32_e32 v143, -8, v143
	v_add_u32_e32 v144, s26, v143
	v_mul_f32_e32 v143, 0xbfb8aa3b, v128
	v_exp_f32_e32 v143, v143
	v_ashrrev_i32_e32 v145, 31, v144
	s_movk_i32 s8, 0x1600
	s_andn2_b64 vcc, exec, s[38:39]
	v_add_f32_e32 v143, 1.0, v143
	v_rcp_f32_e32 v143, v143
	s_nop 0
	v_mul_f32_e32 v128, v128, v143
	v_mul_f32_e32 v124, v128, v124
	v_mul_f32_e32 v128, 0xbfb8aa3b, v129
	v_exp_f32_e32 v128, v128
	s_nop 0
	v_add_f32_e32 v128, 1.0, v128
	v_rcp_f32_e32 v128, v128
	s_nop 0
	v_mul_f32_e32 v128, v129, v128
	v_mul_f32_e32 v125, v128, v125
	v_mul_f32_e32 v128, 0xbfb8aa3b, v130
	v_exp_f32_e32 v128, v128
	s_nop 0
	v_add_f32_e32 v128, 1.0, v128
	v_rcp_f32_e32 v128, v128
	s_nop 0
	v_mul_f32_e32 v128, v130, v128
	v_mul_f32_e32 v126, v128, v126
	v_mul_f32_e32 v128, 0xbfb8aa3b, v131
	v_exp_f32_e32 v128, v128
	s_nop 0
	v_add_f32_e32 v128, 1.0, v128
	v_rcp_f32_e32 v128, v128
	s_nop 0
	v_mul_f32_e32 v128, v131, v128
	v_mul_f32_e32 v127, v128, v127
	v_mul_f32_e32 v128, 0xbfb8aa3b, v120
	v_exp_f32_e32 v128, v128
	s_nop 0
	v_add_f32_e32 v128, 1.0, v128
	v_rcp_f32_e32 v128, v128
	s_nop 0
	v_mul_f32_e32 v120, v120, v128
	v_mul_f32_e32 v116, v120, v116
	v_mul_f32_e32 v120, 0xbfb8aa3b, v121
	v_exp_f32_e32 v120, v120
	s_nop 0
	v_add_f32_e32 v120, 1.0, v120
	v_rcp_f32_e32 v120, v120
	s_nop 0
	v_mul_f32_e32 v120, v121, v120
	v_mul_f32_e32 v117, v120, v117
	v_mul_f32_e32 v120, 0xbfb8aa3b, v122
	v_exp_f32_e32 v120, v120
	s_nop 0
	v_add_f32_e32 v120, 1.0, v120
	v_rcp_f32_e32 v120, v120
	s_nop 0
	v_mul_f32_e32 v120, v122, v120
	v_mul_f32_e32 v118, v120, v118
	v_mul_f32_e32 v120, 0xbfb8aa3b, v123
	v_exp_f32_e32 v120, v120
	s_nop 0
	v_add_f32_e32 v120, 1.0, v120
	v_rcp_f32_e32 v120, v120
	s_nop 0
	v_mul_f32_e32 v120, v123, v120
	v_mul_f32_e32 v119, v120, v119
	v_cvt_pk_bf16_f32 v120, v124, v125
	v_cvt_pk_bf16_f32 v121, v126, v127
	v_cvt_pk_bf16_f32 v122, v116, v117
	v_mov_b64_e32 v[116:117], s[4:5]
	v_cvt_pk_bf16_f32 v123, v118, v119
	v_mad_i64_i32 v[124:125], s[26:27], v142, s8, v[116:117]
	v_lshlrev_b64 v[118:119], 1, v[144:145]
	v_lshl_add_u64 v[124:125], v[124:125], 0, v[118:119]
	global_store_dwordx4 v[124:125], v[120:123], off sc1
	s_nop 1
	v_mul_f32_e32 v120, 0xbfb8aa3b, v112
	v_exp_f32_e32 v120, v120
	s_nop 0
	v_add_f32_e32 v120, 1.0, v120
	v_rcp_f32_e32 v120, v120
	s_nop 0
	v_mul_f32_e32 v112, v112, v120
	v_mul_f32_e32 v108, v112, v108
	v_mul_f32_e32 v112, 0xbfb8aa3b, v113
	v_exp_f32_e32 v112, v112
	s_nop 0
	v_add_f32_e32 v112, 1.0, v112
	v_rcp_f32_e32 v112, v112
	s_nop 0
	v_mul_f32_e32 v112, v113, v112
	v_mul_f32_e32 v109, v112, v109
	v_mul_f32_e32 v112, 0xbfb8aa3b, v114
	v_exp_f32_e32 v112, v112
	s_nop 0
	v_add_f32_e32 v112, 1.0, v112
	v_rcp_f32_e32 v112, v112
	s_nop 0
	v_mul_f32_e32 v112, v114, v112
	v_mul_f32_e32 v110, v112, v110
	v_mul_f32_e32 v112, 0xbfb8aa3b, v115
	v_exp_f32_e32 v112, v112
	s_nop 0
	v_add_f32_e32 v112, 1.0, v112
	v_rcp_f32_e32 v112, v112
	s_nop 0
	v_mul_f32_e32 v112, v115, v112
	v_mul_f32_e32 v111, v112, v111
	v_mul_f32_e32 v112, 0xbfb8aa3b, v104
	v_exp_f32_e32 v112, v112
	s_nop 0
	v_add_f32_e32 v112, 1.0, v112
	v_rcp_f32_e32 v112, v112
	s_nop 0
	v_mul_f32_e32 v104, v104, v112
	v_mul_f32_e32 v104, v104, v100
	v_mul_f32_e32 v100, 0xbfb8aa3b, v105
	v_exp_f32_e32 v100, v100
	s_nop 0
	v_add_f32_e32 v100, 1.0, v100
	v_rcp_f32_e32 v100, v100
	s_nop 0
	v_mul_f32_e32 v100, v105, v100
	v_mul_f32_e32 v105, v100, v101
	v_mul_f32_e32 v100, 0xbfb8aa3b, v106
	v_exp_f32_e32 v100, v100
	s_nop 0
	v_add_f32_e32 v100, 1.0, v100
	v_rcp_f32_e32 v100, v100
	s_nop 0
	v_mul_f32_e32 v100, v106, v100
	v_mul_f32_e32 v106, v100, v102
	v_mul_f32_e32 v100, 0xbfb8aa3b, v107
	v_exp_f32_e32 v100, v100
	s_nop 0
	v_add_f32_e32 v100, 1.0, v100
	v_rcp_f32_e32 v100, v100
	s_nop 0
	v_mul_f32_e32 v100, v107, v100
	v_mul_f32_e32 v103, v100, v103
	v_cvt_pk_bf16_f32 v100, v108, v109
	v_cvt_pk_bf16_f32 v101, v110, v111
	v_cvt_pk_bf16_f32 v102, v104, v105
	v_or_b32_e32 v104, 16, v142
	v_mad_i64_i32 v[104:105], s[26:27], v104, s8, v[116:117]
	v_lshl_add_u64 v[104:105], v[104:105], 0, v[118:119]
	v_cvt_pk_bf16_f32 v103, v106, v103
	global_store_dwordx4 v[104:105], v[100:103], off sc1
	s_nop 1
	v_mul_f32_e32 v100, 0xbfb8aa3b, v96
	v_exp_f32_e32 v100, v100
	s_nop 0
	v_add_f32_e32 v100, 1.0, v100
	v_rcp_f32_e32 v100, v100
	s_nop 0
	v_mul_f32_e32 v96, v96, v100
	v_mul_f32_e32 v92, v96, v92
	v_mul_f32_e32 v96, 0xbfb8aa3b, v97
	v_exp_f32_e32 v96, v96
	s_nop 0
	v_add_f32_e32 v96, 1.0, v96
	v_rcp_f32_e32 v96, v96
	s_nop 0
	v_mul_f32_e32 v96, v97, v96
	v_mul_f32_e32 v93, v96, v93
	v_mul_f32_e32 v96, 0xbfb8aa3b, v98
	v_exp_f32_e32 v96, v96
	s_nop 0
	v_add_f32_e32 v96, 1.0, v96
	v_rcp_f32_e32 v96, v96
	s_nop 0
	v_mul_f32_e32 v96, v98, v96
	v_mul_f32_e32 v94, v96, v94
	v_mul_f32_e32 v96, 0xbfb8aa3b, v99
	v_exp_f32_e32 v96, v96
	s_nop 0
	v_add_f32_e32 v96, 1.0, v96
	v_rcp_f32_e32 v96, v96
	s_nop 0
	v_mul_f32_e32 v96, v99, v96
	v_mul_f32_e32 v95, v96, v95
	v_mul_f32_e32 v96, 0xbfb8aa3b, v88
	v_exp_f32_e32 v96, v96
	s_nop 0
	v_add_f32_e32 v96, 1.0, v96
	v_rcp_f32_e32 v96, v96
	s_nop 0
	v_mul_f32_e32 v88, v88, v96
	v_mul_f32_e32 v88, v88, v84
	v_mul_f32_e32 v84, 0xbfb8aa3b, v89
	v_exp_f32_e32 v84, v84
	s_nop 0
	v_add_f32_e32 v84, 1.0, v84
	v_rcp_f32_e32 v84, v84
	s_nop 0
	v_mul_f32_e32 v84, v89, v84
	v_mul_f32_e32 v89, v84, v85
	v_mul_f32_e32 v84, 0xbfb8aa3b, v90
	v_exp_f32_e32 v84, v84
	s_nop 0
	v_add_f32_e32 v84, 1.0, v84
	v_rcp_f32_e32 v84, v84
	s_nop 0
	v_mul_f32_e32 v84, v90, v84
	v_mul_f32_e32 v90, v84, v86
	v_mul_f32_e32 v84, 0xbfb8aa3b, v91
	v_exp_f32_e32 v84, v84
	s_nop 0
	v_add_f32_e32 v84, 1.0, v84
	v_rcp_f32_e32 v84, v84
	s_nop 0
	v_mul_f32_e32 v84, v91, v84
	v_mul_f32_e32 v87, v84, v87
	v_cvt_pk_bf16_f32 v84, v92, v93
	v_cvt_pk_bf16_f32 v85, v94, v95
	v_cvt_pk_bf16_f32 v86, v88, v89
	v_or_b32_e32 v88, 32, v142
	v_mad_i64_i32 v[88:89], s[26:27], v88, s8, v[116:117]
	v_lshl_add_u64 v[88:89], v[88:89], 0, v[118:119]
	v_cvt_pk_bf16_f32 v87, v90, v87
	global_store_dwordx4 v[88:89], v[84:87], off sc1
	s_nop 1
	v_mul_f32_e32 v84, 0xbfb8aa3b, v80
	v_exp_f32_e32 v84, v84
	s_nop 0
	v_add_f32_e32 v84, 1.0, v84
	v_rcp_f32_e32 v84, v84
	s_nop 0
	v_mul_f32_e32 v80, v80, v84
	v_mul_f32_e32 v76, v80, v76
	v_mul_f32_e32 v80, 0xbfb8aa3b, v81
	v_exp_f32_e32 v80, v80
	s_nop 0
	v_add_f32_e32 v80, 1.0, v80
	v_rcp_f32_e32 v80, v80
	s_nop 0
	v_mul_f32_e32 v80, v81, v80
	v_mul_f32_e32 v77, v80, v77
	v_mul_f32_e32 v80, 0xbfb8aa3b, v82
	v_exp_f32_e32 v80, v80
	s_nop 0
	v_add_f32_e32 v80, 1.0, v80
	v_rcp_f32_e32 v80, v80
	s_nop 0
	v_mul_f32_e32 v80, v82, v80
	v_mul_f32_e32 v78, v80, v78
	v_mul_f32_e32 v80, 0xbfb8aa3b, v83
	v_exp_f32_e32 v80, v80
	s_nop 0
	v_add_f32_e32 v80, 1.0, v80
	v_rcp_f32_e32 v80, v80
	s_nop 0
	v_mul_f32_e32 v80, v83, v80
	v_mul_f32_e32 v79, v80, v79
	v_mul_f32_e32 v80, 0xbfb8aa3b, v72
	v_exp_f32_e32 v80, v80
	s_nop 0
	v_add_f32_e32 v80, 1.0, v80
	v_rcp_f32_e32 v80, v80
	s_nop 0
	v_mul_f32_e32 v72, v72, v80
	v_mul_f32_e32 v72, v72, v68
	v_mul_f32_e32 v68, 0xbfb8aa3b, v73
	v_exp_f32_e32 v68, v68
	s_nop 0
	v_add_f32_e32 v68, 1.0, v68
	v_rcp_f32_e32 v68, v68
	s_nop 0
	v_mul_f32_e32 v68, v73, v68
	v_mul_f32_e32 v73, v68, v69
	v_mul_f32_e32 v68, 0xbfb8aa3b, v74
	v_exp_f32_e32 v68, v68
	s_nop 0
	v_add_f32_e32 v68, 1.0, v68
	v_rcp_f32_e32 v68, v68
	s_nop 0
	v_mul_f32_e32 v68, v74, v68
	v_mul_f32_e32 v74, v68, v70
	v_mul_f32_e32 v68, 0xbfb8aa3b, v75
	v_exp_f32_e32 v68, v68
	s_nop 0
	v_add_f32_e32 v68, 1.0, v68
	v_rcp_f32_e32 v68, v68
	s_nop 0
	v_mul_f32_e32 v68, v75, v68
	v_mul_f32_e32 v71, v68, v71
	v_cvt_pk_bf16_f32 v68, v76, v77
	v_cvt_pk_bf16_f32 v69, v78, v79
	v_cvt_pk_bf16_f32 v70, v72, v73
	v_or_b32_e32 v72, 48, v142
	v_mad_i64_i32 v[72:73], s[26:27], v72, s8, v[116:117]
	v_lshl_add_u64 v[72:73], v[72:73], 0, v[118:119]
	v_cvt_pk_bf16_f32 v71, v74, v71
	global_store_dwordx4 v[72:73], v[68:71], off sc1
	s_nop 1
	v_mul_f32_e32 v69, 0xbfb8aa3b, v64
	v_exp_f32_e32 v69, v69
	v_add_u32_e32 v68, 0x80, v142
	v_add_f32_e32 v69, 1.0, v69
	v_rcp_f32_e32 v69, v69
	s_nop 0
	v_mul_f32_e32 v64, v64, v69
	v_mul_f32_e32 v60, v64, v60
	v_mul_f32_e32 v64, 0xbfb8aa3b, v65
	v_exp_f32_e32 v64, v64
	s_nop 0
	v_add_f32_e32 v64, 1.0, v64
	v_rcp_f32_e32 v64, v64
	s_nop 0
	v_mul_f32_e32 v64, v65, v64
	v_mul_f32_e32 v61, v64, v61
	v_mul_f32_e32 v64, 0xbfb8aa3b, v66
	v_exp_f32_e32 v64, v64
	s_nop 0
	v_add_f32_e32 v64, 1.0, v64
	v_rcp_f32_e32 v64, v64
	s_nop 0
	v_mul_f32_e32 v64, v66, v64
	v_mul_f32_e32 v62, v64, v62
	v_mul_f32_e32 v64, 0xbfb8aa3b, v67
	v_exp_f32_e32 v64, v64
	s_nop 0
	v_add_f32_e32 v64, 1.0, v64
	v_rcp_f32_e32 v64, v64
	s_nop 0
	v_mul_f32_e32 v64, v67, v64
	v_mul_f32_e32 v63, v64, v63
	v_mul_f32_e32 v64, 0xbfb8aa3b, v56
	v_exp_f32_e32 v64, v64
	s_nop 0
	v_add_f32_e32 v64, 1.0, v64
	v_rcp_f32_e32 v64, v64
	s_nop 0
	v_mul_f32_e32 v56, v56, v64
	v_mul_f32_e32 v56, v56, v52
	v_mul_f32_e32 v52, 0xbfb8aa3b, v57
	v_exp_f32_e32 v52, v52
	s_nop 0
	v_add_f32_e32 v52, 1.0, v52
	v_rcp_f32_e32 v52, v52
	s_nop 0
	v_mul_f32_e32 v52, v57, v52
	v_mul_f32_e32 v57, v52, v53
	v_mul_f32_e32 v52, 0xbfb8aa3b, v58
	v_exp_f32_e32 v52, v52
	s_nop 0
	v_add_f32_e32 v52, 1.0, v52
	v_rcp_f32_e32 v52, v52
	s_nop 0
	v_mul_f32_e32 v52, v58, v52
	v_mul_f32_e32 v58, v52, v54
	v_mul_f32_e32 v52, 0xbfb8aa3b, v59
	v_exp_f32_e32 v52, v52
	s_nop 0
	v_add_f32_e32 v52, 1.0, v52
	v_rcp_f32_e32 v52, v52
	s_nop 0
	v_mul_f32_e32 v52, v59, v52
	v_mul_f32_e32 v55, v52, v55
	v_cvt_pk_bf16_f32 v52, v60, v61
	v_cvt_pk_bf16_f32 v53, v62, v63
	v_cvt_pk_bf16_f32 v54, v56, v57
	v_mad_i64_i32 v[56:57], s[26:27], v68, s8, v[116:117]
	v_lshl_add_u64 v[56:57], v[56:57], 0, v[118:119]
	v_cvt_pk_bf16_f32 v55, v58, v55
	global_store_dwordx4 v[56:57], v[52:55], off sc1
	s_nop 1
	v_mul_f32_e32 v52, 0xbfb8aa3b, v44
	v_exp_f32_e32 v52, v52
	s_nop 0
	v_add_f32_e32 v52, 1.0, v52
	v_rcp_f32_e32 v52, v52
	s_nop 0
	v_mul_f32_e32 v44, v44, v52
	v_mul_f32_e32 v40, v44, v40
	v_mul_f32_e32 v44, 0xbfb8aa3b, v45
	v_exp_f32_e32 v44, v44
	s_nop 0
	v_add_f32_e32 v44, 1.0, v44
	v_rcp_f32_e32 v44, v44
	s_nop 0
	v_mul_f32_e32 v44, v45, v44
	v_mul_f32_e32 v41, v44, v41
	v_mul_f32_e32 v44, 0xbfb8aa3b, v46
	v_exp_f32_e32 v44, v44
	s_nop 0
	v_add_f32_e32 v44, 1.0, v44
	v_rcp_f32_e32 v44, v44
	s_nop 0
	v_mul_f32_e32 v44, v46, v44
	v_mul_f32_e32 v42, v44, v42
	v_mul_f32_e32 v44, 0xbfb8aa3b, v47
	v_exp_f32_e32 v44, v44
	s_nop 0
	v_add_f32_e32 v44, 1.0, v44
	v_rcp_f32_e32 v44, v44
	s_nop 0
	v_mul_f32_e32 v44, v47, v44
	v_mul_f32_e32 v43, v44, v43
	v_mul_f32_e32 v44, 0xbfb8aa3b, v36
	v_exp_f32_e32 v44, v44
	s_nop 0
	v_add_f32_e32 v44, 1.0, v44
	v_rcp_f32_e32 v44, v44
	s_nop 0
	v_mul_f32_e32 v36, v36, v44
	v_mul_f32_e32 v36, v36, v32
	v_mul_f32_e32 v32, 0xbfb8aa3b, v37
	v_exp_f32_e32 v32, v32
	s_nop 0
	v_add_f32_e32 v32, 1.0, v32
	v_rcp_f32_e32 v32, v32
	s_nop 0
	v_mul_f32_e32 v32, v37, v32
	v_mul_f32_e32 v37, v32, v33
	v_mul_f32_e32 v32, 0xbfb8aa3b, v38
	v_exp_f32_e32 v32, v32
	s_nop 0
	v_add_f32_e32 v32, 1.0, v32
	v_rcp_f32_e32 v32, v32
	s_nop 0
	v_mul_f32_e32 v32, v38, v32
	v_mul_f32_e32 v38, v32, v34
	v_mul_f32_e32 v32, 0xbfb8aa3b, v39
	v_exp_f32_e32 v32, v32
	s_nop 0
	v_add_f32_e32 v32, 1.0, v32
	v_rcp_f32_e32 v32, v32
	s_nop 0
	v_mul_f32_e32 v32, v39, v32
	v_mul_f32_e32 v35, v32, v35
	v_cvt_pk_bf16_f32 v32, v40, v41
	v_cvt_pk_bf16_f32 v33, v42, v43
	v_cvt_pk_bf16_f32 v34, v36, v37
	v_add_u32_e32 v36, 0x90, v142
	v_mad_i64_i32 v[36:37], s[26:27], v36, s8, v[116:117]
	v_lshl_add_u64 v[36:37], v[36:37], 0, v[118:119]
	v_cvt_pk_bf16_f32 v35, v38, v35
	global_store_dwordx4 v[36:37], v[32:35], off sc1
	s_nop 1
	v_mul_f32_e32 v32, 0xbfb8aa3b, v28
	v_exp_f32_e32 v32, v32
	s_nop 0
	v_add_f32_e32 v32, 1.0, v32
	v_rcp_f32_e32 v32, v32
	s_nop 0
	v_mul_f32_e32 v28, v28, v32
	v_mul_f32_e32 v24, v28, v24
	v_mul_f32_e32 v28, 0xbfb8aa3b, v29
	v_exp_f32_e32 v28, v28
	s_nop 0
	v_add_f32_e32 v28, 1.0, v28
	v_rcp_f32_e32 v28, v28
	s_nop 0
	v_mul_f32_e32 v28, v29, v28
	v_mul_f32_e32 v25, v28, v25
	v_mul_f32_e32 v28, 0xbfb8aa3b, v30
	v_exp_f32_e32 v28, v28
	s_nop 0
	v_add_f32_e32 v28, 1.0, v28
	v_rcp_f32_e32 v28, v28
	s_nop 0
	v_mul_f32_e32 v28, v30, v28
	v_mul_f32_e32 v26, v28, v26
	v_mul_f32_e32 v28, 0xbfb8aa3b, v31
	v_exp_f32_e32 v28, v28
	s_nop 0
	v_add_f32_e32 v28, 1.0, v28
	v_rcp_f32_e32 v28, v28
	s_nop 0
	v_mul_f32_e32 v28, v31, v28
	v_mul_f32_e32 v27, v28, v27
	v_mul_f32_e32 v28, 0xbfb8aa3b, v20
	v_exp_f32_e32 v28, v28
	s_nop 0
	v_add_f32_e32 v28, 1.0, v28
	v_rcp_f32_e32 v28, v28
	s_nop 0
	v_mul_f32_e32 v20, v20, v28
	v_mul_f32_e32 v20, v20, v16
	v_mul_f32_e32 v16, 0xbfb8aa3b, v21
	v_exp_f32_e32 v16, v16
	s_nop 0
	v_add_f32_e32 v16, 1.0, v16
	v_rcp_f32_e32 v16, v16
	s_nop 0
	v_mul_f32_e32 v16, v21, v16
	v_mul_f32_e32 v21, v16, v17
	v_mul_f32_e32 v16, 0xbfb8aa3b, v22
	v_exp_f32_e32 v16, v16
	s_nop 0
	v_add_f32_e32 v16, 1.0, v16
	v_rcp_f32_e32 v16, v16
	s_nop 0
	v_mul_f32_e32 v16, v22, v16
	v_mul_f32_e32 v22, v16, v18
	v_mul_f32_e32 v16, 0xbfb8aa3b, v23
	v_exp_f32_e32 v16, v16
	s_nop 0
	v_add_f32_e32 v16, 1.0, v16
	v_rcp_f32_e32 v16, v16
	s_nop 0
	v_mul_f32_e32 v16, v23, v16
	v_mul_f32_e32 v19, v16, v19
	v_cvt_pk_bf16_f32 v16, v24, v25
	v_cvt_pk_bf16_f32 v17, v26, v27
	v_cvt_pk_bf16_f32 v18, v20, v21
	v_add_u32_e32 v20, 0xa0, v142
	v_mad_i64_i32 v[20:21], s[26:27], v20, s8, v[116:117]
	v_lshl_add_u64 v[20:21], v[20:21], 0, v[118:119]
	v_cvt_pk_bf16_f32 v19, v22, v19
	global_store_dwordx4 v[20:21], v[16:19], off sc1
	s_nop 1
	v_mul_f32_e32 v16, 0xbfb8aa3b, v12
	v_exp_f32_e32 v16, v16
	s_nop 0
	v_add_f32_e32 v16, 1.0, v16
	v_rcp_f32_e32 v16, v16
	s_nop 0
	v_mul_f32_e32 v12, v12, v16
	v_mul_f32_e32 v8, v12, v8
	v_mul_f32_e32 v12, 0xbfb8aa3b, v13
	v_exp_f32_e32 v12, v12
	s_nop 0
	v_add_f32_e32 v12, 1.0, v12
	v_rcp_f32_e32 v12, v12
	s_nop 0
	v_mul_f32_e32 v12, v13, v12
	v_mul_f32_e32 v9, v12, v9
	v_mul_f32_e32 v12, 0xbfb8aa3b, v14
	v_exp_f32_e32 v12, v12
	s_nop 0
	v_add_f32_e32 v12, 1.0, v12
	v_rcp_f32_e32 v12, v12
	s_nop 0
	v_mul_f32_e32 v12, v14, v12
	v_mul_f32_e32 v10, v12, v10
	v_mul_f32_e32 v12, 0xbfb8aa3b, v15
	v_exp_f32_e32 v12, v12
	s_nop 0
	v_add_f32_e32 v12, 1.0, v12
	v_rcp_f32_e32 v12, v12
	s_nop 0
	v_mul_f32_e32 v12, v15, v12
	v_mul_f32_e32 v11, v12, v11
	v_mul_f32_e32 v12, 0xbfb8aa3b, v4
	v_exp_f32_e32 v12, v12
	s_nop 0
	v_add_f32_e32 v12, 1.0, v12
	v_rcp_f32_e32 v12, v12
	s_nop 0
	v_mul_f32_e32 v4, v4, v12
	v_mul_f32_e32 v4, v4, v0
	v_mul_f32_e32 v0, 0xbfb8aa3b, v5
	v_exp_f32_e32 v0, v0
	s_nop 0
	v_add_f32_e32 v0, 1.0, v0
	v_rcp_f32_e32 v0, v0
	s_nop 0
	v_mul_f32_e32 v0, v5, v0
	v_mul_f32_e32 v5, v0, v1
	v_mul_f32_e32 v0, 0xbfb8aa3b, v6
	v_exp_f32_e32 v0, v0
	s_nop 0
	v_add_f32_e32 v0, 1.0, v0
	v_rcp_f32_e32 v0, v0
	s_nop 0
	v_mul_f32_e32 v0, v6, v0
	v_mul_f32_e32 v6, v0, v2
	v_mul_f32_e32 v0, 0xbfb8aa3b, v7
	v_exp_f32_e32 v0, v0
	s_nop 0
	v_add_f32_e32 v0, 1.0, v0
	v_rcp_f32_e32 v0, v0
	s_nop 0
	v_mul_f32_e32 v0, v7, v0
	v_mul_f32_e32 v3, v0, v3
	v_cvt_pk_bf16_f32 v0, v8, v9
	v_cvt_pk_bf16_f32 v1, v10, v11
	v_cvt_pk_bf16_f32 v2, v4, v5
	v_add_u32_e32 v4, 0xb0, v142
	v_mad_i64_i32 v[4:5], s[26:27], v4, s8, v[116:117]
	v_lshl_add_u64 v[4:5], v[4:5], 0, v[118:119]
	s_mov_b64 s[26:27], -1
	v_cvt_pk_bf16_f32 v3, v6, v3
	global_store_dwordx4 v[4:5], v[0:3], off sc1
	s_cbranch_vccnz .LBB0_1702
	s_andn2_b64 vcc, exec, s[2:3]
	s_cbranch_vccnz .LBB0_1701
	s_barrier
	s_branch .LBB0_1701

.LBB0_1828:
	v_readlane_b32 s60, v251, 2
	v_lshlrev_b64 v[18:19], 10, v[208:209]
	s_and_b64 s[44:45], s[44:45], exec
	v_readlane_b32 s61, v251, 3
	s_cselect_b32 s44, s60, s81
	s_cselect_b32 s45, s61, s84
	s_and_b64 s[26:27], exec, s[26:27]
	v_lshl_add_u64 v[18:19], v[18:19], 0, v[216:217]
	s_cselect_b32 s27, s45, s91
	s_cselect_b32 s26, s44, s90
	v_lshlrev_b64 v[180:181], 2, v[18:19]
	v_lshl_add_u64 v[28:29], s[26:27], 0, v[180:181]
	global_load_dwordx4 v[34:37], v[28:29], off
	v_mov_b32_e32 v18, v9
	v_mov_b32_e32 v19, v202
	s_waitcnt vmcnt(1)
	v_pk_add_f32 v[12:13], v[12:13], 1.0 op_sel_hi:[1,0]
	v_pk_add_f32 v[22:23], v[10:11], 1.0 op_sel_hi:[1,0]
	v_lshlrev_b64 v[30:31], 10, v[214:215]
	v_pk_mul_f32 v[10:11], v[12:13], 0.5 op_sel_hi:[1,0]
	v_pk_mul_f32 v[12:13], v[22:23], 0.5 op_sel_hi:[1,0]
	v_lshl_add_u64 v[22:23], v[30:31], 0, v[216:217]
	v_lshlrev_b64 v[22:23], 2, v[22:23]
	v_lshl_add_u64 v[30:31], s[90:91], 0, v[180:181]
	v_lshl_add_u64 v[32:33], s[26:27], 0, v[22:23]
	s_mov_b64 s[8:9], 0x80000
	s_and_b64 vcc, exec, s[40:41]
	v_mov_b32_e32 v211, 1.0
	v_mov_b32_e32 v213, 0
	v_readlane_b32 s62, v251, 4
	v_readlane_b32 s63, v251, 5
	v_readlane_b32 s64, v251, 6
	v_readlane_b32 s65, v251, 7
	v_readlane_b32 s66, v251, 8
	v_readlane_b32 s67, v251, 9
	v_readlane_b32 s68, v251, 10
	v_readlane_b32 s69, v251, 11
	v_readlane_b32 s70, v251, 12
	v_readlane_b32 s71, v251, 13
	v_readlane_b32 s72, v251, 14
	v_readlane_b32 s73, v251, 15
	v_readlane_b32 s74, v251, 16
	v_readlane_b32 s75, v251, 17
	s_waitcnt vmcnt(0)
	v_sub_f32_e32 v35, v35, v0
	v_sub_f32_e32 v34, v34, v0
	v_sub_f32_e32 v37, v37, v0
	v_sub_f32_e32 v36, v36, v0
	v_pk_mul_f32 v[36:37], v[18:19], v[36:37] op_sel_hi:[0,1]
	v_pk_mul_f32 v[34:35], v[18:19], v[34:35] op_sel_hi:[0,1]
	v_pk_fma_f32 v[34:35], v[224:225], v[34:35], v[228:229]
	v_pk_fma_f32 v[36:37], v[222:223], v[36:37], v[226:227]
	v_pk_fma_f32 v[34:35], v[176:177], v[12:13], v[34:35]
	v_pk_fma_f32 v[36:37], v[178:179], v[10:11], v[36:37]
	global_store_dwordx4 v[30:31], v[34:37], off sc1
	global_load_dwordx4 v[46:49], v[32:33], off
	s_waitcnt vmcnt(0)
	v_sub_f32_e32 v41, v49, v1
	v_lshlrev_b64 v[34:35], 10, v[218:219]
	v_lshl_add_u64 v[34:35], v[34:35], 0, v[216:217]
	v_lshlrev_b64 v[36:37], 2, v[34:35]
	v_lshl_add_u64 v[34:35], s[90:91], 0, v[22:23]
	v_sub_f32_e32 v23, v47, v1
	v_sub_f32_e32 v22, v46, v1
	v_sub_f32_e32 v40, v48, v1
	v_pk_mul_f32 v[40:41], v[18:19], v[40:41] op_sel:[1,0]
	v_pk_mul_f32 v[22:23], v[18:19], v[22:23] op_sel:[1,0]
	v_pk_fma_f32 v[40:41], v[222:223], v[40:41], v[226:227]
	v_pk_fma_f32 v[22:23], v[224:225], v[22:23], v[228:229]
	v_pk_fma_f32 v[48:49], v[174:175], v[10:11], v[40:41]
	v_pk_fma_f32 v[46:47], v[172:173], v[12:13], v[22:23]
	v_lshl_add_u64 v[38:39], s[26:27], 0, v[36:37]
	global_store_dwordx4 v[34:35], v[46:49], off sc1
	global_load_dwordx4 v[172:175], v[38:39], off
	v_mov_b32_e32 v22, v207
	v_mov_b32_e32 v23, v204
	v_lshl_add_u64 v[46:47], s[90:91], 0, v[36:37]
	v_lshlrev_b64 v[40:41], 10, v[220:221]
	v_lshl_add_u64 v[40:41], v[40:41], 0, v[216:217]
	v_lshlrev_b64 v[40:41], 2, v[40:41]
	v_lshl_add_u64 v[48:49], s[26:27], 0, v[40:41]
	v_lshl_add_u64 v[40:41], s[90:91], 0, v[40:41]
	s_waitcnt vmcnt(0)
	v_sub_f32_e32 v37, v173, v2
	v_sub_f32_e32 v36, v172, v2
	v_sub_f32_e32 v173, v175, v2
	v_sub_f32_e32 v172, v174, v2
	v_pk_mul_f32 v[172:173], v[22:23], v[172:173] op_sel_hi:[0,1]
	v_pk_mul_f32 v[36:37], v[22:23], v[36:37] op_sel_hi:[0,1]
	v_pk_fma_f32 v[36:37], v[224:225], v[36:37], v[228:229]
	v_pk_fma_f32 v[172:173], v[222:223], v[172:173], v[226:227]
	v_pk_fma_f32 v[168:169], v[168:169], v[12:13], v[36:37]
	v_pk_fma_f32 v[170:171], v[170:171], v[10:11], v[172:173]
	global_store_dwordx4 v[46:47], v[168:171], off sc1
	global_load_dwordx4 v[170:173], v[48:49], off
	v_lshl_add_u64 v[174:175], v[180:181], 0, s[8:9]
	v_lshl_add_u64 v[168:169], s[26:27], 0, v[174:175]
	s_waitcnt vmcnt(0)
	v_sub_f32_e32 v37, v171, v3
	v_sub_f32_e32 v36, v170, v3
	v_sub_f32_e32 v171, v173, v3
	v_sub_f32_e32 v170, v172, v3
	v_pk_mul_f32 v[170:171], v[204:205], v[170:171] op_sel_hi:[0,1]
	v_pk_mul_f32 v[36:37], v[204:205], v[36:37] op_sel_hi:[0,1]
	v_pk_fma_f32 v[36:37], v[224:225], v[36:37], v[228:229]
	v_pk_fma_f32 v[170:171], v[222:223], v[170:171], v[226:227]
	v_pk_fma_f32 v[164:165], v[164:165], v[12:13], v[36:37]
	v_pk_fma_f32 v[166:167], v[166:167], v[10:11], v[170:171]
	global_store_dwordx4 v[40:41], v[164:167], off sc1
	global_load_dwordx4 v[170:173], v[168:169], off
	v_mov_b32_e32 v36, v45
	v_add_u32_e32 v164, 0x90, v208
	v_mov_b32_e32 v37, v42
	v_ashrrev_i32_e32 v165, 31, v164
	v_lshlrev_b64 v[164:165], 10, v[164:165]
	v_lshl_add_u64 v[166:167], v[164:165], 0, v[216:217]
	v_lshl_add_u64 v[164:165], s[90:91], 0, v[174:175]
	v_lshlrev_b64 v[174:175], 2, v[166:167]
	v_lshl_add_u64 v[166:167], s[26:27], 0, v[174:175]
	s_waitcnt vmcnt(0)
	v_sub_f32_e32 v171, v171, v4
	v_sub_f32_e32 v170, v170, v4
	v_sub_f32_e32 v173, v173, v4
	v_sub_f32_e32 v172, v172, v4
	v_pk_mul_f32 v[172:173], v[36:37], v[172:173] op_sel_hi:[0,1]
	v_pk_mul_f32 v[170:171], v[36:37], v[170:171] op_sel_hi:[0,1]
	v_pk_fma_f32 v[170:171], v[224:225], v[170:171], v[228:229]
	v_pk_fma_f32 v[172:173], v[222:223], v[172:173], v[226:227]
	v_pk_fma_f32 v[160:161], v[160:161], v[12:13], v[170:171]
	v_pk_fma_f32 v[162:163], v[162:163], v[10:11], v[172:173]
	global_store_dwordx4 v[164:165], v[160:163], off sc1
	global_load_dwordx4 v[170:173], v[166:167], off
	s_waitcnt vmcnt(0)
	v_sub_f32_e32 v171, v171, v5
	v_add_u32_e32 v160, 0xa0, v208
	v_ashrrev_i32_e32 v161, 31, v160
	v_sub_f32_e32 v170, v170, v5
	v_sub_f32_e32 v173, v173, v5
	v_sub_f32_e32 v172, v172, v5
	v_lshlrev_b64 v[160:161], 10, v[160:161]
	v_pk_mul_f32 v[172:173], v[42:43], v[172:173] op_sel_hi:[0,1]
	v_pk_mul_f32 v[170:171], v[42:43], v[170:171] op_sel_hi:[0,1]
	v_lshl_add_u64 v[160:161], v[160:161], 0, v[216:217]
	v_pk_fma_f32 v[170:171], v[224:225], v[170:171], v[228:229]
	v_pk_fma_f32 v[172:173], v[222:223], v[172:173], v[226:227]
	v_lshlrev_b64 v[176:177], 2, v[160:161]
	v_lshl_add_u64 v[160:161], s[90:91], 0, v[174:175]
	v_pk_fma_f32 v[158:159], v[158:159], v[10:11], v[172:173]
	v_pk_fma_f32 v[156:157], v[156:157], v[12:13], v[170:171]
	v_lshl_add_u64 v[162:163], s[26:27], 0, v[176:177]
	global_store_dwordx4 v[160:161], v[156:159], off sc1
	global_load_dwordx4 v[170:173], v[162:163], off
	s_waitcnt vmcnt(0)
	v_sub_f32_e32 v171, v171, v6
	v_add_u32_e32 v156, 0xb0, v208
	v_ashrrev_i32_e32 v157, 31, v156
	v_sub_f32_e32 v170, v170, v6
	v_sub_f32_e32 v173, v173, v6
	v_sub_f32_e32 v172, v172, v6
	v_lshlrev_b64 v[156:157], 10, v[156:157]
	v_pk_mul_f32 v[172:173], v[24:25], v[172:173] op_sel_hi:[0,1]
	v_pk_mul_f32 v[170:171], v[24:25], v[170:171] op_sel_hi:[0,1]
	v_lshl_add_u64 v[156:157], v[156:157], 0, v[216:217]
	v_pk_fma_f32 v[170:171], v[224:225], v[170:171], v[228:229]
	v_pk_fma_f32 v[172:173], v[222:223], v[172:173], v[226:227]
	v_lshlrev_b64 v[174:175], 2, v[156:157]
	v_lshl_add_u64 v[156:157], s[90:91], 0, v[176:177]
	v_pk_fma_f32 v[154:155], v[154:155], v[10:11], v[172:173]
	v_pk_fma_f32 v[152:153], v[152:153], v[12:13], v[170:171]
	v_lshl_add_u64 v[158:159], s[26:27], 0, v[174:175]
	global_store_dwordx4 v[156:157], v[152:155], off sc1
	global_load_dwordx4 v[170:173], v[158:159], off
	s_nop 0
	v_lshl_add_u64 v[152:153], s[90:91], 0, v[174:175]
	s_waitcnt vmcnt(0)
	v_sub_f32_e32 v155, v171, v7
	v_sub_f32_e32 v154, v170, v7
	v_sub_f32_e32 v171, v173, v7
	v_sub_f32_e32 v170, v172, v7
	v_pk_mul_f32 v[170:171], v[26:27], v[170:171] op_sel_hi:[0,1]
	v_pk_mul_f32 v[154:155], v[26:27], v[154:155] op_sel_hi:[0,1]
	v_pk_fma_f32 v[154:155], v[224:225], v[154:155], v[228:229]
	v_pk_fma_f32 v[170:171], v[222:223], v[170:171], v[226:227]
	v_pk_fma_f32 v[148:149], v[148:149], v[12:13], v[154:155]
	v_pk_fma_f32 v[150:151], v[150:151], v[10:11], v[170:171]
	global_store_dwordx4 v[152:153], v[148:151], off sc1
	global_load_dwordx4 v[10:13], v[20:21], off offset:64
	v_mov_b32_e32 v154, 0
	v_mov_b32_e32 v150, 1.0
	v_mov_b32_e32 v151, 1.0
	v_mov_b32_e32 v155, 0
	s_cbranch_vccnz .LBB0_1830
	global_load_dwordx4 v[148:151], v[16:17], off offset:64
	global_load_dwordx4 v[170:173], v[14:15], off offset:64
	s_waitcnt vmcnt(1)
	v_pk_mul_f32 v[150:151], v[150:151], s[28:29] op_sel_hi:[1,0]
	v_pk_mul_f32 v[210:211], v[148:149], s[28:29] op_sel_hi:[1,0]
	s_waitcnt vmcnt(0)
	v_pk_mul_f32 v[154:155], v[172:173], s[28:29] op_sel_hi:[1,0]
	v_pk_mul_f32 v[212:213], v[170:171], s[28:29] op_sel_hi:[1,0]
.LBB0_1830:
	global_load_dwordx4 v[170:173], v[28:29], off offset:64
	s_waitcnt vmcnt(1)
	v_pk_add_f32 v[12:13], v[12:13], 1.0 op_sel_hi:[1,0]
	v_pk_add_f32 v[10:11], v[10:11], 1.0 op_sel_hi:[1,0]
	v_mov_b32_e32 v8, v18
	v_mov_b32_e32 v148, v18
	v_mov_b32_e32 v149, v9
	v_pk_mul_f32 v[174:175], v[12:13], 0.5 op_sel_hi:[1,0]
	v_pk_mul_f32 v[176:177], v[10:11], 0.5 op_sel_hi:[1,0]
	v_mov_b32_e32 v203, v19
	v_mov_b32_e32 v206, v22
	v_mov_b32_e32 v205, v23
	v_mov_b32_e32 v44, v36
	v_mov_b32_e32 v43, v37
	v_mov_b32_e32 v25, v24
	v_mov_b32_e32 v27, v26
	v_readlane_b32 s70, v255, 18
	s_and_b64 vcc, exec, s[40:41]
	s_movk_i32 s60, 0x306
	s_movk_i32 s61, 0x5a
	s_movk_i32 s62, 0xa5
	s_movk_i32 s63, 0x130
	s_movk_i32 s66, 0x22e
	s_movk_i32 s67, 0x210
	s_movk_i32 s68, 0x1000
	v_readlane_b32 s71, v255, 19
	s_waitcnt vmcnt(0)
	v_sub_f32_e32 v11, v171, v0
	v_sub_f32_e32 v10, v170, v0
	v_sub_f32_e32 v13, v173, v0
	v_sub_f32_e32 v12, v172, v0
	v_pk_mul_f32 v[12:13], v[148:149], v[12:13]
	v_pk_mul_f32 v[10:11], v[8:9], v[10:11]
	v_pk_fma_f32 v[12:13], v[150:151], v[12:13], v[154:155]
	v_pk_fma_f32 v[10:11], v[210:211], v[10:11], v[212:213]
	v_pk_fma_f32 v[12:13], v[146:147], v[174:175], v[12:13]
	v_pk_fma_f32 v[10:11], v[144:145], v[176:177], v[10:11]
	global_store_dwordx4 v[30:31], v[10:13], off offset:64 sc1
	global_load_dwordx4 v[10:13], v[32:33], off offset:64
	v_mov_b32_e32 v144, v202
	v_mov_b32_e32 v145, v19
	s_waitcnt vmcnt(0)
	v_sub_f32_e32 v11, v11, v1
	v_sub_f32_e32 v10, v10, v1
	v_sub_f32_e32 v13, v13, v1
	v_sub_f32_e32 v12, v12, v1
	v_pk_mul_f32 v[12:13], v[144:145], v[12:13]
	v_pk_mul_f32 v[10:11], v[202:203], v[10:11]
	v_pk_fma_f32 v[12:13], v[150:151], v[12:13], v[154:155]
	v_pk_fma_f32 v[10:11], v[210:211], v[10:11], v[212:213]
	v_pk_fma_f32 v[12:13], v[142:143], v[174:175], v[12:13]
	v_pk_fma_f32 v[10:11], v[140:141], v[176:177], v[10:11]
	global_store_dwordx4 v[34:35], v[10:13], off offset:64 sc1
	global_load_dwordx4 v[10:13], v[38:39], off offset:64
	v_mov_b32_e32 v140, v22
	v_mov_b32_e32 v141, v207
	s_waitcnt vmcnt(0)
	v_sub_f32_e32 v11, v11, v2
	v_sub_f32_e32 v10, v10, v2
	v_sub_f32_e32 v13, v13, v2
	v_sub_f32_e32 v12, v12, v2
	v_pk_mul_f32 v[12:13], v[140:141], v[12:13]
	v_pk_mul_f32 v[10:11], v[206:207], v[10:11]
	v_pk_fma_f32 v[12:13], v[150:151], v[12:13], v[154:155]
	v_pk_fma_f32 v[10:11], v[210:211], v[10:11], v[212:213]
	v_pk_fma_f32 v[12:13], v[138:139], v[174:175], v[12:13]
	v_pk_fma_f32 v[10:11], v[136:137], v[176:177], v[10:11]
	global_store_dwordx4 v[46:47], v[10:13], off offset:64 sc1
	global_load_dwordx4 v[10:13], v[48:49], off offset:64
	v_mov_b32_e32 v136, v204
	v_mov_b32_e32 v137, v23
	s_waitcnt vmcnt(0)
	v_sub_f32_e32 v11, v11, v3
	v_sub_f32_e32 v10, v10, v3
	v_sub_f32_e32 v13, v13, v3
	v_sub_f32_e32 v12, v12, v3
	v_pk_mul_f32 v[12:13], v[136:137], v[12:13]
	v_pk_mul_f32 v[10:11], v[204:205], v[10:11]
	v_pk_fma_f32 v[12:13], v[150:151], v[12:13], v[154:155]
	v_pk_fma_f32 v[10:11], v[210:211], v[10:11], v[212:213]
	v_pk_fma_f32 v[12:13], v[134:135], v[174:175], v[12:13]
	v_pk_fma_f32 v[10:11], v[132:133], v[176:177], v[10:11]
	global_store_dwordx4 v[40:41], v[10:13], off offset:64 sc1
	global_load_dwordx4 v[10:13], v[168:169], off offset:64
	v_mov_b32_e32 v132, v36
	v_mov_b32_e32 v133, v45
	v_mov_b32_e32 v134, 0
	v_mov_b32_e32 v135, 0
	s_waitcnt vmcnt(0)
	v_sub_f32_e32 v11, v11, v4
	v_sub_f32_e32 v10, v10, v4
	v_sub_f32_e32 v13, v13, v4
	v_sub_f32_e32 v12, v12, v4
	v_pk_mul_f32 v[12:13], v[132:133], v[12:13]
	v_pk_mul_f32 v[10:11], v[44:45], v[10:11]
	v_pk_fma_f32 v[12:13], v[150:151], v[12:13], v[154:155]
	v_pk_fma_f32 v[10:11], v[210:211], v[10:11], v[212:213]
	v_pk_fma_f32 v[12:13], v[130:131], v[174:175], v[12:13]
	v_pk_fma_f32 v[10:11], v[128:129], v[176:177], v[10:11]
	global_store_dwordx4 v[164:165], v[10:13], off offset:64 sc1
	global_load_dwordx4 v[10:13], v[166:167], off offset:64
	v_mov_b32_e32 v128, v42
	v_mov_b32_e32 v129, v37
	v_mov_b32_e32 v130, 0
	v_mov_b32_e32 v131, 0
	s_waitcnt vmcnt(0)
	v_sub_f32_e32 v11, v11, v5
	v_sub_f32_e32 v10, v10, v5
	v_sub_f32_e32 v13, v13, v5
	v_sub_f32_e32 v12, v12, v5
	v_pk_mul_f32 v[12:13], v[128:129], v[12:13]
	v_pk_mul_f32 v[10:11], v[42:43], v[10:11]
	v_pk_fma_f32 v[12:13], v[150:151], v[12:13], v[154:155]
	v_pk_fma_f32 v[10:11], v[210:211], v[10:11], v[212:213]
	v_pk_fma_f32 v[12:13], v[126:127], v[174:175], v[12:13]
	v_pk_fma_f32 v[10:11], v[124:125], v[176:177], v[10:11]
	global_store_dwordx4 v[160:161], v[10:13], off offset:64 sc1
	global_load_dwordx4 v[10:13], v[162:163], off offset:64
	v_mov_b32_e32 v124, v24
	v_mov_b32_e32 v125, v24
	v_mov_b32_e32 v126, 1.0
	v_mov_b32_e32 v127, 1.0
	s_waitcnt vmcnt(0)
	v_sub_f32_e32 v11, v11, v6
	v_sub_f32_e32 v10, v10, v6
	v_sub_f32_e32 v13, v13, v6
	v_sub_f32_e32 v12, v12, v6
	v_pk_mul_f32 v[12:13], v[124:125], v[12:13]
	v_pk_mul_f32 v[10:11], v[24:25], v[10:11]
	v_pk_fma_f32 v[12:13], v[150:151], v[12:13], v[154:155]
	v_pk_fma_f32 v[10:11], v[210:211], v[10:11], v[212:213]
	v_pk_fma_f32 v[12:13], v[122:123], v[174:175], v[12:13]
	v_pk_fma_f32 v[10:11], v[120:121], v[176:177], v[10:11]
	global_store_dwordx4 v[156:157], v[10:13], off offset:64 sc1
	global_load_dwordx4 v[10:13], v[158:159], off offset:64
	v_mov_b32_e32 v120, v26
	v_mov_b32_e32 v121, v26
	v_mov_b32_e32 v122, 1.0
	v_mov_b32_e32 v123, 1.0
	s_waitcnt vmcnt(0)
	v_sub_f32_e32 v11, v11, v7
	v_sub_f32_e32 v10, v10, v7
	v_sub_f32_e32 v13, v13, v7
	v_sub_f32_e32 v12, v12, v7
	v_pk_mul_f32 v[12:13], v[120:121], v[12:13]
	v_pk_mul_f32 v[10:11], v[26:27], v[10:11]
	v_pk_fma_f32 v[12:13], v[150:151], v[12:13], v[154:155]
	v_pk_fma_f32 v[10:11], v[210:211], v[10:11], v[212:213]
	v_pk_fma_f32 v[12:13], v[118:119], v[174:175], v[12:13]
	v_pk_fma_f32 v[10:11], v[116:117], v[176:177], v[10:11]
	global_store_dwordx4 v[152:153], v[10:13], off offset:64 sc1
	global_load_dwordx4 v[10:13], v[20:21], off offset:512
	v_mov_b32_e32 v118, 0
	v_mov_b32_e32 v116, 1.0
	s_cbranch_vccnz .LBB0_1832
	global_load_dwordx4 v[170:173], v[16:17], off offset:512
	global_load_dwordx4 v[174:177], v[14:15], off offset:512
	s_waitcnt vmcnt(1)
	v_pk_mul_f32 v[122:123], v[172:173], s[28:29] op_sel_hi:[1,0]
	v_pk_mul_f32 v[126:127], v[170:171], s[28:29] op_sel_hi:[1,0]
	s_waitcnt vmcnt(0)
	v_pk_mul_f32 v[130:131], v[176:177], s[28:29] op_sel_hi:[1,0]
	v_pk_mul_f32 v[134:135], v[174:175], s[28:29] op_sel_hi:[1,0]
.LBB0_1832:
	global_load_dwordx4 v[170:173], v[28:29], off offset:512
	s_waitcnt vmcnt(1)
	v_pk_add_f32 v[12:13], v[12:13], 1.0 op_sel_hi:[1,0]
	v_pk_add_f32 v[10:11], v[10:11], 1.0 op_sel_hi:[1,0]
	v_pk_mul_f32 v[138:139], v[12:13], 0.5 op_sel_hi:[1,0]
	v_pk_mul_f32 v[142:143], v[10:11], 0.5 op_sel_hi:[1,0]
	s_and_b64 vcc, exec, s[40:41]
	v_mov_b32_e32 v117, 1.0
	v_mov_b32_e32 v119, 0
	s_waitcnt vmcnt(0)
	v_sub_f32_e32 v11, v171, v0
	v_sub_f32_e32 v10, v170, v0
	v_sub_f32_e32 v13, v173, v0
	v_sub_f32_e32 v12, v172, v0
	v_pk_mul_f32 v[12:13], v[148:149], v[12:13]
	v_pk_mul_f32 v[10:11], v[8:9], v[10:11]
	v_pk_fma_f32 v[12:13], v[122:123], v[12:13], v[130:131]
	v_pk_fma_f32 v[10:11], v[126:127], v[10:11], v[134:135]
	v_pk_fma_f32 v[12:13], v[114:115], v[138:139], v[12:13]
	v_pk_fma_f32 v[10:11], v[112:113], v[142:143], v[10:11]
	global_store_dwordx4 v[30:31], v[10:13], off offset:512 sc1
	global_load_dwordx4 v[10:13], v[32:33], off offset:512
	s_waitcnt vmcnt(0)
	v_sub_f32_e32 v11, v11, v1
	v_sub_f32_e32 v10, v10, v1
	v_sub_f32_e32 v13, v13, v1
	v_sub_f32_e32 v12, v12, v1
	v_pk_mul_f32 v[12:13], v[144:145], v[12:13]
	v_pk_mul_f32 v[10:11], v[202:203], v[10:11]
	v_pk_fma_f32 v[12:13], v[122:123], v[12:13], v[130:131]
	v_pk_fma_f32 v[10:11], v[126:127], v[10:11], v[134:135]
	v_pk_fma_f32 v[12:13], v[110:111], v[138:139], v[12:13]
	v_pk_fma_f32 v[10:11], v[108:109], v[142:143], v[10:11]
	global_store_dwordx4 v[34:35], v[10:13], off offset:512 sc1
	global_load_dwordx4 v[10:13], v[38:39], off offset:512
	s_waitcnt vmcnt(0)
	v_sub_f32_e32 v11, v11, v2
	v_sub_f32_e32 v10, v10, v2
	v_sub_f32_e32 v13, v13, v2
	v_sub_f32_e32 v12, v12, v2
	v_pk_mul_f32 v[12:13], v[140:141], v[12:13]
	v_pk_mul_f32 v[10:11], v[206:207], v[10:11]
	v_pk_fma_f32 v[12:13], v[122:123], v[12:13], v[130:131]
	v_pk_fma_f32 v[10:11], v[126:127], v[10:11], v[134:135]
	v_pk_fma_f32 v[12:13], v[106:107], v[138:139], v[12:13]
	v_pk_fma_f32 v[10:11], v[104:105], v[142:143], v[10:11]
	global_store_dwordx4 v[46:47], v[10:13], off offset:512 sc1
	global_load_dwordx4 v[10:13], v[48:49], off offset:512
	s_waitcnt vmcnt(0)
	v_sub_f32_e32 v11, v11, v3
	v_sub_f32_e32 v10, v10, v3
	v_sub_f32_e32 v13, v13, v3
	v_sub_f32_e32 v12, v12, v3
	v_pk_mul_f32 v[12:13], v[136:137], v[12:13]
	v_pk_mul_f32 v[10:11], v[204:205], v[10:11]
	v_pk_fma_f32 v[12:13], v[122:123], v[12:13], v[130:131]
	v_pk_fma_f32 v[10:11], v[126:127], v[10:11], v[134:135]
	v_pk_fma_f32 v[12:13], v[102:103], v[138:139], v[12:13]
	v_pk_fma_f32 v[10:11], v[100:101], v[142:143], v[10:11]
	global_store_dwordx4 v[40:41], v[10:13], off offset:512 sc1
	global_load_dwordx4 v[10:13], v[168:169], off offset:512
	s_waitcnt vmcnt(0)
	v_sub_f32_e32 v11, v11, v4
	v_sub_f32_e32 v10, v10, v4
	v_sub_f32_e32 v13, v13, v4
	v_sub_f32_e32 v12, v12, v4
	v_pk_mul_f32 v[12:13], v[132:133], v[12:13]
	v_pk_mul_f32 v[10:11], v[44:45], v[10:11]
	v_pk_fma_f32 v[12:13], v[122:123], v[12:13], v[130:131]
	v_pk_fma_f32 v[10:11], v[126:127], v[10:11], v[134:135]
	v_pk_fma_f32 v[12:13], v[98:99], v[138:139], v[12:13]
	v_pk_fma_f32 v[10:11], v[96:97], v[142:143], v[10:11]
	global_store_dwordx4 v[164:165], v[10:13], off offset:512 sc1
	global_load_dwordx4 v[10:13], v[166:167], off offset:512
	s_waitcnt vmcnt(0)
	v_sub_f32_e32 v11, v11, v5
	v_sub_f32_e32 v10, v10, v5
	v_sub_f32_e32 v13, v13, v5
	v_sub_f32_e32 v12, v12, v5
	v_pk_mul_f32 v[12:13], v[128:129], v[12:13]
	v_pk_mul_f32 v[10:11], v[42:43], v[10:11]
	v_pk_fma_f32 v[12:13], v[122:123], v[12:13], v[130:131]
	v_pk_fma_f32 v[10:11], v[126:127], v[10:11], v[134:135]
	v_pk_fma_f32 v[12:13], v[94:95], v[138:139], v[12:13]
	v_pk_fma_f32 v[10:11], v[92:93], v[142:143], v[10:11]
	global_store_dwordx4 v[160:161], v[10:13], off offset:512 sc1
	global_load_dwordx4 v[10:13], v[162:163], off offset:512
	s_waitcnt vmcnt(0)
	v_sub_f32_e32 v11, v11, v6
	v_sub_f32_e32 v10, v10, v6
	v_sub_f32_e32 v13, v13, v6
	v_sub_f32_e32 v12, v12, v6
	v_pk_mul_f32 v[12:13], v[124:125], v[12:13]
	v_pk_mul_f32 v[10:11], v[24:25], v[10:11]
	v_pk_fma_f32 v[12:13], v[122:123], v[12:13], v[130:131]
	v_pk_fma_f32 v[10:11], v[126:127], v[10:11], v[134:135]
	v_pk_fma_f32 v[12:13], v[90:91], v[138:139], v[12:13]
	v_pk_fma_f32 v[10:11], v[88:89], v[142:143], v[10:11]
	global_store_dwordx4 v[156:157], v[10:13], off offset:512 sc1
	global_load_dwordx4 v[10:13], v[158:159], off offset:512
	s_waitcnt vmcnt(0)
	v_sub_f32_e32 v11, v11, v7
	v_sub_f32_e32 v10, v10, v7
	v_sub_f32_e32 v13, v13, v7
	v_sub_f32_e32 v12, v12, v7
	v_pk_mul_f32 v[12:13], v[120:121], v[12:13]
	v_pk_mul_f32 v[10:11], v[26:27], v[10:11]
	v_pk_fma_f32 v[12:13], v[122:123], v[12:13], v[130:131]
	v_pk_fma_f32 v[10:11], v[126:127], v[10:11], v[134:135]
	v_pk_fma_f32 v[12:13], v[86:87], v[138:139], v[12:13]
	v_pk_fma_f32 v[10:11], v[84:85], v[142:143], v[10:11]
	global_store_dwordx4 v[152:153], v[10:13], off offset:512 sc1
	global_load_dwordx4 v[10:13], v[20:21], off offset:576
	v_mov_b32_e32 v20, 1.0
	v_mov_b32_e32 v21, 1.0
	v_mov_b32_e32 v84, 0
	v_mov_b32_e32 v85, 0
	s_cbranch_vccnz .LBB0_1834
	global_load_dwordx4 v[84:87], v[16:17], off offset:576
	s_nop 0
	global_load_dwordx4 v[14:17], v[14:15], off offset:576
	s_waitcnt vmcnt(1)
	v_pk_mul_f32 v[20:21], v[86:87], s[28:29] op_sel_hi:[1,0]
	v_pk_mul_f32 v[116:117], v[84:85], s[28:29] op_sel_hi:[1,0]
	s_waitcnt vmcnt(0)
	v_pk_mul_f32 v[84:85], v[16:17], s[28:29] op_sel_hi:[1,0]
	v_pk_mul_f32 v[118:119], v[14:15], s[28:29] op_sel_hi:[1,0]
.LBB0_1834:
	global_load_dwordx4 v[14:17], v[28:29], off offset:576
	s_waitcnt vmcnt(1)
	v_pk_add_f32 v[10:11], v[10:11], 1.0 op_sel_hi:[1,0]
	v_mov_b32_e32 v28, v18
	v_mov_b32_e32 v29, v9
	v_pk_mul_f32 v[86:87], v[10:11], 0.5 op_sel_hi:[1,0]
	v_pk_add_f32 v[12:13], v[12:13], 1.0 op_sel_hi:[1,0]
	v_mov_b32_e32 v18, v202
	v_pk_mul_f32 v[12:13], v[12:13], 0.5 op_sel_hi:[1,0]
	s_and_b64 vcc, exec, s[38:39]
	s_mov_b64 s[26:27], -1
	s_waitcnt vmcnt(0)
	v_sub_f32_e32 v11, v15, v0
	v_sub_f32_e32 v10, v14, v0
	v_sub_f32_e32 v15, v17, v0
	v_sub_f32_e32 v14, v16, v0
	v_pk_mul_f32 v[14:15], v[28:29], v[14:15]
	v_pk_mul_f32 v[8:9], v[8:9], v[10:11]
	v_pk_fma_f32 v[10:11], v[20:21], v[14:15], v[84:85]
	v_pk_fma_f32 v[8:9], v[116:117], v[8:9], v[118:119]
	v_pk_fma_f32 v[10:11], v[82:83], v[12:13], v[10:11]
	v_pk_fma_f32 v[8:9], v[80:81], v[86:87], v[8:9]
	global_store_dwordx4 v[30:31], v[8:11], off offset:576 sc1
	global_load_dwordx4 v[8:11], v[32:33], off offset:576
	s_waitcnt vmcnt(0)
	v_sub_f32_e32 v9, v9, v1
	v_sub_f32_e32 v8, v8, v1
	v_sub_f32_e32 v11, v11, v1
	v_sub_f32_e32 v10, v10, v1
	v_pk_mul_f32 v[0:1], v[18:19], v[10:11]
	v_pk_mul_f32 v[8:9], v[202:203], v[8:9]
	v_pk_fma_f32 v[0:1], v[20:21], v[0:1], v[84:85]
	v_pk_fma_f32 v[8:9], v[116:117], v[8:9], v[118:119]
	v_pk_fma_f32 v[10:11], v[78:79], v[12:13], v[0:1]
	v_pk_fma_f32 v[8:9], v[76:77], v[86:87], v[8:9]
	global_store_dwordx4 v[34:35], v[8:11], off offset:576 sc1
	global_load_dwordx4 v[8:11], v[38:39], off offset:576
	v_mov_b32_e32 v0, v22
	v_mov_b32_e32 v1, v207
	v_mov_b32_e32 v22, v204
	s_waitcnt vmcnt(0)
	v_sub_f32_e32 v9, v9, v2
	v_sub_f32_e32 v8, v8, v2
	v_sub_f32_e32 v11, v11, v2
	v_sub_f32_e32 v10, v10, v2
	v_pk_mul_f32 v[0:1], v[0:1], v[10:11]
	v_pk_mul_f32 v[8:9], v[206:207], v[8:9]
	v_pk_fma_f32 v[0:1], v[20:21], v[0:1], v[84:85]
	v_pk_fma_f32 v[8:9], v[116:117], v[8:9], v[118:119]
	v_pk_fma_f32 v[10:11], v[74:75], v[12:13], v[0:1]
	v_pk_fma_f32 v[8:9], v[72:73], v[86:87], v[8:9]
	global_store_dwordx4 v[46:47], v[8:11], off offset:576 sc1
	global_load_dwordx4 v[8:11], v[48:49], off offset:576
	s_waitcnt vmcnt(0)
	v_sub_f32_e32 v1, v9, v3
	v_sub_f32_e32 v0, v8, v3
	v_sub_f32_e32 v9, v11, v3
	v_sub_f32_e32 v8, v10, v3
	v_pk_mul_f32 v[2:3], v[22:23], v[8:9]
	v_pk_mul_f32 v[0:1], v[204:205], v[0:1]
	v_pk_fma_f32 v[2:3], v[20:21], v[2:3], v[84:85]
	v_pk_fma_f32 v[0:1], v[116:117], v[0:1], v[118:119]
	v_pk_fma_f32 v[2:3], v[70:71], v[12:13], v[2:3]
	v_pk_fma_f32 v[0:1], v[68:69], v[86:87], v[0:1]
	global_store_dwordx4 v[40:41], v[0:3], off offset:576 sc1
	global_load_dwordx4 v[0:3], v[168:169], off offset:576
	v_mov_b32_e32 v8, v36
	v_mov_b32_e32 v9, v45
	v_mov_b32_e32 v36, v42
	s_waitcnt vmcnt(0)
	v_sub_f32_e32 v1, v1, v4
	v_sub_f32_e32 v0, v0, v4
	v_sub_f32_e32 v3, v3, v4
	v_sub_f32_e32 v2, v2, v4
	v_pk_mul_f32 v[2:3], v[8:9], v[2:3]
	v_pk_mul_f32 v[0:1], v[44:45], v[0:1]
	v_pk_fma_f32 v[2:3], v[20:21], v[2:3], v[84:85]
	v_pk_fma_f32 v[0:1], v[116:117], v[0:1], v[118:119]
	v_pk_fma_f32 v[2:3], v[66:67], v[12:13], v[2:3]
	v_pk_fma_f32 v[0:1], v[64:65], v[86:87], v[0:1]
	global_store_dwordx4 v[164:165], v[0:3], off offset:576 sc1
	global_load_dwordx4 v[0:3], v[166:167], off offset:576
	v_mov_b32_e32 v4, v24
	s_waitcnt vmcnt(0)
	v_sub_f32_e32 v1, v1, v5
	v_sub_f32_e32 v0, v0, v5
	v_sub_f32_e32 v3, v3, v5
	v_sub_f32_e32 v2, v2, v5
	v_pk_mul_f32 v[2:3], v[36:37], v[2:3]
	v_pk_mul_f32 v[0:1], v[42:43], v[0:1]
	v_pk_fma_f32 v[2:3], v[20:21], v[2:3], v[84:85]
	v_pk_fma_f32 v[0:1], v[116:117], v[0:1], v[118:119]
	v_pk_fma_f32 v[2:3], v[62:63], v[12:13], v[2:3]
	v_pk_fma_f32 v[0:1], v[60:61], v[86:87], v[0:1]
	global_store_dwordx4 v[160:161], v[0:3], off offset:576 sc1
	global_load_dwordx4 v[0:3], v[162:163], off offset:576
	v_mov_b32_e32 v5, v24
	s_waitcnt vmcnt(0)
	v_sub_f32_e32 v1, v1, v6
	v_sub_f32_e32 v0, v0, v6
	v_sub_f32_e32 v3, v3, v6
	v_sub_f32_e32 v2, v2, v6
	v_pk_mul_f32 v[2:3], v[4:5], v[2:3]
	v_pk_mul_f32 v[0:1], v[24:25], v[0:1]
	v_pk_fma_f32 v[2:3], v[20:21], v[2:3], v[84:85]
	v_pk_fma_f32 v[0:1], v[116:117], v[0:1], v[118:119]
	v_pk_fma_f32 v[2:3], v[58:59], v[12:13], v[2:3]
	v_pk_fma_f32 v[0:1], v[56:57], v[86:87], v[0:1]
	global_store_dwordx4 v[156:157], v[0:3], off offset:576 sc1
	global_load_dwordx4 v[0:3], v[158:159], off offset:576
	v_mov_b32_e32 v4, v26
	v_mov_b32_e32 v5, v26
	s_waitcnt vmcnt(0)
	v_sub_f32_e32 v1, v1, v7
	v_sub_f32_e32 v0, v0, v7
	v_sub_f32_e32 v3, v3, v7
	v_sub_f32_e32 v2, v2, v7
	v_pk_mul_f32 v[2:3], v[4:5], v[2:3]
	v_pk_mul_f32 v[0:1], v[26:27], v[0:1]
	v_pk_fma_f32 v[2:3], v[20:21], v[2:3], v[84:85]
	v_pk_fma_f32 v[0:1], v[116:117], v[0:1], v[118:119]
	v_pk_fma_f32 v[2:3], v[54:55], v[12:13], v[2:3]
	v_pk_fma_f32 v[0:1], v[52:53], v[86:87], v[0:1]
	global_store_dwordx4 v[152:153], v[0:3], off offset:576 sc1
	s_cbranch_vccnz .LBB0_1794
	s_andn2_b64 vcc, exec, s[2:3]
	s_cbranch_vccnz .LBB0_1793
	s_barrier
	s_branch .LBB0_1793

.LBB0_1912:
	s_or_b64 exec, exec, s[34:35]
	v_mov_b32_e32 v24, v47
	v_mov_b32_e32 v25, v21
	v_mov_b32_e32 v26, v49
	v_mov_b32_e32 v27, v23
	v_pk_mul_f32 v[58:59], v[26:27], v[44:45] op_sel_hi:[1,0]
	v_pk_mul_f32 v[60:61], v[24:25], v[44:45] op_sel_hi:[1,0]
	global_load_dwordx4 v[24:27], v[30:31], off
	global_load_dwordx4 v[54:57], v[32:33], off
	v_readlane_b32 s8, v254, 31
	v_readlane_b32 s9, v254, 32
	s_andn2_b64 vcc, exec, s[8:9]
	s_waitcnt vmcnt(0)
	v_pk_fma_f32 v[26:27], v[58:59], v[26:27], v[56:57]
	v_cndmask_b32_e64 v21, 0, 1, s[8:9]
	v_pk_fma_f32 v[24:25], v[60:61], v[24:25], v[54:55]
	v_cmp_ne_u32_e64 s[38:39], 1, v21
	s_cbranch_vccnz .LBB0_1914
	global_store_dwordx4 v[38:39], v[24:27], off offset:-2048 sc1

.LBB0_1916:
	v_mov_b32_e32 v47, v20
	v_mov_b32_e32 v20, v44
	v_mov_b32_e32 v21, v44
	v_mov_b32_e32 v49, v22
	v_pk_mul_f32 v[48:49], v[48:49], v[20:21]
	global_load_dwordx4 v[20:23], v[30:31], off offset:1024
	global_load_dwordx4 v[24:27], v[32:33], off offset:1024
	v_mov_b32_e32 v45, v44
	v_pk_mul_f32 v[46:47], v[46:47], v[44:45]
	s_and_b64 vcc, exec, s[38:39]
	s_waitcnt vmcnt(0)
	v_pk_fma_f32 v[22:23], v[48:49], v[22:23], v[26:27]
	v_pk_fma_f32 v[20:21], v[46:47], v[20:21], v[24:25]
	s_cbranch_vccnz .LBB0_1918
	global_store_dwordx4 v[38:39], v[20:23], off offset:-1024 sc1

.LBB0_1920:
	v_mov_b32_e32 v20, v41
	v_mov_b32_e32 v21, v17
	v_mov_b32_e32 v22, v44
	v_mov_b32_e32 v23, v44
	v_mov_b32_e32 v24, v43
	v_mov_b32_e32 v25, v19
	v_pk_mul_f32 v[46:47], v[24:25], v[22:23]
	v_pk_mul_f32 v[48:49], v[20:21], v[44:45]
	global_load_dwordx4 v[20:23], v[30:31], off offset:2048
	global_load_dwordx4 v[24:27], v[32:33], off offset:2048
	s_and_b64 vcc, exec, s[38:39]
	s_waitcnt vmcnt(0)
	v_pk_fma_f32 v[22:23], v[46:47], v[22:23], v[26:27]
	v_pk_fma_f32 v[20:21], v[48:49], v[20:21], v[24:25]
	s_cbranch_vccnz .LBB0_1922
	global_store_dwordx4 v[38:39], v[20:23], off sc1

.LBB0_1924:
	v_mov_b32_e32 v41, v16
	v_mov_b32_e32 v16, v44
	v_mov_b32_e32 v17, v44
	v_mov_b32_e32 v43, v18
	v_pk_mul_f32 v[24:25], v[42:43], v[16:17]
	global_load_dwordx4 v[16:19], v[30:31], off offset:3072
	global_load_dwordx4 v[20:23], v[32:33], off offset:3072
	v_pk_mul_f32 v[26:27], v[40:41], v[44:45]
	s_and_b64 vcc, exec, s[38:39]
	s_waitcnt vmcnt(0)
	v_pk_fma_f32 v[18:19], v[24:25], v[18:19], v[22:23]
	v_pk_fma_f32 v[16:17], v[26:27], v[16:17], v[20:21]
	s_cbranch_vccnz .LBB0_1926
	global_store_dwordx4 v[38:39], v[16:19], off offset:1024 sc1

.LBB0_1980:
	s_waitcnt vmcnt(0)
	ds_write2_b32 v23, v0, v1 offset1:65
	ds_write2_b32 v23, v2, v3 offset0:130 offset1:195
	v_add_u32_e32 v0, 0x400, v23
	s_mul_hi_i32 s12, s15, 0x2e8ba2e9
	ds_write2_b32 v0, v4, v5 offset0:4 offset1:69
	ds_write2_b32 v0, v6, v7 offset0:134 offset1:199
	s_waitcnt lgkmcnt(0)
	s_barrier
	ds_read2_b32 v[0:1], v24 offset1:65
	ds_read2_b32 v[2:3], v24 offset0:130 offset1:195
	v_add_u32_e32 v6, 0x400, v24
	s_lshr_b32 s13, s12, 31
	s_ashr_i32 s12, s12, 4
	ds_read2_b32 v[4:5], v6 offset0:4 offset1:69
	ds_read2_b32 v[6:7], v6 offset0:134 offset1:199
	s_add_i32 s13, s12, s13
	s_lshl_b32 s12, s13, 6
	s_mulk_i32 s13, 0xea00
	s_add_i32 s13, s13, s11
	s_waitcnt lgkmcnt(3)
	v_cvt_pk_bf16_f32 v0, v0, v1
	s_waitcnt lgkmcnt(2)
	v_cvt_pk_bf16_f32 v1, v2, v3
	s_waitcnt lgkmcnt(1)
	v_cvt_pk_bf16_f32 v2, v4, v5
	v_add_u32_e32 v4, s13, v19
	v_ashrrev_i32_e32 v5, 31, v4
	v_readlane_b32 s8, v251, 53
	v_lshlrev_b64 v[4:5], 11, v[4:5]
	v_readlane_b32 s9, v251, 54
	s_ashr_i32 s13, s12, 31
	s_andn2_b64 vcc, exec, s[2:3]
	v_lshl_add_u64 v[4:5], s[8:9], 0, v[4:5]
	v_lshl_add_u64 v[4:5], s[12:13], 1, v[4:5]
	v_lshl_add_u64 v[4:5], v[4:5], 0, v[50:51]
	s_add_i32 s0, s0, s10
	s_waitcnt lgkmcnt(0)
	v_cvt_pk_bf16_f32 v3, v6, v7
	global_store_dwordx4 v[4:5], v[0:3], off sc1
	s_barrier
	s_cbranch_vccz .LBB0_2161
	v_mov_b64_e32 v[0:1], v[8:9]
	s_mov_b32 s11, s14
	s_mov_b32 s15, s1
	v_mov_b64_e32 v[2:3], v[10:11]
	v_mov_b64_e32 v[4:5], v[12:13]
	v_mov_b64_e32 v[6:7], v[14:15]
	s_branch .LBB0_1959

.LBB0_2034:
	s_add_i32 s10, s14, s10
	ds_write2_b32 v25, v0, v1 offset1:65
	ds_write2_b32 v25, v2, v3 offset0:130 offset1:195
	v_add_u32_e32 v0, 0x400, v25
	s_addk_i32 s10, 0xfa80
	ds_write2_b32 v0, v4, v5 offset0:4 offset1:69
	ds_write2_b32 v0, v6, v7 offset0:134 offset1:199
	v_add_u32_e32 v6, 0x400, v26
	s_ashr_i32 s12, s10, 31
	s_waitcnt lgkmcnt(0)
	s_barrier
	ds_read2_b32 v[0:1], v26 offset1:65
	ds_read2_b32 v[2:3], v26 offset0:130 offset1:195
	ds_read2_b32 v[4:5], v6 offset0:4 offset1:69
	ds_read2_b32 v[6:7], v6 offset0:134 offset1:199
	s_lshr_b32 s12, s12, 28
	s_add_i32 s12, s10, s12
	s_and_b32 s13, s12, 0x3fffff0
	v_readlane_b32 s8, v253, 57
	s_sub_i32 s10, s10, s13
	s_lshl_b32 s12, s12, 2
	v_readlane_b32 s9, v253, 58
	s_andn2_b32 s12, s12, 63
	s_waitcnt lgkmcnt(3)
	v_cvt_pk_bf16_f32 v0, v0, v1
	s_waitcnt lgkmcnt(2)
	v_cvt_pk_bf16_f32 v1, v2, v3
	s_waitcnt lgkmcnt(1)
	v_cvt_pk_bf16_f32 v2, v4, v5
	s_waitcnt lgkmcnt(0)
	v_cvt_pk_bf16_f32 v3, v6, v7
	v_lshl_add_u32 v6, s10, 6, v24
	v_mov_b64_e32 v[4:5], s[8:9]
	s_movk_i32 s8, 0x1600
	v_mad_i64_i32 v[4:5], s[16:17], v6, s8, v[4:5]
	s_ashr_i32 s13, s12, 31
	v_lshl_add_u64 v[4:5], s[12:13], 1, v[4:5]
	v_lshl_add_u64 v[4:5], v[4:5], 0, v[50:51]
	s_andn2_b64 vcc, exec, s[2:3]
	global_store_dwordx4 v[4:5], v[0:3], off sc1
	s_barrier
	s_cbranch_vccz .LBB0_2037
	s_waitcnt vmcnt(1)
	v_mov_b64_e32 v[0:1], v[8:9]
	s_mov_b32 s10, s1
	v_mov_b64_e32 v[2:3], v[10:11]
	v_mov_b64_e32 v[4:5], v[12:13]
	v_mov_b64_e32 v[6:7], v[14:15]
	s_branch .LBB0_2015

.LBB0_2075:
	s_add_i32 s1, s11, s1
	s_addk_i32 s1, 0xf7c0
	s_mul_hi_i32 s12, s1, 0x92492493
	s_waitcnt vmcnt(0)
	ds_write2_b32 v23, v0, v1 offset1:65
	ds_write2_b32 v23, v2, v3 offset0:130 offset1:195
	v_add_u32_e32 v0, 0x400, v23
	s_add_i32 s12, s12, s1
	ds_write2_b32 v0, v4, v5 offset0:4 offset1:69
	ds_write2_b32 v0, v6, v7 offset0:134 offset1:199
	s_waitcnt lgkmcnt(0)
	s_barrier
	ds_read2_b32 v[0:1], v24 offset1:65
	ds_read2_b32 v[2:3], v24 offset0:130 offset1:195
	v_add_u32_e32 v6, 0x400, v24
	s_lshr_b32 s13, s12, 31
	s_ashr_i32 s12, s12, 5
	ds_read2_b32 v[4:5], v6 offset0:4 offset1:69
	ds_read2_b32 v[6:7], v6 offset0:134 offset1:199
	s_add_i32 s12, s12, s13
	s_mul_i32 s13, s12, 56
	s_sub_i32 s1, s1, s13
	s_waitcnt lgkmcnt(3)
	v_cvt_pk_bf16_f32 v0, v0, v1
	s_waitcnt lgkmcnt(2)
	v_cvt_pk_bf16_f32 v1, v2, v3
	s_waitcnt lgkmcnt(1)
	v_cvt_pk_bf16_f32 v2, v4, v5
	v_lshl_add_u32 v4, s1, 6, v19
	v_ashrrev_i32_e32 v5, 31, v4
	v_readlane_b32 s8, v251, 56
	s_lshl_b32 s12, s12, 6
	v_lshlrev_b64 v[4:5], 11, v[4:5]
	v_readlane_b32 s9, v251, 57
	s_ashr_i32 s13, s12, 31
	s_andn2_b64 vcc, exec, s[2:3]
	v_lshl_add_u64 v[4:5], s[8:9], 0, v[4:5]
	v_lshl_add_u64 v[4:5], s[12:13], 1, v[4:5]
	v_lshl_add_u64 v[4:5], v[4:5], 0, v[50:51]
	s_mov_b32 s1, s14
	s_waitcnt lgkmcnt(0)
	v_cvt_pk_bf16_f32 v3, v6, v7
	global_store_dwordx4 v[4:5], v[0:3], off sc1
	s_barrier
	s_cbranch_vccz .LBB0_2078
	v_mov_b64_e32 v[0:1], v[8:9]
	v_mov_b64_e32 v[2:3], v[10:11]
	v_mov_b64_e32 v[4:5], v[12:13]
	v_mov_b64_e32 v[6:7], v[14:15]
	s_branch .LBB0_2056

.LBB0_2097:
	s_add_i32 s1, s11, s1
	s_waitcnt vmcnt(0)
	ds_write2_b32 v24, v0, v1 offset1:65
	ds_write2_b32 v24, v2, v3 offset0:130 offset1:195
	v_add_u32_e32 v0, 0x400, v24
	s_ashr_i32 s12, s1, 31
	ds_write2_b32 v0, v4, v5 offset0:4 offset1:69
	ds_write2_b32 v0, v6, v7 offset0:134 offset1:199
	s_waitcnt lgkmcnt(0)
	s_barrier
	ds_read2_b32 v[0:1], v25 offset1:65
	ds_read2_b32 v[2:3], v25 offset0:130 offset1:195
	v_add_u32_e32 v6, 0x400, v25
	s_lshr_b32 s12, s12, 28
	ds_read2_b32 v[4:5], v6 offset0:4 offset1:69
	ds_read2_b32 v[6:7], v6 offset0:134 offset1:199
	s_add_i32 s12, s1, s12
	s_and_b32 s13, s12, 0x3fffff0
	s_sub_i32 s1, s1, s13
	s_waitcnt lgkmcnt(3)
	v_cvt_pk_bf16_f32 v0, v0, v1
	s_waitcnt lgkmcnt(2)
	v_cvt_pk_bf16_f32 v1, v2, v3
	s_waitcnt lgkmcnt(1)
	v_cvt_pk_bf16_f32 v2, v4, v5
	v_lshl_add_u32 v4, s1, 6, v22
	s_lshl_b32 s12, s12, 2
	v_ashrrev_i32_e32 v5, 31, v4
	v_readlane_b32 s8, v253, 49
	s_andn2_b32 s12, s12, 63
	v_lshlrev_b64 v[4:5], 11, v[4:5]
	v_readlane_b32 s9, v253, 50
	s_ashr_i32 s13, s12, 31
	s_waitcnt lgkmcnt(0)
	v_cvt_pk_bf16_f32 v3, v6, v7
	s_andn2_b64 vcc, exec, s[2:3]
	v_lshl_add_u64 v[4:5], s[8:9], 0, v[4:5]
	v_lshl_add_u64 v[4:5], s[12:13], 1, v[4:5]
	v_lshl_add_u64 v[4:5], v[4:5], 0, v[50:51]
	global_store_dwordx4 v[4:5], v[0:3], off sc1
	s_mov_b32 s1, s14
	s_nop 0
	v_mov_b64_e32 v[0:1], v[8:9]
	v_mov_b64_e32 v[2:3], v[10:11]
	v_mov_b64_e32 v[4:5], v[12:13]
	v_mov_b64_e32 v[6:7], v[14:15]
	s_barrier
	s_cbranch_vccz .LBB0_2116

.LBB0_2167:
	s_waitcnt vmcnt(0)
	ds_write2_b32 v7, v1, v2 offset1:65
	ds_write2_b32 v7, v3, v4 offset0:130 offset1:195
	v_add_u32_e32 v1, 0x400, v7
	ds_write2_b32 v1, v6, v9 offset0:4 offset1:69
	ds_write2_b32 v1, v10, v11 offset0:134 offset1:199
	s_waitcnt lgkmcnt(0)
	s_barrier
	ds_read2_b32 v[2:3], v8 offset1:65
	ds_read2_b32 v[10:11], v8 offset0:130 offset1:195
	v_add_u32_e32 v1, 0x400, v8
	v_readlane_b32 s8, v253, 34
	s_and_b32 s0, s0, 0x3c0
	ds_read2_b32 v[26:27], v1 offset0:4 offset1:69
	ds_read2_b32 v[28:29], v1 offset0:134 offset1:199
	v_readlane_b32 s9, v253, 35
	s_andn2_b32 s10, s10, 63
	s_waitcnt lgkmcnt(3)
	v_cvt_pk_bf16_f32 v24, v2, v3
	v_add_u32_e32 v1, s0, v5
	v_mov_b64_e32 v[2:3], s[8:9]
	s_movk_i32 s0, 0x1600
	s_add_i32 s78, s10, 0xffffea00
	v_mad_i64_i32 v[2:3], s[12:13], v1, s0, v[2:3]
	v_lshl_add_u64 v[2:3], s[78:79], 1, v[2:3]
	v_lshl_add_u64 v[2:3], v[2:3], 0, v[50:51]
	s_andn2_b64 vcc, exec, s[2:3]
	s_waitcnt lgkmcnt(2)
	v_cvt_pk_bf16_f32 v25, v10, v11
	s_waitcnt lgkmcnt(1)
	v_cvt_pk_bf16_f32 v26, v26, v27
	s_waitcnt lgkmcnt(0)
	v_cvt_pk_bf16_f32 v27, v28, v29
	global_store_dwordx4 v[2:3], v[24:27], off sc1
	s_barrier
	s_cbranch_vccz .LBB0_2169
	s_mov_b32 s0, s14
	s_mov_b32 s10, s11
	v_mov_b32_e32 v1, v12
	v_mov_b32_e32 v2, v13
	v_mov_b32_e32 v3, v14
	v_mov_b32_e32 v4, v15
	v_mov_b32_e32 v6, v16
	v_mov_b32_e32 v9, v17
	v_mov_b32_e32 v10, v18
	v_mov_b32_e32 v11, v19
	s_branch .LBB0_2163

.LBB0_2206:
	s_add_i32 s1, s11, s1
	s_waitcnt vmcnt(0)
	ds_write2_b32 v23, v0, v1 offset1:65
	ds_write2_b32 v23, v2, v3 offset0:130 offset1:195
	v_add_u32_e32 v0, 0x400, v23
	s_mul_hi_i32 s12, s1, 0x2e8ba2e9
	ds_write2_b32 v0, v4, v5 offset0:4 offset1:69
	ds_write2_b32 v0, v6, v7 offset0:134 offset1:199
	s_waitcnt lgkmcnt(0)
	s_barrier
	ds_read2_b32 v[0:1], v24 offset1:65
	ds_read2_b32 v[2:3], v24 offset0:130 offset1:195
	v_add_u32_e32 v6, 0x400, v24
	s_lshr_b32 s13, s12, 31
	s_ashr_i32 s12, s12, 4
	ds_read2_b32 v[4:5], v6 offset0:4 offset1:69
	ds_read2_b32 v[6:7], v6 offset0:134 offset1:199
	s_add_i32 s12, s12, s13
	s_mul_i32 s13, s12, 0x58
	s_sub_i32 s1, s1, s13
	s_waitcnt lgkmcnt(3)
	v_cvt_pk_bf16_f32 v0, v0, v1
	s_waitcnt lgkmcnt(2)
	v_cvt_pk_bf16_f32 v1, v2, v3
	s_waitcnt lgkmcnt(1)
	v_cvt_pk_bf16_f32 v2, v4, v5
	v_lshl_add_u32 v4, s1, 6, v19
	v_ashrrev_i32_e32 v5, 31, v4
	v_readlane_b32 s8, v253, 53
	s_lshl_b32 s12, s12, 6
	v_lshlrev_b64 v[4:5], 11, v[4:5]
	v_readlane_b32 s9, v253, 54
	s_ashr_i32 s13, s12, 31
	s_andn2_b64 vcc, exec, s[2:3]
	v_lshl_add_u64 v[4:5], s[8:9], 0, v[4:5]
	v_lshl_add_u64 v[4:5], s[12:13], 1, v[4:5]
	v_lshl_add_u64 v[4:5], v[4:5], 0, v[50:51]
	s_waitcnt lgkmcnt(0)
	v_cvt_pk_bf16_f32 v3, v6, v7
	global_store_dwordx4 v[4:5], v[0:3], off sc1
	s_barrier
	s_cbranch_vccz .LBB0_1997
	v_mov_b64_e32 v[0:1], v[8:9]
	s_mov_b32 s1, s10
	v_mov_b64_e32 v[2:3], v[10:11]
	v_mov_b64_e32 v[4:5], v[12:13]
	v_mov_b64_e32 v[6:7], v[14:15]
	s_branch .LBB0_2187
